# GEMM main loops: in every load segment the LDS-DMA pieces are issued before the ds_read fragment reads (was reads first)
# baseline (speedup 1.0000x reference)
; #define PG8_STAGE(bufoff, gbase, voff) do { _Pragma("unroll") for (int _i = 0; _i < 2; ++_i) \
;         __builtin_amdgcn_global_load_lds((const unsigned*)((const char*)(gbase) + (voff)[_i]), (LAS unsigned*)(lds + (bufoff) + ldsw + _i * 8192), 16, 0, 0); } while (0)
; #define PG8_LDA(dst, b, h) do { _Pragma("unroll") for (int m = 0; m < 4; ++m) _Pragma("unroll") for (int k = 0; k < 2; ++k) dst[m][k] = *(const LAS bf16x8*)(lds + PG8_SA(b, h) + aoff + m * 2048 + k * 1024); } while (0)
; #define PG8_LDB(dst, b, h) do { _Pragma("unroll") for (int n = 0; n < 2; ++n) _Pragma("unroll") for (int k = 0; k < 2; ++k) dst[n][k] = *(const LAS bf16x8*)(lds + PG8_SB(b, h) + boff + n * 2048 + k * 1024); } while (0)
; #define PG8_MMA(ai, bj, At, Bt) do { __builtin_amdgcn_s_setprio(1); _Pragma("unroll") for (int m = 0; m < 4; ++m) _Pragma("unroll") for (int n = 0; n < 2; ++n) _Pragma("unroll") for (int k = 0; k < 2; ++k) \
;         acc[ai][bj][m][n] = mma16<I8>(Bt[n][k], At[m][k], acc[ai][bj][m][n]); __builtin_amdgcn_s_setprio(0); } while (0)
; #define PG8_WAIT_V(n) asm volatile("s_waitcnt vmcnt(" #n ")" ::: "memory")
; #define PG8_WAIT_L(n) asm volatile("s_waitcnt lgkmcnt(" #n ")" ::: "memory")
; #define PG8_BAR __builtin_amdgcn_s_barrier()
; #define PG8_SCHED __builtin_amdgcn_sched_barrier(0)
; template <class Epi, class Sched, bool I8 = false>
; __device__ __forceinline__ void gemm_phase(LAS unsigned char* lds, const Gemm g, const Sched& S, const Epi& E) {
;     ...
;         for (int t = 0; t < nt; t += 2) {
;             const bool last = (t == nt - 2);
;             const char* a1 = cA + (size_t)(t + 1) * kstep;
;             const char* a2 = last ? nA : cA + (size_t)(t + 2) * kstep; const char* b2 = last ? nB : cB + (size_t)(t + 2) * kstep;
;             const char* a3 = a2 + kstep; const char* b3 = b2 + kstep;
;             if (PG8_SP2) {
;             PG8_LDB(B0, 0, 0); PG8_LDB(B1, 0, 1); PG8_SCHED; PG8_LDA(At, 0, 0); PG8_STAGE(PG8_SA(1, 1), a1 + hstepA, voffA);
;             PG8_WAIT_V(8); PG8_WAIT_L(0); PG8_BAR; PG8_MMA(0, 0, At, B0); PG8_MMA(0, 1, At, B1); PG8_BAR; PG8_SCHED;
;             PG8_LDA(At, 0, 1); PG8_STAGE(PG8_SB(0, 0), b2, voffB); PG8_STAGE(PG8_SB(0, 1), b2 + hstepB, voffB); PG8_STAGE(PG8_SA(0, 0), a2, voffA);
;             PG8_WAIT_V(8); PG8_WAIT_L(0); PG8_BAR; PG8_MMA(1, 0, At, B0); PG8_MMA(1, 1, At, B1); PG8_BAR; PG8_SCHED;
.LBB0_281:
	s_add_i32 s4, s0, 0xff840080
	s_cmp_lg_u32 s24, 28
	s_cselect_b32 s4, s4, 0
	s_add_u32 s6, s34, s4
	s_addc_u32 s7, s35, 0
	s_add_i32 s25, 0, 0x10000
	s_add_u32 s4, s30, s4
	s_addc_u32 s5, s31, 0
	s_add_i32 s29, 0, 0x14000
	v_lshl_add_u64 v[202:203], v[138:139], 0, s[0:1]
	s_add_i32 m0, s8, 0xc000
	s_nop 0
	global_load_lds_dwordx4 v[202:203], off
	v_lshl_add_u64 v[202:203], v[140:141], 0, s[0:1]
	s_add_i32 m0, s8, 0xe000
	s_nop 0
	global_load_lds_dwordx4 v[202:203], off
	v_add_u32_e32 v158, s25, v144
	v_add_u32_e32 v174, s29, v144
	ds_read_b128 v[146:149], v158
	ds_read_b128 v[150:153], v158 offset:1024
	ds_read_b128 v[154:157], v158 offset:2048
	ds_read_b128 v[158:161], v158 offset:3072
	ds_read_b128 v[162:165], v174
	ds_read_b128 v[166:169], v174 offset:1024
	ds_read_b128 v[170:173], v174 offset:2048
	ds_read_b128 v[174:177], v174 offset:3072
	ds_read_b128 v[178:181], v145
	ds_read_b128 v[182:185], v145 offset:1024
	ds_read_b128 v[186:189], v145 offset:2048
	ds_read_b128 v[190:193], v145 offset:3072
	ds_read_b128 v[194:197], v145 offset:4096
	ds_read_b128 v[198:201], v145 offset:5120
	ds_read_b128 v[212:215], v145 offset:6144
	ds_read_b128 v[216:219], v145 offset:7168
	s_waitcnt vmcnt(8)
	s_waitcnt lgkmcnt(0)
	s_barrier
	s_setprio 1
	s_waitcnt lgkmcnt(0)
	v_mfma_f32_16x16x32_bf16 v[126:129], v[146:149], v[178:181], v[126:129]
	v_mfma_f32_16x16x32_bf16 v[122:125], v[154:157], v[178:181], v[122:125]
	v_mfma_f32_16x16x32_bf16 v[110:113], v[146:149], v[186:189], v[110:113]
	v_mfma_f32_16x16x32_bf16 v[106:109], v[154:157], v[186:189], v[106:109]
	v_mfma_f32_16x16x32_bf16 v[94:97], v[146:149], v[194:197], v[94:97]
	v_mfma_f32_16x16x32_bf16 v[90:93], v[154:157], v[194:197], v[90:93]
	v_mfma_f32_16x16x32_bf16 v[78:81], v[146:149], v[212:215], v[78:81]
	v_mfma_f32_16x16x32_bf16 v[74:77], v[154:157], v[212:215], v[74:77]
	v_mfma_f32_16x16x32_bf16 v[126:129], v[150:153], v[182:185], v[126:129]
	v_mfma_f32_16x16x32_bf16 v[122:125], v[158:161], v[182:185], v[122:125]
	v_mfma_f32_16x16x32_bf16 v[110:113], v[150:153], v[190:193], v[110:113]
	v_mfma_f32_16x16x32_bf16 v[106:109], v[158:161], v[190:193], v[106:109]
	v_mfma_f32_16x16x32_bf16 v[94:97], v[150:153], v[198:201], v[94:97]
	v_mfma_f32_16x16x32_bf16 v[90:93], v[158:161], v[198:201], v[90:93]
	v_mfma_f32_16x16x32_bf16 v[78:81], v[150:153], v[216:219], v[78:81]
	v_mfma_f32_16x16x32_bf16 v[74:77], v[158:161], v[216:219], v[74:77]
	s_setprio 0
	s_setprio 1
	v_mfma_f32_16x16x32_bf16 v[118:121], v[162:165], v[178:181], v[118:121]
	v_mfma_f32_16x16x32_bf16 v[114:117], v[170:173], v[178:181], v[114:117]
	v_mfma_f32_16x16x32_bf16 v[102:105], v[162:165], v[186:189], v[102:105]
	v_mfma_f32_16x16x32_bf16 v[98:101], v[170:173], v[186:189], v[98:101]
	v_mfma_f32_16x16x32_bf16 v[86:89], v[162:165], v[194:197], v[86:89]
	v_mfma_f32_16x16x32_bf16 v[82:85], v[170:173], v[194:197], v[82:85]
	v_mfma_f32_16x16x32_bf16 v[70:73], v[162:165], v[212:215], v[70:73]
	v_mfma_f32_16x16x32_bf16 v[66:69], v[170:173], v[212:215], v[66:69]
	v_mfma_f32_16x16x32_bf16 v[118:121], v[166:169], v[182:185], v[118:121]
	v_mfma_f32_16x16x32_bf16 v[114:117], v[174:177], v[182:185], v[114:117]
	v_mfma_f32_16x16x32_bf16 v[102:105], v[166:169], v[190:193], v[102:105]
	v_mfma_f32_16x16x32_bf16 v[98:101], v[174:177], v[190:193], v[98:101]
	v_mfma_f32_16x16x32_bf16 v[86:89], v[166:169], v[198:201], v[86:89]
	v_mfma_f32_16x16x32_bf16 v[82:85], v[174:177], v[198:201], v[82:85]
	v_mfma_f32_16x16x32_bf16 v[70:73], v[166:169], v[216:219], v[70:73]
	v_mfma_f32_16x16x32_bf16 v[66:69], v[174:177], v[216:219], v[66:69]
	s_setprio 0
	s_barrier
	s_add_i32 s25, s25, s3
	v_lshl_add_u64 v[202:203], s[4:5], 0, v[130:131]
	s_mov_b32 m0, s25
	s_nop 0
	global_load_lds_dwordx4 v[202:203], off
	s_add_i32 m0, s25, 0x2000
	s_add_u32 s26, s4, 0x20000
	v_lshl_add_u64 v[220:221], s[4:5], 0, v[132:133]
	s_addc_u32 s27, s5, 0
	s_add_i32 s25, s29, s3
	global_load_lds_dwordx4 v[220:221], off
	v_lshl_add_u64 v[222:223], s[26:27], 0, v[130:131]
	s_mov_b32 m0, s25
	v_lshl_add_u64 v[224:225], s[6:7], 0, v[134:135]
	global_load_lds_dwordx4 v[222:223], off
	v_lshl_add_u64 v[222:223], s[26:27], 0, v[132:133]
	s_add_i32 m0, s25, 0x2000
	s_nop 0
	global_load_lds_dwordx4 v[222:223], off
	v_lshl_add_u64 v[222:223], s[6:7], 0, v[136:137]
	s_mov_b32 m0, s8
	s_nop 0
	global_load_lds_dwordx4 v[222:223], off
	s_mov_b32 m0, s9
	s_nop 0
	global_load_lds_dwordx4 v[224:225], off
	ds_read_b128 v[178:181], v145 offset:16384
	ds_read_b128 v[182:185], v145 offset:17408
	ds_read_b128 v[186:189], v145 offset:18432
	ds_read_b128 v[190:193], v145 offset:19456
	ds_read_b128 v[194:197], v145 offset:20480
	ds_read_b128 v[198:201], v145 offset:21504
	ds_read_b128 v[212:215], v145 offset:22528
	ds_read_b128 v[216:219], v145 offset:23552
	s_waitcnt vmcnt(8)
	s_waitcnt lgkmcnt(0)
	s_barrier
; #define PG8_STAGE(bufoff, gbase, voff) do { _Pragma("unroll") for (int _i = 0; _i < 2; ++_i) \
;         __builtin_amdgcn_global_load_lds((const unsigned*)((const char*)(gbase) + (voff)[_i]), (LAS unsigned*)(lds + (bufoff) + ldsw + _i * 8192), 16, 0, 0); } while (0)
; #define PG8_LDA(dst, b, h) do { _Pragma("unroll") for (int m = 0; m < 4; ++m) _Pragma("unroll") for (int k = 0; k < 2; ++k) dst[m][k] = *(const LAS bf16x8*)(lds + PG8_SA(b, h) + aoff + m * 2048 + k * 1024); } while (0)
; #define PG8_LDB(dst, b, h) do { _Pragma("unroll") for (int n = 0; n < 2; ++n) _Pragma("unroll") for (int k = 0; k < 2; ++k) dst[n][k] = *(const LAS bf16x8*)(lds + PG8_SB(b, h) + boff + n * 2048 + k * 1024); } while (0)
; #define PG8_MMA(ai, bj, At, Bt) do { __builtin_amdgcn_s_setprio(1); _Pragma("unroll") for (int m = 0; m < 4; ++m) _Pragma("unroll") for (int n = 0; n < 2; ++n) _Pragma("unroll") for (int k = 0; k < 2; ++k) \
;         acc[ai][bj][m][n] = mma16<I8>(Bt[n][k], At[m][k], acc[ai][bj][m][n]); __builtin_amdgcn_s_setprio(0); } while (0)
; #define PG8_WAIT_V(n) asm volatile("s_waitcnt vmcnt(" #n ")" ::: "memory")
; #define PG8_WAIT_L(n) asm volatile("s_waitcnt lgkmcnt(" #n ")" ::: "memory")
; #define PG8_BAR __builtin_amdgcn_s_barrier()
; #define PG8_SCHED __builtin_amdgcn_sched_barrier(0)
; template <class Epi, class Sched, bool I8 = false>
; __device__ __forceinline__ void gemm_phase(LAS unsigned char* lds, const Gemm g, const Sched& S, const Epi& E) {
;     ...
;             PG8_WAIT_V(8); PG8_WAIT_L(0); PG8_BAR; PG8_MMA(1, 0, At, B0); PG8_MMA(1, 1, At, B1); PG8_BAR; PG8_SCHED;
;             PG8_LDB(B0, 1, 0); PG8_LDB(B1, 1, 1); PG8_SCHED; PG8_LDA(At, 1, 0); PG8_STAGE(PG8_SA(0, 1), a2 + hstepA, voffA);
;             PG8_WAIT_V(8); PG8_WAIT_L(0); PG8_BAR; PG8_MMA(0, 0, At, B0); PG8_MMA(0, 1, At, B1); PG8_BAR; PG8_SCHED;
	s_setprio 1
	s_waitcnt lgkmcnt(0)
	v_mfma_f32_16x16x32_bf16 v[62:65], v[146:149], v[178:181], v[62:65]
	v_mfma_f32_16x16x32_bf16 v[58:61], v[154:157], v[178:181], v[58:61]
	v_mfma_f32_16x16x32_bf16 v[46:49], v[146:149], v[186:189], v[46:49]
	v_mfma_f32_16x16x32_bf16 v[42:45], v[154:157], v[186:189], v[42:45]
	v_mfma_f32_16x16x32_bf16 v[30:33], v[146:149], v[194:197], v[30:33]
	v_mfma_f32_16x16x32_bf16 v[26:29], v[154:157], v[194:197], v[26:29]
	v_mfma_f32_16x16x32_bf16 v[14:17], v[146:149], v[212:215], v[14:17]
	v_mfma_f32_16x16x32_bf16 v[10:13], v[154:157], v[212:215], v[10:13]
	v_mfma_f32_16x16x32_bf16 v[62:65], v[150:153], v[182:185], v[62:65]
	v_mfma_f32_16x16x32_bf16 v[58:61], v[158:161], v[182:185], v[58:61]
	v_mfma_f32_16x16x32_bf16 v[46:49], v[150:153], v[190:193], v[46:49]
	v_mfma_f32_16x16x32_bf16 v[42:45], v[158:161], v[190:193], v[42:45]
	v_mfma_f32_16x16x32_bf16 v[30:33], v[150:153], v[198:201], v[30:33]
	v_mfma_f32_16x16x32_bf16 v[26:29], v[158:161], v[198:201], v[26:29]
	v_mfma_f32_16x16x32_bf16 v[14:17], v[150:153], v[216:219], v[14:17]
	v_mfma_f32_16x16x32_bf16 v[10:13], v[158:161], v[216:219], v[10:13]
	s_setprio 0
	s_setprio 1
	v_mfma_f32_16x16x32_bf16 v[54:57], v[162:165], v[178:181], v[54:57]
	v_mfma_f32_16x16x32_bf16 v[50:53], v[170:173], v[178:181], v[50:53]
	v_mfma_f32_16x16x32_bf16 v[38:41], v[162:165], v[186:189], v[38:41]
	v_mfma_f32_16x16x32_bf16 v[34:37], v[170:173], v[186:189], v[34:37]
	v_mfma_f32_16x16x32_bf16 v[22:25], v[162:165], v[194:197], v[22:25]
	v_mfma_f32_16x16x32_bf16 v[18:21], v[170:173], v[194:197], v[18:21]
	v_mfma_f32_16x16x32_bf16 v[6:9], v[162:165], v[212:215], v[6:9]
	v_mfma_f32_16x16x32_bf16 v[2:5], v[170:173], v[212:215], v[2:5]
	v_mfma_f32_16x16x32_bf16 v[54:57], v[166:169], v[182:185], v[54:57]
	v_mfma_f32_16x16x32_bf16 v[50:53], v[174:177], v[182:185], v[50:53]
	v_mfma_f32_16x16x32_bf16 v[38:41], v[166:169], v[190:193], v[38:41]
	v_mfma_f32_16x16x32_bf16 v[34:37], v[174:177], v[190:193], v[34:37]
	v_mfma_f32_16x16x32_bf16 v[22:25], v[166:169], v[198:201], v[22:25]
	v_mfma_f32_16x16x32_bf16 v[18:21], v[174:177], v[198:201], v[18:21]
	v_mfma_f32_16x16x32_bf16 v[6:9], v[166:169], v[216:219], v[6:9]
	v_mfma_f32_16x16x32_bf16 v[2:5], v[174:177], v[216:219], v[2:5]
	s_setprio 0
	s_barrier
	s_add_i32 s25, 0, 0x18000
	s_add_i32 s26, 0, 0x1c000
	s_add_u32 s6, s6, 0x80000
	s_addc_u32 s7, s7, 0
	s_mov_b32 m0, s14
	v_lshl_add_u64 v[226:227], s[6:7], 0, v[136:137]
	global_load_lds_dwordx4 v[226:227], off
	v_lshl_add_u64 v[226:227], s[6:7], 0, v[134:135]
	s_mov_b32 m0, s16
	s_nop 0
	global_load_lds_dwordx4 v[226:227], off
	v_add_u32_e32 v158, s25, v144
	v_add_u32_e32 v174, s26, v144
	ds_read_b128 v[146:149], v158
	ds_read_b128 v[150:153], v158 offset:1024
	ds_read_b128 v[154:157], v158 offset:2048
	ds_read_b128 v[158:161], v158 offset:3072
	ds_read_b128 v[162:165], v174
	ds_read_b128 v[166:169], v174 offset:1024
	ds_read_b128 v[170:173], v174 offset:2048
	ds_read_b128 v[174:177], v174 offset:3072
	ds_read_b128 v[178:181], v145 offset:32768
	ds_read_b128 v[182:185], v145 offset:33792
	ds_read_b128 v[186:189], v145 offset:34816
	ds_read_b128 v[190:193], v145 offset:35840
	ds_read_b128 v[194:197], v145 offset:36864
	ds_read_b128 v[198:201], v145 offset:37888
	ds_read_b128 v[212:215], v145 offset:38912
	ds_read_b128 v[216:219], v145 offset:39936
	s_waitcnt vmcnt(8)
	s_waitcnt lgkmcnt(0)
	s_barrier
	s_setprio 1
	s_waitcnt lgkmcnt(0)
	v_mfma_f32_16x16x32_bf16 v[126:129], v[146:149], v[178:181], v[126:129]
	v_mfma_f32_16x16x32_bf16 v[122:125], v[154:157], v[178:181], v[122:125]
	v_mfma_f32_16x16x32_bf16 v[110:113], v[146:149], v[186:189], v[110:113]
	v_mfma_f32_16x16x32_bf16 v[106:109], v[154:157], v[186:189], v[106:109]
	v_mfma_f32_16x16x32_bf16 v[94:97], v[146:149], v[194:197], v[94:97]
	v_mfma_f32_16x16x32_bf16 v[90:93], v[154:157], v[194:197], v[90:93]
	v_mfma_f32_16x16x32_bf16 v[78:81], v[146:149], v[212:215], v[78:81]
	v_mfma_f32_16x16x32_bf16 v[74:77], v[154:157], v[212:215], v[74:77]
	v_mfma_f32_16x16x32_bf16 v[126:129], v[150:153], v[182:185], v[126:129]
	v_mfma_f32_16x16x32_bf16 v[122:125], v[158:161], v[182:185], v[122:125]
	v_mfma_f32_16x16x32_bf16 v[110:113], v[150:153], v[190:193], v[110:113]
	v_mfma_f32_16x16x32_bf16 v[106:109], v[158:161], v[190:193], v[106:109]
	v_mfma_f32_16x16x32_bf16 v[94:97], v[150:153], v[198:201], v[94:97]
	v_mfma_f32_16x16x32_bf16 v[90:93], v[158:161], v[198:201], v[90:93]
	v_mfma_f32_16x16x32_bf16 v[78:81], v[150:153], v[216:219], v[78:81]
	v_mfma_f32_16x16x32_bf16 v[74:77], v[158:161], v[216:219], v[74:77]
	s_setprio 0
	s_setprio 1
	v_mfma_f32_16x16x32_bf16 v[118:121], v[162:165], v[178:181], v[118:121]
	v_mfma_f32_16x16x32_bf16 v[114:117], v[170:173], v[178:181], v[114:117]
	v_mfma_f32_16x16x32_bf16 v[102:105], v[162:165], v[186:189], v[102:105]
	v_mfma_f32_16x16x32_bf16 v[98:101], v[170:173], v[186:189], v[98:101]
	v_mfma_f32_16x16x32_bf16 v[86:89], v[162:165], v[194:197], v[86:89]
	v_mfma_f32_16x16x32_bf16 v[82:85], v[170:173], v[194:197], v[82:85]
	v_mfma_f32_16x16x32_bf16 v[70:73], v[162:165], v[212:215], v[70:73]
	v_mfma_f32_16x16x32_bf16 v[66:69], v[170:173], v[212:215], v[66:69]
	v_mfma_f32_16x16x32_bf16 v[118:121], v[166:169], v[182:185], v[118:121]
	v_mfma_f32_16x16x32_bf16 v[114:117], v[174:177], v[182:185], v[114:117]
	v_mfma_f32_16x16x32_bf16 v[102:105], v[166:169], v[190:193], v[102:105]
	v_mfma_f32_16x16x32_bf16 v[98:101], v[174:177], v[190:193], v[98:101]
	v_mfma_f32_16x16x32_bf16 v[86:89], v[166:169], v[198:201], v[86:89]
	v_mfma_f32_16x16x32_bf16 v[82:85], v[174:177], v[198:201], v[82:85]
	v_mfma_f32_16x16x32_bf16 v[70:73], v[166:169], v[216:219], v[70:73]
	v_mfma_f32_16x16x32_bf16 v[66:69], v[174:177], v[216:219], v[66:69]
	s_setprio 0
	s_barrier
; #define PG8_STAGE(bufoff, gbase, voff) do { _Pragma("unroll") for (int _i = 0; _i < 2; ++_i) \
;         __builtin_amdgcn_global_load_lds((const unsigned*)((const char*)(gbase) + (voff)[_i]), (LAS unsigned*)(lds + (bufoff) + ldsw + _i * 8192), 16, 0, 0); } while (0)
; #define PG8_LDA(dst, b, h) do { _Pragma("unroll") for (int m = 0; m < 4; ++m) _Pragma("unroll") for (int k = 0; k < 2; ++k) dst[m][k] = *(const LAS bf16x8*)(lds + PG8_SA(b, h) + aoff + m * 2048 + k * 1024); } while (0)
; #define PG8_MMA(ai, bj, At, Bt) do { __builtin_amdgcn_s_setprio(1); _Pragma("unroll") for (int m = 0; m < 4; ++m) _Pragma("unroll") for (int n = 0; n < 2; ++n) _Pragma("unroll") for (int k = 0; k < 2; ++k) \
;         acc[ai][bj][m][n] = mma16<I8>(Bt[n][k], At[m][k], acc[ai][bj][m][n]); __builtin_amdgcn_s_setprio(0); } while (0)
; #define PG8_WAIT_V(n) asm volatile("s_waitcnt vmcnt(" #n ")" ::: "memory")
; #define PG8_WAIT_L(n) asm volatile("s_waitcnt lgkmcnt(" #n ")" ::: "memory")
; #define PG8_BAR __builtin_amdgcn_s_barrier()
; #define PG8_SCHED __builtin_amdgcn_sched_barrier(0)
; template <class Epi, class Sched, bool I8 = false>
; __device__ __forceinline__ void gemm_phase(LAS unsigned char* lds, const Gemm g, const Sched& S, const Epi& E) {
;     ...
;             PG8_LDA(At, 1, 1); PG8_STAGE(PG8_SB(1, 0), b3, voffB); PG8_STAGE(PG8_SB(1, 1), b3 + hstepB, voffB); PG8_STAGE(PG8_SA(1, 0), a3, voffA);
;             PG8_WAIT_V(8); PG8_WAIT_L(0); PG8_BAR; PG8_MMA(1, 0, At, B0); PG8_MMA(1, 1, At, B1); PG8_BAR; PG8_SCHED;
;     ...
;         if (PG8_ALIGN) { if (wr == 0) PG8_BAR; }
	s_add_i32 s6, s25, s3
	v_lshl_add_u64 v[202:203], v[202:203], 0, s[12:13]
	s_mov_b32 m0, s6
	s_nop 0
	global_load_lds_dwordx4 v[202:203], off
	s_add_i32 m0, s6, 0x2000
	s_add_u32 s4, s4, 0x20080
	v_lshl_add_u64 v[202:203], v[220:221], 0, s[12:13]
	s_addc_u32 s5, s5, 0
	s_add_i32 s6, s26, s3
	global_load_lds_dwordx4 v[202:203], off
	v_lshl_add_u64 v[202:203], s[4:5], 0, v[130:131]
	s_mov_b32 m0, s6
	s_nop 0
	global_load_lds_dwordx4 v[202:203], off
	v_lshl_add_u64 v[202:203], s[4:5], 0, v[132:133]
	s_add_i32 m0, s6, 0x2000
	s_nop 0
	global_load_lds_dwordx4 v[202:203], off
	v_lshl_add_u64 v[202:203], v[222:223], 0, s[12:13]
	s_mov_b32 m0, s22
	s_nop 0
	global_load_lds_dwordx4 v[202:203], off
	v_lshl_add_u64 v[202:203], v[224:225], 0, s[12:13]
	s_mov_b32 m0, s23
	s_nop 0
	global_load_lds_dwordx4 v[202:203], off
	ds_read_b128 v[178:181], v145 offset:49152
	ds_read_b128 v[182:185], v145 offset:50176
	ds_read_b128 v[186:189], v145 offset:51200
	ds_read_b128 v[190:193], v145 offset:52224
	ds_read_b128 v[194:197], v145 offset:53248
	ds_read_b128 v[198:201], v145 offset:54272
	ds_read_b128 v[212:215], v145 offset:55296
	ds_read_b128 v[216:219], v145 offset:56320
	s_waitcnt vmcnt(8)
	s_waitcnt lgkmcnt(0)
	s_barrier
	s_setprio 1
	s_waitcnt lgkmcnt(0)
	v_mfma_f32_16x16x32_bf16 v[62:65], v[146:149], v[178:181], v[62:65]
	v_mfma_f32_16x16x32_bf16 v[58:61], v[154:157], v[178:181], v[58:61]
	v_mfma_f32_16x16x32_bf16 v[46:49], v[146:149], v[186:189], v[46:49]
	v_mfma_f32_16x16x32_bf16 v[42:45], v[154:157], v[186:189], v[42:45]
	v_mfma_f32_16x16x32_bf16 v[30:33], v[146:149], v[194:197], v[30:33]
	v_mfma_f32_16x16x32_bf16 v[26:29], v[154:157], v[194:197], v[26:29]
	v_mfma_f32_16x16x32_bf16 v[14:17], v[146:149], v[212:215], v[14:17]
	v_mfma_f32_16x16x32_bf16 v[10:13], v[154:157], v[212:215], v[10:13]
	v_mfma_f32_16x16x32_bf16 v[62:65], v[150:153], v[182:185], v[62:65]
	v_mfma_f32_16x16x32_bf16 v[58:61], v[158:161], v[182:185], v[58:61]
	v_mfma_f32_16x16x32_bf16 v[46:49], v[150:153], v[190:193], v[46:49]
	v_mfma_f32_16x16x32_bf16 v[42:45], v[158:161], v[190:193], v[42:45]
	v_mfma_f32_16x16x32_bf16 v[30:33], v[150:153], v[198:201], v[30:33]
	v_mfma_f32_16x16x32_bf16 v[26:29], v[158:161], v[198:201], v[26:29]
	v_mfma_f32_16x16x32_bf16 v[14:17], v[150:153], v[216:219], v[14:17]
	v_mfma_f32_16x16x32_bf16 v[10:13], v[158:161], v[216:219], v[10:13]
	s_setprio 0
	s_setprio 1
	v_mfma_f32_16x16x32_bf16 v[54:57], v[162:165], v[178:181], v[54:57]
	v_mfma_f32_16x16x32_bf16 v[50:53], v[170:173], v[178:181], v[50:53]
	v_mfma_f32_16x16x32_bf16 v[38:41], v[162:165], v[186:189], v[38:41]
	v_mfma_f32_16x16x32_bf16 v[34:37], v[170:173], v[186:189], v[34:37]
	v_mfma_f32_16x16x32_bf16 v[22:25], v[162:165], v[194:197], v[22:25]
	v_mfma_f32_16x16x32_bf16 v[18:21], v[170:173], v[194:197], v[18:21]
	v_mfma_f32_16x16x32_bf16 v[6:9], v[162:165], v[212:215], v[6:9]
	v_mfma_f32_16x16x32_bf16 v[2:5], v[170:173], v[212:215], v[2:5]
	v_mfma_f32_16x16x32_bf16 v[54:57], v[166:169], v[182:185], v[54:57]
	v_mfma_f32_16x16x32_bf16 v[50:53], v[174:177], v[182:185], v[50:53]
	v_mfma_f32_16x16x32_bf16 v[38:41], v[166:169], v[190:193], v[38:41]
	v_mfma_f32_16x16x32_bf16 v[34:37], v[174:177], v[190:193], v[34:37]
	v_mfma_f32_16x16x32_bf16 v[22:25], v[166:169], v[198:201], v[22:25]
	v_mfma_f32_16x16x32_bf16 v[18:21], v[174:177], v[198:201], v[18:21]
	v_mfma_f32_16x16x32_bf16 v[6:9], v[166:169], v[216:219], v[6:9]
	v_mfma_f32_16x16x32_bf16 v[2:5], v[174:177], v[216:219], v[2:5]
	s_setprio 0
	s_barrier
	s_add_i32 s24, s24, 2
	s_add_u32 s0, s0, 0x100
	s_addc_u32 s1, s1, 0
	s_cmp_gt_u32 s24, 29
	s_cbranch_scc0 .LBB0_281
	s_cmpk_lt_u32 s2, 0x100
	v_readlane_b32 s22, v249, 31
	v_readlane_b32 s23, v249, 32
	s_cbranch_scc0 .LBB0_284
	s_barrier

; #define PG8_STAGE(bufoff, gbase, voff) do { _Pragma("unroll") for (int _i = 0; _i < 2; ++_i) \
;         __builtin_amdgcn_global_load_lds((const unsigned*)((const char*)(gbase) + (voff)[_i]), (LAS unsigned*)(lds + (bufoff) + ldsw + _i * 8192), 16, 0, 0); } while (0)
; #define PG8_LDA(dst, b, h) do { _Pragma("unroll") for (int m = 0; m < 4; ++m) _Pragma("unroll") for (int k = 0; k < 2; ++k) dst[m][k] = *(const LAS bf16x8*)(lds + PG8_SA(b, h) + aoff + m * 2048 + k * 1024); } while (0)
; #define PG8_LDB(dst, b, h) do { _Pragma("unroll") for (int n = 0; n < 2; ++n) _Pragma("unroll") for (int k = 0; k < 2; ++k) dst[n][k] = *(const LAS bf16x8*)(lds + PG8_SB(b, h) + boff + n * 2048 + k * 1024); } while (0)
; #define PG8_MMA(ai, bj, At, Bt) do { __builtin_amdgcn_s_setprio(1); _Pragma("unroll") for (int m = 0; m < 4; ++m) _Pragma("unroll") for (int n = 0; n < 2; ++n) _Pragma("unroll") for (int k = 0; k < 2; ++k) \
;         acc[ai][bj][m][n] = mma16<I8>(Bt[n][k], At[m][k], acc[ai][bj][m][n]); __builtin_amdgcn_s_setprio(0); } while (0)
; #define PG8_WAIT_V(n) asm volatile("s_waitcnt vmcnt(" #n ")" ::: "memory")
; #define PG8_WAIT_L(n) asm volatile("s_waitcnt lgkmcnt(" #n ")" ::: "memory")
; #define PG8_BAR __builtin_amdgcn_s_barrier()
; #define PG8_SCHED __builtin_amdgcn_sched_barrier(0)
; template <class Epi, class Sched, bool I8 = false>
; __device__ __forceinline__ void gemm_phase(LAS unsigned char* lds, const Gemm g, const Sched& S, const Epi& E) {
;     ...
;         for (int t = 0; t < nt; t += 2) {
;             const bool last = (t == nt - 2);
;             const char* a1 = cA + (size_t)(t + 1) * kstep;
;             const char* a2 = last ? nA : cA + (size_t)(t + 2) * kstep; const char* b2 = last ? nB : cB + (size_t)(t + 2) * kstep;
;             const char* a3 = a2 + kstep; const char* b3 = b2 + kstep;
;             if (PG8_SP2) {
;             PG8_LDB(B0, 0, 0); PG8_LDB(B1, 0, 1); PG8_SCHED; PG8_LDA(At, 0, 0); PG8_STAGE(PG8_SA(1, 1), a1 + hstepA, voffA);
;             PG8_WAIT_V(8); PG8_WAIT_L(0); PG8_BAR; PG8_MMA(0, 0, At, B0); PG8_MMA(0, 1, At, B1); PG8_BAR; PG8_SCHED;
;             PG8_LDA(At, 0, 1); PG8_STAGE(PG8_SB(0, 0), b2, voffB); PG8_STAGE(PG8_SB(0, 1), b2 + hstepB, voffB); PG8_STAGE(PG8_SA(0, 0), a2, voffA);
;             PG8_WAIT_V(8); PG8_WAIT_L(0); PG8_BAR; PG8_MMA(1, 0, At, B0); PG8_MMA(1, 1, At, B1); PG8_BAR; PG8_SCHED;
.LBB0_356:
	s_add_u32 s4, s0, 0xfff80080
	s_addc_u32 s5, s1, -1
	s_add_i32 s30, 0, 0x10000
	s_cmp_eq_u32 s29, 28
	s_cselect_b32 s7, s14, s5
	s_cselect_b32 s6, s21, s4
	s_cselect_b32 s5, s22, s25
	s_cselect_b32 s4, s23, s24
	s_add_i32 s34, 0, 0x14000
	v_lshl_add_u64 v[202:203], s[0:1], 0, v[146:147]
	s_add_i32 m0, s41, 0xc000
	s_nop 0
	global_load_lds_dwordx4 v[202:203], off
	v_lshl_add_u64 v[202:203], s[0:1], 0, v[148:149]
	s_add_i32 m0, s41, 0xe000
	s_nop 0
	global_load_lds_dwordx4 v[202:203], off
	v_add_u32_e32 v130, s30, v141
	ds_read_b128 v[150:153], v130
	ds_read_b128 v[154:157], v130 offset:1024
	ds_read_b128 v[158:161], v130 offset:2048
	ds_read_b128 v[162:165], v130 offset:3072
	v_add_u32_e32 v130, s34, v141
	ds_read_b128 v[166:169], v130
	ds_read_b128 v[170:173], v130 offset:1024
	ds_read_b128 v[174:177], v130 offset:2048
	ds_read_b128 v[178:181], v130 offset:3072
	ds_read_b128 v[182:185], v143
	ds_read_b128 v[186:189], v143 offset:1024
	ds_read_b128 v[190:193], v143 offset:2048
	ds_read_b128 v[194:197], v143 offset:3072
	ds_read_b128 v[198:201], v143 offset:4096
	ds_read_b128 v[212:215], v143 offset:5120
	ds_read_b128 v[216:219], v143 offset:6144
	ds_read_b128 v[220:223], v143 offset:7168
	s_waitcnt vmcnt(8)
	s_waitcnt lgkmcnt(0)
	s_barrier
	s_setprio 1
	s_waitcnt lgkmcnt(0)
	v_mfma_f32_16x16x32_bf16 v[126:129], v[150:153], v[182:185], v[126:129]
	v_mfma_f32_16x16x32_bf16 v[122:125], v[158:161], v[182:185], v[122:125]
	v_mfma_f32_16x16x32_bf16 v[110:113], v[150:153], v[190:193], v[110:113]
	v_mfma_f32_16x16x32_bf16 v[106:109], v[158:161], v[190:193], v[106:109]
	v_mfma_f32_16x16x32_bf16 v[94:97], v[150:153], v[198:201], v[94:97]
	v_mfma_f32_16x16x32_bf16 v[90:93], v[158:161], v[198:201], v[90:93]
	v_mfma_f32_16x16x32_bf16 v[78:81], v[150:153], v[216:219], v[78:81]
	v_mfma_f32_16x16x32_bf16 v[74:77], v[158:161], v[216:219], v[74:77]
	v_mfma_f32_16x16x32_bf16 v[126:129], v[154:157], v[186:189], v[126:129]
	v_mfma_f32_16x16x32_bf16 v[122:125], v[162:165], v[186:189], v[122:125]
	v_mfma_f32_16x16x32_bf16 v[110:113], v[154:157], v[194:197], v[110:113]
	v_mfma_f32_16x16x32_bf16 v[106:109], v[162:165], v[194:197], v[106:109]
	v_mfma_f32_16x16x32_bf16 v[94:97], v[154:157], v[212:215], v[94:97]
	v_mfma_f32_16x16x32_bf16 v[90:93], v[162:165], v[212:215], v[90:93]
	v_mfma_f32_16x16x32_bf16 v[78:81], v[154:157], v[220:223], v[78:81]
	v_mfma_f32_16x16x32_bf16 v[74:77], v[162:165], v[220:223], v[74:77]
	s_setprio 0
	s_setprio 1
	v_mfma_f32_16x16x32_bf16 v[118:121], v[166:169], v[182:185], v[118:121]
	v_mfma_f32_16x16x32_bf16 v[114:117], v[174:177], v[182:185], v[114:117]
	v_mfma_f32_16x16x32_bf16 v[102:105], v[166:169], v[190:193], v[102:105]
	v_mfma_f32_16x16x32_bf16 v[98:101], v[174:177], v[190:193], v[98:101]
	v_mfma_f32_16x16x32_bf16 v[86:89], v[166:169], v[198:201], v[86:89]
	v_mfma_f32_16x16x32_bf16 v[82:85], v[174:177], v[198:201], v[82:85]
	v_mfma_f32_16x16x32_bf16 v[70:73], v[166:169], v[216:219], v[70:73]
	v_mfma_f32_16x16x32_bf16 v[66:69], v[174:177], v[216:219], v[66:69]
	v_mfma_f32_16x16x32_bf16 v[118:121], v[170:173], v[186:189], v[118:121]
	v_mfma_f32_16x16x32_bf16 v[114:117], v[178:181], v[186:189], v[114:117]
	v_mfma_f32_16x16x32_bf16 v[102:105], v[170:173], v[194:197], v[102:105]
	v_mfma_f32_16x16x32_bf16 v[98:101], v[178:181], v[194:197], v[98:101]
	v_mfma_f32_16x16x32_bf16 v[86:89], v[170:173], v[212:215], v[86:89]
	v_mfma_f32_16x16x32_bf16 v[82:85], v[178:181], v[212:215], v[82:85]
	v_mfma_f32_16x16x32_bf16 v[70:73], v[170:173], v[220:223], v[70:73]
	v_mfma_f32_16x16x32_bf16 v[66:69], v[178:181], v[220:223], v[66:69]
	s_setprio 0
	s_barrier
	s_add_i32 s30, s30, s40
	v_lshl_add_u64 v[202:203], s[4:5], 0, v[136:137]
	s_mov_b32 m0, s30
	s_nop 0
	global_load_lds_dwordx4 v[202:203], off
	s_add_i32 m0, s30, 0x2000
	s_add_u32 s30, s4, 0x20000
	v_lshl_add_u64 v[224:225], s[4:5], 0, v[132:133]
	s_addc_u32 s31, s5, 0
	s_add_i32 s34, s34, s40
	global_load_lds_dwordx4 v[224:225], off
	v_lshl_add_u64 v[226:227], s[30:31], 0, v[136:137]
	s_mov_b32 m0, s34
	v_lshl_add_u64 v[228:229], s[6:7], 0, v[134:135]
	global_load_lds_dwordx4 v[226:227], off
	v_lshl_add_u64 v[226:227], s[30:31], 0, v[132:133]
	s_add_i32 m0, s34, 0x2000
	s_nop 0
	global_load_lds_dwordx4 v[226:227], off
	v_lshl_add_u64 v[226:227], s[6:7], 0, v[138:139]
	s_mov_b32 m0, s41
	s_nop 0
	global_load_lds_dwordx4 v[226:227], off
	s_mov_b32 m0, s42
	s_nop 0
	global_load_lds_dwordx4 v[228:229], off
	ds_read_b128 v[182:185], v143 offset:16384
	ds_read_b128 v[186:189], v143 offset:17408
	ds_read_b128 v[190:193], v143 offset:18432
	ds_read_b128 v[194:197], v143 offset:19456
	ds_read_b128 v[198:201], v143 offset:20480
	ds_read_b128 v[212:215], v143 offset:21504
	ds_read_b128 v[216:219], v143 offset:22528
	ds_read_b128 v[220:223], v143 offset:23552
	s_waitcnt vmcnt(8)
	s_waitcnt lgkmcnt(0)
	s_barrier
; #define PG8_STAGE(bufoff, gbase, voff) do { _Pragma("unroll") for (int _i = 0; _i < 2; ++_i) \
;         __builtin_amdgcn_global_load_lds((const unsigned*)((const char*)(gbase) + (voff)[_i]), (LAS unsigned*)(lds + (bufoff) + ldsw + _i * 8192), 16, 0, 0); } while (0)
; #define PG8_LDA(dst, b, h) do { _Pragma("unroll") for (int m = 0; m < 4; ++m) _Pragma("unroll") for (int k = 0; k < 2; ++k) dst[m][k] = *(const LAS bf16x8*)(lds + PG8_SA(b, h) + aoff + m * 2048 + k * 1024); } while (0)
; #define PG8_LDB(dst, b, h) do { _Pragma("unroll") for (int n = 0; n < 2; ++n) _Pragma("unroll") for (int k = 0; k < 2; ++k) dst[n][k] = *(const LAS bf16x8*)(lds + PG8_SB(b, h) + boff + n * 2048 + k * 1024); } while (0)
; #define PG8_MMA(ai, bj, At, Bt) do { __builtin_amdgcn_s_setprio(1); _Pragma("unroll") for (int m = 0; m < 4; ++m) _Pragma("unroll") for (int n = 0; n < 2; ++n) _Pragma("unroll") for (int k = 0; k < 2; ++k) \
;         acc[ai][bj][m][n] = mma16<I8>(Bt[n][k], At[m][k], acc[ai][bj][m][n]); __builtin_amdgcn_s_setprio(0); } while (0)
; #define PG8_WAIT_V(n) asm volatile("s_waitcnt vmcnt(" #n ")" ::: "memory")
; #define PG8_WAIT_L(n) asm volatile("s_waitcnt lgkmcnt(" #n ")" ::: "memory")
; #define PG8_BAR __builtin_amdgcn_s_barrier()
; #define PG8_SCHED __builtin_amdgcn_sched_barrier(0)
; template <class Epi, class Sched, bool I8 = false>
; __device__ __forceinline__ void gemm_phase(LAS unsigned char* lds, const Gemm g, const Sched& S, const Epi& E) {
;     ...
;             PG8_WAIT_V(8); PG8_WAIT_L(0); PG8_BAR; PG8_MMA(1, 0, At, B0); PG8_MMA(1, 1, At, B1); PG8_BAR; PG8_SCHED;
;             PG8_LDB(B0, 1, 0); PG8_LDB(B1, 1, 1); PG8_SCHED; PG8_LDA(At, 1, 0); PG8_STAGE(PG8_SA(0, 1), a2 + hstepA, voffA);
;             PG8_WAIT_V(8); PG8_WAIT_L(0); PG8_BAR; PG8_MMA(0, 0, At, B0); PG8_MMA(0, 1, At, B1); PG8_BAR; PG8_SCHED;
	s_setprio 1
	s_waitcnt lgkmcnt(0)
	v_mfma_f32_16x16x32_bf16 v[62:65], v[150:153], v[182:185], v[62:65]
	v_mfma_f32_16x16x32_bf16 v[58:61], v[158:161], v[182:185], v[58:61]
	v_mfma_f32_16x16x32_bf16 v[46:49], v[150:153], v[190:193], v[46:49]
	v_mfma_f32_16x16x32_bf16 v[42:45], v[158:161], v[190:193], v[42:45]
	v_mfma_f32_16x16x32_bf16 v[30:33], v[150:153], v[198:201], v[30:33]
	v_mfma_f32_16x16x32_bf16 v[26:29], v[158:161], v[198:201], v[26:29]
	v_mfma_f32_16x16x32_bf16 v[14:17], v[150:153], v[216:219], v[14:17]
	v_mfma_f32_16x16x32_bf16 v[10:13], v[158:161], v[216:219], v[10:13]
	v_mfma_f32_16x16x32_bf16 v[62:65], v[154:157], v[186:189], v[62:65]
	v_mfma_f32_16x16x32_bf16 v[58:61], v[162:165], v[186:189], v[58:61]
	v_mfma_f32_16x16x32_bf16 v[46:49], v[154:157], v[194:197], v[46:49]
	v_mfma_f32_16x16x32_bf16 v[42:45], v[162:165], v[194:197], v[42:45]
	v_mfma_f32_16x16x32_bf16 v[30:33], v[154:157], v[212:215], v[30:33]
	v_mfma_f32_16x16x32_bf16 v[26:29], v[162:165], v[212:215], v[26:29]
	v_mfma_f32_16x16x32_bf16 v[14:17], v[154:157], v[220:223], v[14:17]
	v_mfma_f32_16x16x32_bf16 v[10:13], v[162:165], v[220:223], v[10:13]
	s_setprio 0
	s_setprio 1
	v_mfma_f32_16x16x32_bf16 v[54:57], v[166:169], v[182:185], v[54:57]
	v_mfma_f32_16x16x32_bf16 v[50:53], v[174:177], v[182:185], v[50:53]
	v_mfma_f32_16x16x32_bf16 v[38:41], v[166:169], v[190:193], v[38:41]
	v_mfma_f32_16x16x32_bf16 v[34:37], v[174:177], v[190:193], v[34:37]
	v_mfma_f32_16x16x32_bf16 v[22:25], v[166:169], v[198:201], v[22:25]
	v_mfma_f32_16x16x32_bf16 v[18:21], v[174:177], v[198:201], v[18:21]
	v_mfma_f32_16x16x32_bf16 v[6:9], v[166:169], v[216:219], v[6:9]
	v_mfma_f32_16x16x32_bf16 v[2:5], v[174:177], v[216:219], v[2:5]
	v_mfma_f32_16x16x32_bf16 v[54:57], v[170:173], v[186:189], v[54:57]
	v_mfma_f32_16x16x32_bf16 v[50:53], v[178:181], v[186:189], v[50:53]
	v_mfma_f32_16x16x32_bf16 v[38:41], v[170:173], v[194:197], v[38:41]
	v_mfma_f32_16x16x32_bf16 v[34:37], v[178:181], v[194:197], v[34:37]
	v_mfma_f32_16x16x32_bf16 v[22:25], v[170:173], v[212:215], v[22:25]
	v_mfma_f32_16x16x32_bf16 v[18:21], v[178:181], v[212:215], v[18:21]
	v_mfma_f32_16x16x32_bf16 v[6:9], v[170:173], v[220:223], v[6:9]
	v_mfma_f32_16x16x32_bf16 v[2:5], v[178:181], v[220:223], v[2:5]
	s_setprio 0
	s_barrier
	s_add_i32 s30, 0, 0x18000
	s_add_i32 s31, 0, 0x1c000
	s_add_u32 s6, s6, 0x80000
	s_addc_u32 s7, s7, 0
	s_mov_b32 m0, s43
	v_lshl_add_u64 v[230:231], s[6:7], 0, v[138:139]
	global_load_lds_dwordx4 v[230:231], off
	v_lshl_add_u64 v[230:231], s[6:7], 0, v[134:135]
	s_mov_b32 m0, s44
	s_nop 0
	global_load_lds_dwordx4 v[230:231], off
	v_add_u32_e32 v130, s30, v141
	ds_read_b128 v[150:153], v130
	ds_read_b128 v[154:157], v130 offset:1024
	ds_read_b128 v[158:161], v130 offset:2048
	ds_read_b128 v[162:165], v130 offset:3072
	v_add_u32_e32 v130, s31, v141
	ds_read_b128 v[166:169], v130
	ds_read_b128 v[170:173], v130 offset:1024
	ds_read_b128 v[174:177], v130 offset:2048
	ds_read_b128 v[178:181], v130 offset:3072
	ds_read_b128 v[182:185], v143 offset:32768
	ds_read_b128 v[186:189], v143 offset:33792
	ds_read_b128 v[190:193], v143 offset:34816
	ds_read_b128 v[194:197], v143 offset:35840
	ds_read_b128 v[198:201], v143 offset:36864
	ds_read_b128 v[212:215], v143 offset:37888
	ds_read_b128 v[216:219], v143 offset:38912
	ds_read_b128 v[220:223], v143 offset:39936
	s_waitcnt vmcnt(8)
	s_waitcnt lgkmcnt(0)
	s_barrier
	s_setprio 1
	s_waitcnt lgkmcnt(0)
	v_mfma_f32_16x16x32_bf16 v[126:129], v[150:153], v[182:185], v[126:129]
	v_mfma_f32_16x16x32_bf16 v[122:125], v[158:161], v[182:185], v[122:125]
	v_mfma_f32_16x16x32_bf16 v[110:113], v[150:153], v[190:193], v[110:113]
	v_mfma_f32_16x16x32_bf16 v[106:109], v[158:161], v[190:193], v[106:109]
	v_mfma_f32_16x16x32_bf16 v[94:97], v[150:153], v[198:201], v[94:97]
	v_mfma_f32_16x16x32_bf16 v[90:93], v[158:161], v[198:201], v[90:93]
	v_mfma_f32_16x16x32_bf16 v[78:81], v[150:153], v[216:219], v[78:81]
	v_mfma_f32_16x16x32_bf16 v[74:77], v[158:161], v[216:219], v[74:77]
	v_mfma_f32_16x16x32_bf16 v[126:129], v[154:157], v[186:189], v[126:129]
	v_mfma_f32_16x16x32_bf16 v[122:125], v[162:165], v[186:189], v[122:125]
	v_mfma_f32_16x16x32_bf16 v[110:113], v[154:157], v[194:197], v[110:113]
	v_mfma_f32_16x16x32_bf16 v[106:109], v[162:165], v[194:197], v[106:109]
	v_mfma_f32_16x16x32_bf16 v[94:97], v[154:157], v[212:215], v[94:97]
	v_mfma_f32_16x16x32_bf16 v[90:93], v[162:165], v[212:215], v[90:93]
	v_mfma_f32_16x16x32_bf16 v[78:81], v[154:157], v[220:223], v[78:81]
	v_mfma_f32_16x16x32_bf16 v[74:77], v[162:165], v[220:223], v[74:77]
	s_setprio 0
	s_setprio 1
	v_mfma_f32_16x16x32_bf16 v[118:121], v[166:169], v[182:185], v[118:121]
	v_mfma_f32_16x16x32_bf16 v[114:117], v[174:177], v[182:185], v[114:117]
	v_mfma_f32_16x16x32_bf16 v[102:105], v[166:169], v[190:193], v[102:105]
	v_mfma_f32_16x16x32_bf16 v[98:101], v[174:177], v[190:193], v[98:101]
	v_mfma_f32_16x16x32_bf16 v[86:89], v[166:169], v[198:201], v[86:89]
	v_mfma_f32_16x16x32_bf16 v[82:85], v[174:177], v[198:201], v[82:85]
	v_mfma_f32_16x16x32_bf16 v[70:73], v[166:169], v[216:219], v[70:73]
	v_mfma_f32_16x16x32_bf16 v[66:69], v[174:177], v[216:219], v[66:69]
	v_mfma_f32_16x16x32_bf16 v[118:121], v[170:173], v[186:189], v[118:121]
	v_mfma_f32_16x16x32_bf16 v[114:117], v[178:181], v[186:189], v[114:117]
	v_mfma_f32_16x16x32_bf16 v[102:105], v[170:173], v[194:197], v[102:105]
	v_mfma_f32_16x16x32_bf16 v[98:101], v[178:181], v[194:197], v[98:101]
	v_mfma_f32_16x16x32_bf16 v[86:89], v[170:173], v[212:215], v[86:89]
	v_mfma_f32_16x16x32_bf16 v[82:85], v[178:181], v[212:215], v[82:85]
	v_mfma_f32_16x16x32_bf16 v[70:73], v[170:173], v[220:223], v[70:73]
	v_mfma_f32_16x16x32_bf16 v[66:69], v[178:181], v[220:223], v[66:69]
	s_setprio 0
	s_barrier
; #define PG8_STAGE(bufoff, gbase, voff) do { _Pragma("unroll") for (int _i = 0; _i < 2; ++_i) \
;         __builtin_amdgcn_global_load_lds((const unsigned*)((const char*)(gbase) + (voff)[_i]), (LAS unsigned*)(lds + (bufoff) + ldsw + _i * 8192), 16, 0, 0); } while (0)
; #define PG8_LDA(dst, b, h) do { _Pragma("unroll") for (int m = 0; m < 4; ++m) _Pragma("unroll") for (int k = 0; k < 2; ++k) dst[m][k] = *(const LAS bf16x8*)(lds + PG8_SA(b, h) + aoff + m * 2048 + k * 1024); } while (0)
; #define PG8_MMA(ai, bj, At, Bt) do { __builtin_amdgcn_s_setprio(1); _Pragma("unroll") for (int m = 0; m < 4; ++m) _Pragma("unroll") for (int n = 0; n < 2; ++n) _Pragma("unroll") for (int k = 0; k < 2; ++k) \
;         acc[ai][bj][m][n] = mma16<I8>(Bt[n][k], At[m][k], acc[ai][bj][m][n]); __builtin_amdgcn_s_setprio(0); } while (0)
; #define PG8_WAIT_V(n) asm volatile("s_waitcnt vmcnt(" #n ")" ::: "memory")
; #define PG8_WAIT_L(n) asm volatile("s_waitcnt lgkmcnt(" #n ")" ::: "memory")
; #define PG8_BAR __builtin_amdgcn_s_barrier()
; #define PG8_SCHED __builtin_amdgcn_sched_barrier(0)
; template <class Epi, class Sched, bool I8 = false>
; __device__ __forceinline__ void gemm_phase(LAS unsigned char* lds, const Gemm g, const Sched& S, const Epi& E) {
;     ...
;             PG8_LDA(At, 1, 1); PG8_STAGE(PG8_SB(1, 0), b3, voffB); PG8_STAGE(PG8_SB(1, 1), b3 + hstepB, voffB); PG8_STAGE(PG8_SA(1, 0), a3, voffA);
;             PG8_WAIT_V(8); PG8_WAIT_L(0); PG8_BAR; PG8_MMA(1, 0, At, B0); PG8_MMA(1, 1, At, B1); PG8_BAR; PG8_SCHED;
;     ...
;         if (PG8_ALIGN) { if (wr == 0) PG8_BAR; }
	s_add_i32 s6, s30, s40
	v_lshl_add_u64 v[202:203], v[202:203], 0, s[12:13]
	s_mov_b32 m0, s6
	s_nop 0
	global_load_lds_dwordx4 v[202:203], off
	s_add_i32 m0, s6, 0x2000
	s_add_u32 s4, s4, 0x20080
	v_lshl_add_u64 v[202:203], v[224:225], 0, s[12:13]
	s_addc_u32 s5, s5, 0
	s_add_i32 s6, s31, s40
	global_load_lds_dwordx4 v[202:203], off
	v_lshl_add_u64 v[202:203], s[4:5], 0, v[136:137]
	s_mov_b32 m0, s6
	s_nop 0
	global_load_lds_dwordx4 v[202:203], off
	v_lshl_add_u64 v[202:203], s[4:5], 0, v[132:133]
	s_add_i32 m0, s6, 0x2000
	s_nop 0
	global_load_lds_dwordx4 v[202:203], off
	v_lshl_add_u64 v[202:203], v[226:227], 0, s[12:13]
	s_mov_b32 m0, s80
	s_nop 0
	global_load_lds_dwordx4 v[202:203], off
	v_lshl_add_u64 v[202:203], v[228:229], 0, s[12:13]
	s_mov_b32 m0, s82
	s_nop 0
	global_load_lds_dwordx4 v[202:203], off
	ds_read_b128 v[182:185], v143 offset:49152
	ds_read_b128 v[186:189], v143 offset:50176
	ds_read_b128 v[190:193], v143 offset:51200
	ds_read_b128 v[194:197], v143 offset:52224
	ds_read_b128 v[198:201], v143 offset:53248
	ds_read_b128 v[212:215], v143 offset:54272
	ds_read_b128 v[216:219], v143 offset:55296
	ds_read_b128 v[220:223], v143 offset:56320
	s_waitcnt vmcnt(8)
	s_waitcnt lgkmcnt(0)
	s_barrier
	s_setprio 1
	s_waitcnt lgkmcnt(0)
	v_mfma_f32_16x16x32_bf16 v[62:65], v[150:153], v[182:185], v[62:65]
	v_mfma_f32_16x16x32_bf16 v[58:61], v[158:161], v[182:185], v[58:61]
	v_mfma_f32_16x16x32_bf16 v[46:49], v[150:153], v[190:193], v[46:49]
	v_mfma_f32_16x16x32_bf16 v[42:45], v[158:161], v[190:193], v[42:45]
	v_mfma_f32_16x16x32_bf16 v[30:33], v[150:153], v[198:201], v[30:33]
	v_mfma_f32_16x16x32_bf16 v[26:29], v[158:161], v[198:201], v[26:29]
	v_mfma_f32_16x16x32_bf16 v[14:17], v[150:153], v[216:219], v[14:17]
	v_mfma_f32_16x16x32_bf16 v[10:13], v[158:161], v[216:219], v[10:13]
	v_mfma_f32_16x16x32_bf16 v[62:65], v[154:157], v[186:189], v[62:65]
	v_mfma_f32_16x16x32_bf16 v[58:61], v[162:165], v[186:189], v[58:61]
	v_mfma_f32_16x16x32_bf16 v[46:49], v[154:157], v[194:197], v[46:49]
	v_mfma_f32_16x16x32_bf16 v[42:45], v[162:165], v[194:197], v[42:45]
	v_mfma_f32_16x16x32_bf16 v[30:33], v[154:157], v[212:215], v[30:33]
	v_mfma_f32_16x16x32_bf16 v[26:29], v[162:165], v[212:215], v[26:29]
	v_mfma_f32_16x16x32_bf16 v[14:17], v[154:157], v[220:223], v[14:17]
	v_mfma_f32_16x16x32_bf16 v[10:13], v[162:165], v[220:223], v[10:13]
	s_setprio 0
	s_setprio 1
	v_mfma_f32_16x16x32_bf16 v[54:57], v[166:169], v[182:185], v[54:57]
	v_mfma_f32_16x16x32_bf16 v[50:53], v[174:177], v[182:185], v[50:53]
	v_mfma_f32_16x16x32_bf16 v[38:41], v[166:169], v[190:193], v[38:41]
	v_mfma_f32_16x16x32_bf16 v[34:37], v[174:177], v[190:193], v[34:37]
	v_mfma_f32_16x16x32_bf16 v[22:25], v[166:169], v[198:201], v[22:25]
	v_mfma_f32_16x16x32_bf16 v[18:21], v[174:177], v[198:201], v[18:21]
	v_mfma_f32_16x16x32_bf16 v[6:9], v[166:169], v[216:219], v[6:9]
	v_mfma_f32_16x16x32_bf16 v[2:5], v[174:177], v[216:219], v[2:5]
	v_mfma_f32_16x16x32_bf16 v[54:57], v[170:173], v[186:189], v[54:57]
	v_mfma_f32_16x16x32_bf16 v[50:53], v[178:181], v[186:189], v[50:53]
	v_mfma_f32_16x16x32_bf16 v[38:41], v[170:173], v[194:197], v[38:41]
	v_mfma_f32_16x16x32_bf16 v[34:37], v[178:181], v[194:197], v[34:37]
	v_mfma_f32_16x16x32_bf16 v[22:25], v[170:173], v[212:215], v[22:25]
	v_mfma_f32_16x16x32_bf16 v[18:21], v[178:181], v[212:215], v[18:21]
	v_mfma_f32_16x16x32_bf16 v[6:9], v[170:173], v[220:223], v[6:9]
	v_mfma_f32_16x16x32_bf16 v[2:5], v[178:181], v[220:223], v[2:5]
	s_setprio 0
	s_barrier
	s_add_i32 s29, s29, 2
	s_add_u32 s0, s0, 0x100
	s_addc_u32 s1, s1, 0
	s_add_u32 s24, s24, 0x100
	s_addc_u32 s25, s25, 0
	s_cmp_gt_u32 s29, 29
	s_cbranch_scc0 .LBB0_356
	s_and_b64 vcc, exec, s[8:9]
	s_cbranch_vccz .LBB0_359
	s_barrier

; #define PG8_STAGE(bufoff, gbase, voff) do { _Pragma("unroll") for (int _i = 0; _i < 2; ++_i) \
;         __builtin_amdgcn_global_load_lds((const unsigned*)((const char*)(gbase) + (voff)[_i]), (LAS unsigned*)(lds + (bufoff) + ldsw + _i * 8192), 16, 0, 0); } while (0)
; #define PG8_LDA(dst, b, h) do { _Pragma("unroll") for (int m = 0; m < 4; ++m) _Pragma("unroll") for (int k = 0; k < 2; ++k) dst[m][k] = *(const LAS bf16x8*)(lds + PG8_SA(b, h) + aoff + m * 2048 + k * 1024); } while (0)
; #define PG8_LDB(dst, b, h) do { _Pragma("unroll") for (int n = 0; n < 2; ++n) _Pragma("unroll") for (int k = 0; k < 2; ++k) dst[n][k] = *(const LAS bf16x8*)(lds + PG8_SB(b, h) + boff + n * 2048 + k * 1024); } while (0)
; #define PG8_MMA(ai, bj, At, Bt) do { __builtin_amdgcn_s_setprio(1); _Pragma("unroll") for (int m = 0; m < 4; ++m) _Pragma("unroll") for (int n = 0; n < 2; ++n) _Pragma("unroll") for (int k = 0; k < 2; ++k) \
;         acc[ai][bj][m][n] = mma16<I8>(Bt[n][k], At[m][k], acc[ai][bj][m][n]); __builtin_amdgcn_s_setprio(0); } while (0)
; #define PG8_WAIT_V(n) asm volatile("s_waitcnt vmcnt(" #n ")" ::: "memory")
; #define PG8_WAIT_L(n) asm volatile("s_waitcnt lgkmcnt(" #n ")" ::: "memory")
; #define PG8_BAR __builtin_amdgcn_s_barrier()
; #define PG8_SCHED __builtin_amdgcn_sched_barrier(0)
; template <class Epi, class Sched, bool I8 = false>
; __device__ __forceinline__ void gemm_phase(LAS unsigned char* lds, const Gemm g, const Sched& S, const Epi& E) {
;     ...
;         for (int t = 0; t < nt; t += 2) {
;             const bool last = (t == nt - 2);
;             const char* a1 = cA + (size_t)(t + 1) * kstep;
;             const char* a2 = last ? nA : cA + (size_t)(t + 2) * kstep; const char* b2 = last ? nB : cB + (size_t)(t + 2) * kstep;
;             const char* a3 = a2 + kstep; const char* b3 = b2 + kstep;
;             if (PG8_SP2) {
;             PG8_LDB(B0, 0, 0); PG8_LDB(B1, 0, 1); PG8_SCHED; PG8_LDA(At, 0, 0); PG8_STAGE(PG8_SA(1, 1), a1 + hstepA, voffA);
;             PG8_WAIT_V(8); PG8_WAIT_L(0); PG8_BAR; PG8_MMA(0, 0, At, B0); PG8_MMA(0, 1, At, B1); PG8_BAR; PG8_SCHED;
;             PG8_LDA(At, 0, 1); PG8_STAGE(PG8_SB(0, 0), b2, voffB); PG8_STAGE(PG8_SB(0, 1), b2 + hstepB, voffB); PG8_STAGE(PG8_SA(0, 0), a2, voffA);
;             PG8_WAIT_V(8); PG8_WAIT_L(0); PG8_BAR; PG8_MMA(1, 0, At, B0); PG8_MMA(1, 1, At, B1); PG8_BAR; PG8_SCHED;
.LBB0_539:
	s_add_u32 s6, s0, 0xfffc0080
	s_addc_u32 s7, s1, -1
	s_add_i32 s31, 0, 0x10000
	s_cmp_eq_u32 s30, 12
	s_cselect_b32 s27, s14, s7
	s_cselect_b32 s26, s21, s6
	s_cselect_b32 s7, s22, s25
	s_cselect_b32 s6, s23, s24
	s_add_i32 s38, 0, 0x14000
	v_lshl_add_u64 v[172:173], s[0:1], 0, v[144:145]
	s_add_i32 m0, s43, 0xc000
	s_nop 0
	global_load_lds_dwordx4 v[172:173], off
	v_lshl_add_u64 v[172:173], s[0:1], 0, v[146:147]
	s_add_i32 m0, s43, 0xe000
	s_nop 0
	global_load_lds_dwordx4 v[172:173], off
	v_add_u32_e32 v149, s31, v175
	ds_read_b128 v[152:155], v149
	ds_read_b128 v[156:159], v149 offset:1024
	ds_read_b128 v[160:163], v149 offset:2048
	ds_read_b128 v[164:167], v149 offset:3072
	v_add_u32_e32 v149, s38, v175
	ds_read_b128 v[168:171], v149
	ds_read_b128 v[180:183], v149 offset:1024
	ds_read_b128 v[184:187], v149 offset:2048
	ds_read_b128 v[188:191], v149 offset:3072
	ds_read_b128 v[192:195], v179
	ds_read_b128 v[196:199], v179 offset:1024
	ds_read_b128 v[200:203], v179 offset:2048
	ds_read_b128 v[212:215], v179 offset:3072
	ds_read_b128 v[216:219], v179 offset:4096
	ds_read_b128 v[220:223], v179 offset:5120
	ds_read_b128 v[224:227], v179 offset:6144
	ds_read_b128 v[228:231], v179 offset:7168
	s_waitcnt vmcnt(8)
	s_waitcnt lgkmcnt(0)
	s_barrier
	s_setprio 1
	s_waitcnt lgkmcnt(0)
	v_mfma_i32_16x16x64_i8 v[126:129], v[152:155], v[192:195], v[126:129]
	v_mfma_i32_16x16x64_i8 v[122:125], v[160:163], v[192:195], v[122:125]
	v_mfma_i32_16x16x64_i8 v[118:121], v[152:155], v[200:203], v[118:121]
	v_mfma_i32_16x16x64_i8 v[114:117], v[160:163], v[200:203], v[114:117]
	v_mfma_i32_16x16x64_i8 v[102:105], v[152:155], v[216:219], v[102:105]
	v_mfma_i32_16x16x64_i8 v[98:101], v[160:163], v[216:219], v[98:101]
	v_mfma_i32_16x16x64_i8 v[86:89], v[152:155], v[224:227], v[86:89]
	v_mfma_i32_16x16x64_i8 v[82:85], v[160:163], v[224:227], v[82:85]
	v_mfma_i32_16x16x64_i8 v[126:129], v[156:159], v[196:199], v[126:129]
	v_mfma_i32_16x16x64_i8 v[122:125], v[164:167], v[196:199], v[122:125]
	v_mfma_i32_16x16x64_i8 v[118:121], v[156:159], v[212:215], v[118:121]
	v_mfma_i32_16x16x64_i8 v[114:117], v[164:167], v[212:215], v[114:117]
	v_mfma_i32_16x16x64_i8 v[102:105], v[156:159], v[220:223], v[102:105]
	v_mfma_i32_16x16x64_i8 v[98:101], v[164:167], v[220:223], v[98:101]
	v_mfma_i32_16x16x64_i8 v[86:89], v[156:159], v[228:231], v[86:89]
	v_mfma_i32_16x16x64_i8 v[82:85], v[164:167], v[228:231], v[82:85]
	s_setprio 0
	s_setprio 1
	v_mfma_i32_16x16x64_i8 v[110:113], v[168:171], v[192:195], v[110:113]
	v_mfma_i32_16x16x64_i8 v[106:109], v[184:187], v[192:195], v[106:109]
	v_mfma_i32_16x16x64_i8 v[94:97], v[168:171], v[200:203], v[94:97]
	v_mfma_i32_16x16x64_i8 v[90:93], v[184:187], v[200:203], v[90:93]
	v_mfma_i32_16x16x64_i8 v[78:81], v[168:171], v[216:219], v[78:81]
	v_mfma_i32_16x16x64_i8 v[74:77], v[184:187], v[216:219], v[74:77]
	v_mfma_i32_16x16x64_i8 v[70:73], v[168:171], v[224:227], v[70:73]
	v_mfma_i32_16x16x64_i8 v[66:69], v[184:187], v[224:227], v[66:69]
	v_mfma_i32_16x16x64_i8 v[110:113], v[180:183], v[196:199], v[110:113]
	v_mfma_i32_16x16x64_i8 v[106:109], v[188:191], v[196:199], v[106:109]
	v_mfma_i32_16x16x64_i8 v[94:97], v[180:183], v[212:215], v[94:97]
	v_mfma_i32_16x16x64_i8 v[90:93], v[188:191], v[212:215], v[90:93]
	v_mfma_i32_16x16x64_i8 v[78:81], v[180:183], v[220:223], v[78:81]
	v_mfma_i32_16x16x64_i8 v[74:77], v[188:191], v[220:223], v[74:77]
	v_mfma_i32_16x16x64_i8 v[70:73], v[180:183], v[228:231], v[70:73]
	v_mfma_i32_16x16x64_i8 v[66:69], v[188:191], v[228:231], v[66:69]
	s_setprio 0
	s_barrier
	s_add_i32 s31, s31, s42
	v_lshl_add_u64 v[172:173], s[6:7], 0, v[136:137]
	s_mov_b32 m0, s31
	s_nop 0
	global_load_lds_dwordx4 v[172:173], off
	s_add_i32 m0, s31, 0x2000
	s_add_u32 s34, s6, 0x10000
	v_lshl_add_u64 v[232:233], s[6:7], 0, v[132:133]
	s_addc_u32 s35, s7, 0
	s_add_i32 s31, s38, s42
	global_load_lds_dwordx4 v[232:233], off
	v_lshl_add_u64 v[234:235], s[34:35], 0, v[136:137]
	s_mov_b32 m0, s31
	v_lshl_add_u64 v[236:237], s[26:27], 0, v[134:135]
	global_load_lds_dwordx4 v[234:235], off
	v_lshl_add_u64 v[234:235], s[34:35], 0, v[132:133]
	s_add_i32 m0, s31, 0x2000
	s_nop 0
	global_load_lds_dwordx4 v[234:235], off
	v_lshl_add_u64 v[234:235], s[26:27], 0, v[138:139]
	s_mov_b32 m0, s43
	s_nop 0
	global_load_lds_dwordx4 v[234:235], off
	s_mov_b32 m0, s44
	s_nop 0
	global_load_lds_dwordx4 v[236:237], off
	ds_read_b128 v[192:195], v179 offset:16384
	ds_read_b128 v[196:199], v179 offset:17408
	ds_read_b128 v[200:203], v179 offset:18432
	ds_read_b128 v[212:215], v179 offset:19456
	ds_read_b128 v[216:219], v179 offset:20480
	ds_read_b128 v[220:223], v179 offset:21504
	ds_read_b128 v[224:227], v179 offset:22528
	ds_read_b128 v[228:231], v179 offset:23552
	s_waitcnt vmcnt(8)
	s_waitcnt lgkmcnt(0)
	s_barrier
; #define PG8_STAGE(bufoff, gbase, voff) do { _Pragma("unroll") for (int _i = 0; _i < 2; ++_i) \
;         __builtin_amdgcn_global_load_lds((const unsigned*)((const char*)(gbase) + (voff)[_i]), (LAS unsigned*)(lds + (bufoff) + ldsw + _i * 8192), 16, 0, 0); } while (0)
; #define PG8_LDA(dst, b, h) do { _Pragma("unroll") for (int m = 0; m < 4; ++m) _Pragma("unroll") for (int k = 0; k < 2; ++k) dst[m][k] = *(const LAS bf16x8*)(lds + PG8_SA(b, h) + aoff + m * 2048 + k * 1024); } while (0)
; #define PG8_LDB(dst, b, h) do { _Pragma("unroll") for (int n = 0; n < 2; ++n) _Pragma("unroll") for (int k = 0; k < 2; ++k) dst[n][k] = *(const LAS bf16x8*)(lds + PG8_SB(b, h) + boff + n * 2048 + k * 1024); } while (0)
; #define PG8_MMA(ai, bj, At, Bt) do { __builtin_amdgcn_s_setprio(1); _Pragma("unroll") for (int m = 0; m < 4; ++m) _Pragma("unroll") for (int n = 0; n < 2; ++n) _Pragma("unroll") for (int k = 0; k < 2; ++k) \
;         acc[ai][bj][m][n] = mma16<I8>(Bt[n][k], At[m][k], acc[ai][bj][m][n]); __builtin_amdgcn_s_setprio(0); } while (0)
; #define PG8_WAIT_V(n) asm volatile("s_waitcnt vmcnt(" #n ")" ::: "memory")
; #define PG8_WAIT_L(n) asm volatile("s_waitcnt lgkmcnt(" #n ")" ::: "memory")
; #define PG8_BAR __builtin_amdgcn_s_barrier()
; #define PG8_SCHED __builtin_amdgcn_sched_barrier(0)
; template <class Epi, class Sched, bool I8 = false>
; __device__ __forceinline__ void gemm_phase(LAS unsigned char* lds, const Gemm g, const Sched& S, const Epi& E) {
;     ...
;             PG8_WAIT_V(8); PG8_WAIT_L(0); PG8_BAR; PG8_MMA(1, 0, At, B0); PG8_MMA(1, 1, At, B1); PG8_BAR; PG8_SCHED;
;             PG8_LDB(B0, 1, 0); PG8_LDB(B1, 1, 1); PG8_SCHED; PG8_LDA(At, 1, 0); PG8_STAGE(PG8_SA(0, 1), a2 + hstepA, voffA);
;             PG8_WAIT_V(8); PG8_WAIT_L(0); PG8_BAR; PG8_MMA(0, 0, At, B0); PG8_MMA(0, 1, At, B1); PG8_BAR; PG8_SCHED;
	s_setprio 1
	s_waitcnt lgkmcnt(0)
	v_mfma_i32_16x16x64_i8 v[62:65], v[152:155], v[192:195], v[62:65]
	v_mfma_i32_16x16x64_i8 v[58:61], v[160:163], v[192:195], v[58:61]
	v_mfma_i32_16x16x64_i8 v[54:57], v[152:155], v[200:203], v[54:57]
	v_mfma_i32_16x16x64_i8 v[50:53], v[160:163], v[200:203], v[50:53]
	v_mfma_i32_16x16x64_i8 v[30:33], v[152:155], v[216:219], v[30:33]
	v_mfma_i32_16x16x64_i8 v[26:29], v[160:163], v[216:219], v[26:29]
	v_mfma_i32_16x16x64_i8 v[14:17], v[152:155], v[224:227], v[14:17]
	v_mfma_i32_16x16x64_i8 v[10:13], v[160:163], v[224:227], v[10:13]
	v_mfma_i32_16x16x64_i8 v[62:65], v[156:159], v[196:199], v[62:65]
	v_mfma_i32_16x16x64_i8 v[58:61], v[164:167], v[196:199], v[58:61]
	v_mfma_i32_16x16x64_i8 v[54:57], v[156:159], v[212:215], v[54:57]
	v_mfma_i32_16x16x64_i8 v[50:53], v[164:167], v[212:215], v[50:53]
	v_mfma_i32_16x16x64_i8 v[30:33], v[156:159], v[220:223], v[30:33]
	v_mfma_i32_16x16x64_i8 v[26:29], v[164:167], v[220:223], v[26:29]
	v_mfma_i32_16x16x64_i8 v[14:17], v[156:159], v[228:231], v[14:17]
	v_mfma_i32_16x16x64_i8 v[10:13], v[164:167], v[228:231], v[10:13]
	s_setprio 0
	s_setprio 1
	v_mfma_i32_16x16x64_i8 v[46:49], v[168:171], v[192:195], v[46:49]
	v_mfma_i32_16x16x64_i8 v[42:45], v[184:187], v[192:195], v[42:45]
	v_mfma_i32_16x16x64_i8 v[38:41], v[168:171], v[200:203], v[38:41]
	v_mfma_i32_16x16x64_i8 v[34:37], v[184:187], v[200:203], v[34:37]
	v_mfma_i32_16x16x64_i8 v[22:25], v[168:171], v[216:219], v[22:25]
	v_mfma_i32_16x16x64_i8 v[18:21], v[184:187], v[216:219], v[18:21]
	v_mfma_i32_16x16x64_i8 v[6:9], v[168:171], v[224:227], v[6:9]
	v_mfma_i32_16x16x64_i8 v[2:5], v[184:187], v[224:227], v[2:5]
	v_mfma_i32_16x16x64_i8 v[46:49], v[180:183], v[196:199], v[46:49]
	v_mfma_i32_16x16x64_i8 v[42:45], v[188:191], v[196:199], v[42:45]
	v_mfma_i32_16x16x64_i8 v[38:41], v[180:183], v[212:215], v[38:41]
	v_mfma_i32_16x16x64_i8 v[34:37], v[188:191], v[212:215], v[34:37]
	v_mfma_i32_16x16x64_i8 v[22:25], v[180:183], v[220:223], v[22:25]
	v_mfma_i32_16x16x64_i8 v[18:21], v[188:191], v[220:223], v[18:21]
	v_mfma_i32_16x16x64_i8 v[6:9], v[180:183], v[228:231], v[6:9]
	v_mfma_i32_16x16x64_i8 v[2:5], v[188:191], v[228:231], v[2:5]
	s_setprio 0
	s_barrier
	s_add_i32 s31, 0, 0x18000
	s_add_i32 s34, 0, 0x1c000
	s_add_u32 s26, s26, 0x40000
	s_addc_u32 s27, s27, 0
	s_mov_b32 m0, s45
	v_lshl_add_u64 v[238:239], s[26:27], 0, v[138:139]
	global_load_lds_dwordx4 v[238:239], off
	v_lshl_add_u64 v[238:239], s[26:27], 0, v[134:135]
	s_mov_b32 m0, s82
	s_nop 0
	global_load_lds_dwordx4 v[238:239], off
	v_add_u32_e32 v149, s31, v175
	ds_read_b128 v[152:155], v149
	ds_read_b128 v[156:159], v149 offset:1024
	ds_read_b128 v[160:163], v149 offset:2048
	ds_read_b128 v[164:167], v149 offset:3072
	v_add_u32_e32 v149, s34, v175
	ds_read_b128 v[168:171], v149
	ds_read_b128 v[180:183], v149 offset:1024
	ds_read_b128 v[184:187], v149 offset:2048
	ds_read_b128 v[188:191], v149 offset:3072
	ds_read_b128 v[192:195], v179 offset:32768
	ds_read_b128 v[196:199], v179 offset:33792
	ds_read_b128 v[200:203], v179 offset:34816
	ds_read_b128 v[212:215], v179 offset:35840
	ds_read_b128 v[216:219], v179 offset:36864
	ds_read_b128 v[220:223], v179 offset:37888
	ds_read_b128 v[224:227], v179 offset:38912
	ds_read_b128 v[228:231], v179 offset:39936
	s_waitcnt vmcnt(8)
	s_waitcnt lgkmcnt(0)
	s_barrier
	s_setprio 1
	s_waitcnt lgkmcnt(0)
	v_mfma_i32_16x16x64_i8 v[126:129], v[152:155], v[192:195], v[126:129]
	v_mfma_i32_16x16x64_i8 v[122:125], v[160:163], v[192:195], v[122:125]
	v_mfma_i32_16x16x64_i8 v[118:121], v[152:155], v[200:203], v[118:121]
	v_mfma_i32_16x16x64_i8 v[114:117], v[160:163], v[200:203], v[114:117]
	v_mfma_i32_16x16x64_i8 v[102:105], v[152:155], v[216:219], v[102:105]
	v_mfma_i32_16x16x64_i8 v[98:101], v[160:163], v[216:219], v[98:101]
	v_mfma_i32_16x16x64_i8 v[86:89], v[152:155], v[224:227], v[86:89]
	v_mfma_i32_16x16x64_i8 v[82:85], v[160:163], v[224:227], v[82:85]
	v_mfma_i32_16x16x64_i8 v[126:129], v[156:159], v[196:199], v[126:129]
	v_mfma_i32_16x16x64_i8 v[122:125], v[164:167], v[196:199], v[122:125]
	v_mfma_i32_16x16x64_i8 v[118:121], v[156:159], v[212:215], v[118:121]
	v_mfma_i32_16x16x64_i8 v[114:117], v[164:167], v[212:215], v[114:117]
	v_mfma_i32_16x16x64_i8 v[102:105], v[156:159], v[220:223], v[102:105]
	v_mfma_i32_16x16x64_i8 v[98:101], v[164:167], v[220:223], v[98:101]
	v_mfma_i32_16x16x64_i8 v[86:89], v[156:159], v[228:231], v[86:89]
	v_mfma_i32_16x16x64_i8 v[82:85], v[164:167], v[228:231], v[82:85]
	s_setprio 0
	s_setprio 1
	v_mfma_i32_16x16x64_i8 v[110:113], v[168:171], v[192:195], v[110:113]
	v_mfma_i32_16x16x64_i8 v[106:109], v[184:187], v[192:195], v[106:109]
	v_mfma_i32_16x16x64_i8 v[94:97], v[168:171], v[200:203], v[94:97]
	v_mfma_i32_16x16x64_i8 v[90:93], v[184:187], v[200:203], v[90:93]
	v_mfma_i32_16x16x64_i8 v[78:81], v[168:171], v[216:219], v[78:81]
	v_mfma_i32_16x16x64_i8 v[74:77], v[184:187], v[216:219], v[74:77]
	v_mfma_i32_16x16x64_i8 v[70:73], v[168:171], v[224:227], v[70:73]
	v_mfma_i32_16x16x64_i8 v[66:69], v[184:187], v[224:227], v[66:69]
	v_mfma_i32_16x16x64_i8 v[110:113], v[180:183], v[196:199], v[110:113]
	v_mfma_i32_16x16x64_i8 v[106:109], v[188:191], v[196:199], v[106:109]
	v_mfma_i32_16x16x64_i8 v[94:97], v[180:183], v[212:215], v[94:97]
	v_mfma_i32_16x16x64_i8 v[90:93], v[188:191], v[212:215], v[90:93]
	v_mfma_i32_16x16x64_i8 v[78:81], v[180:183], v[220:223], v[78:81]
	v_mfma_i32_16x16x64_i8 v[74:77], v[188:191], v[220:223], v[74:77]
	v_mfma_i32_16x16x64_i8 v[70:73], v[180:183], v[228:231], v[70:73]
	v_mfma_i32_16x16x64_i8 v[66:69], v[188:191], v[228:231], v[66:69]
	s_setprio 0
	s_barrier
; #define PG8_STAGE(bufoff, gbase, voff) do { _Pragma("unroll") for (int _i = 0; _i < 2; ++_i) \
;         __builtin_amdgcn_global_load_lds((const unsigned*)((const char*)(gbase) + (voff)[_i]), (LAS unsigned*)(lds + (bufoff) + ldsw + _i * 8192), 16, 0, 0); } while (0)
; #define PG8_LDA(dst, b, h) do { _Pragma("unroll") for (int m = 0; m < 4; ++m) _Pragma("unroll") for (int k = 0; k < 2; ++k) dst[m][k] = *(const LAS bf16x8*)(lds + PG8_SA(b, h) + aoff + m * 2048 + k * 1024); } while (0)
; #define PG8_MMA(ai, bj, At, Bt) do { __builtin_amdgcn_s_setprio(1); _Pragma("unroll") for (int m = 0; m < 4; ++m) _Pragma("unroll") for (int n = 0; n < 2; ++n) _Pragma("unroll") for (int k = 0; k < 2; ++k) \
;         acc[ai][bj][m][n] = mma16<I8>(Bt[n][k], At[m][k], acc[ai][bj][m][n]); __builtin_amdgcn_s_setprio(0); } while (0)
; #define PG8_WAIT_V(n) asm volatile("s_waitcnt vmcnt(" #n ")" ::: "memory")
; #define PG8_WAIT_L(n) asm volatile("s_waitcnt lgkmcnt(" #n ")" ::: "memory")
; #define PG8_BAR __builtin_amdgcn_s_barrier()
; #define PG8_SCHED __builtin_amdgcn_sched_barrier(0)
; template <class Epi, class Sched, bool I8 = false>
; __device__ __forceinline__ void gemm_phase(LAS unsigned char* lds, const Gemm g, const Sched& S, const Epi& E) {
;     ...
;             PG8_LDA(At, 1, 1); PG8_STAGE(PG8_SB(1, 0), b3, voffB); PG8_STAGE(PG8_SB(1, 1), b3 + hstepB, voffB); PG8_STAGE(PG8_SA(1, 0), a3, voffA);
;             PG8_WAIT_V(8); PG8_WAIT_L(0); PG8_BAR; PG8_MMA(1, 0, At, B0); PG8_MMA(1, 1, At, B1); PG8_BAR; PG8_SCHED;
;     ...
;         if (PG8_ALIGN) { if (wr == 0) PG8_BAR; }
	s_add_i32 s26, s31, s42
	v_lshl_add_u64 v[172:173], v[172:173], 0, s[12:13]
	s_mov_b32 m0, s26
	s_nop 0
	global_load_lds_dwordx4 v[172:173], off
	s_add_i32 m0, s26, 0x2000
	s_add_u32 s6, s6, 0x10080
	v_lshl_add_u64 v[172:173], v[232:233], 0, s[12:13]
	s_addc_u32 s7, s7, 0
	s_add_i32 s26, s34, s42
	global_load_lds_dwordx4 v[172:173], off
	v_lshl_add_u64 v[172:173], s[6:7], 0, v[136:137]
	s_mov_b32 m0, s26
	s_nop 0
	global_load_lds_dwordx4 v[172:173], off
	v_lshl_add_u64 v[172:173], s[6:7], 0, v[132:133]
	s_add_i32 m0, s26, 0x2000
	s_nop 0
	global_load_lds_dwordx4 v[172:173], off
	v_lshl_add_u64 v[172:173], v[234:235], 0, s[12:13]
	s_mov_b32 m0, s83
	s_nop 0
	global_load_lds_dwordx4 v[172:173], off
	v_lshl_add_u64 v[172:173], v[236:237], 0, s[12:13]
	s_mov_b32 m0, s94
	s_nop 0
	global_load_lds_dwordx4 v[172:173], off
	ds_read_b128 v[192:195], v179 offset:49152
	ds_read_b128 v[196:199], v179 offset:50176
	ds_read_b128 v[200:203], v179 offset:51200
	ds_read_b128 v[212:215], v179 offset:52224
	ds_read_b128 v[216:219], v179 offset:53248
	ds_read_b128 v[220:223], v179 offset:54272
	ds_read_b128 v[224:227], v179 offset:55296
	ds_read_b128 v[228:231], v179 offset:56320
	s_waitcnt vmcnt(8)
	s_waitcnt lgkmcnt(0)
	s_barrier
	s_setprio 1
	s_waitcnt lgkmcnt(0)
	v_mfma_i32_16x16x64_i8 v[62:65], v[152:155], v[192:195], v[62:65]
	v_mfma_i32_16x16x64_i8 v[58:61], v[160:163], v[192:195], v[58:61]
	v_mfma_i32_16x16x64_i8 v[54:57], v[152:155], v[200:203], v[54:57]
	v_mfma_i32_16x16x64_i8 v[50:53], v[160:163], v[200:203], v[50:53]
	v_mfma_i32_16x16x64_i8 v[30:33], v[152:155], v[216:219], v[30:33]
	v_mfma_i32_16x16x64_i8 v[26:29], v[160:163], v[216:219], v[26:29]
	v_mfma_i32_16x16x64_i8 v[14:17], v[152:155], v[224:227], v[14:17]
	v_mfma_i32_16x16x64_i8 v[10:13], v[160:163], v[224:227], v[10:13]
	v_mfma_i32_16x16x64_i8 v[62:65], v[156:159], v[196:199], v[62:65]
	v_mfma_i32_16x16x64_i8 v[58:61], v[164:167], v[196:199], v[58:61]
	v_mfma_i32_16x16x64_i8 v[54:57], v[156:159], v[212:215], v[54:57]
	v_mfma_i32_16x16x64_i8 v[50:53], v[164:167], v[212:215], v[50:53]
	v_mfma_i32_16x16x64_i8 v[30:33], v[156:159], v[220:223], v[30:33]
	v_mfma_i32_16x16x64_i8 v[26:29], v[164:167], v[220:223], v[26:29]
	v_mfma_i32_16x16x64_i8 v[14:17], v[156:159], v[228:231], v[14:17]
	v_mfma_i32_16x16x64_i8 v[10:13], v[164:167], v[228:231], v[10:13]
	s_setprio 0
	s_setprio 1
	v_mfma_i32_16x16x64_i8 v[46:49], v[168:171], v[192:195], v[46:49]
	v_mfma_i32_16x16x64_i8 v[42:45], v[184:187], v[192:195], v[42:45]
	v_mfma_i32_16x16x64_i8 v[38:41], v[168:171], v[200:203], v[38:41]
	v_mfma_i32_16x16x64_i8 v[34:37], v[184:187], v[200:203], v[34:37]
	v_mfma_i32_16x16x64_i8 v[22:25], v[168:171], v[216:219], v[22:25]
	v_mfma_i32_16x16x64_i8 v[18:21], v[184:187], v[216:219], v[18:21]
	v_mfma_i32_16x16x64_i8 v[6:9], v[168:171], v[224:227], v[6:9]
	v_mfma_i32_16x16x64_i8 v[2:5], v[184:187], v[224:227], v[2:5]
	v_mfma_i32_16x16x64_i8 v[46:49], v[180:183], v[196:199], v[46:49]
	v_mfma_i32_16x16x64_i8 v[42:45], v[188:191], v[196:199], v[42:45]
	v_mfma_i32_16x16x64_i8 v[38:41], v[180:183], v[212:215], v[38:41]
	v_mfma_i32_16x16x64_i8 v[34:37], v[188:191], v[212:215], v[34:37]
	v_mfma_i32_16x16x64_i8 v[22:25], v[180:183], v[220:223], v[22:25]
	v_mfma_i32_16x16x64_i8 v[18:21], v[188:191], v[220:223], v[18:21]
	v_mfma_i32_16x16x64_i8 v[6:9], v[180:183], v[228:231], v[6:9]
	v_mfma_i32_16x16x64_i8 v[2:5], v[188:191], v[228:231], v[2:5]
	s_setprio 0
	s_barrier
	s_add_i32 s30, s30, 2
	s_add_u32 s0, s0, 0x100
	s_addc_u32 s1, s1, 0
	s_add_u32 s24, s24, 0x100
	s_addc_u32 s25, s25, 0
	s_cmp_gt_u32 s30, 13
	s_cbranch_scc0 .LBB0_539
	s_and_b64 vcc, exec, s[36:37]
	s_cbranch_vccz .LBB0_542
	s_barrier

; #define PG8_STAGE(bufoff, gbase, voff) do { _Pragma("unroll") for (int _i = 0; _i < 2; ++_i) \
;         __builtin_amdgcn_global_load_lds((const unsigned*)((const char*)(gbase) + (voff)[_i]), (LAS unsigned*)(lds + (bufoff) + ldsw + _i * 8192), 16, 0, 0); } while (0)
; #define PG8_LDA(dst, b, h) do { _Pragma("unroll") for (int m = 0; m < 4; ++m) _Pragma("unroll") for (int k = 0; k < 2; ++k) dst[m][k] = *(const LAS bf16x8*)(lds + PG8_SA(b, h) + aoff + m * 2048 + k * 1024); } while (0)
; #define PG8_LDB(dst, b, h) do { _Pragma("unroll") for (int n = 0; n < 2; ++n) _Pragma("unroll") for (int k = 0; k < 2; ++k) dst[n][k] = *(const LAS bf16x8*)(lds + PG8_SB(b, h) + boff + n * 2048 + k * 1024); } while (0)
; #define PG8_MMA(ai, bj, At, Bt) do { __builtin_amdgcn_s_setprio(1); _Pragma("unroll") for (int m = 0; m < 4; ++m) _Pragma("unroll") for (int n = 0; n < 2; ++n) _Pragma("unroll") for (int k = 0; k < 2; ++k) \
;         acc[ai][bj][m][n] = mma16<I8>(Bt[n][k], At[m][k], acc[ai][bj][m][n]); __builtin_amdgcn_s_setprio(0); } while (0)
; #define PG8_WAIT_V(n) asm volatile("s_waitcnt vmcnt(" #n ")" ::: "memory")
; #define PG8_WAIT_L(n) asm volatile("s_waitcnt lgkmcnt(" #n ")" ::: "memory")
; #define PG8_BAR __builtin_amdgcn_s_barrier()
; #define PG8_SCHED __builtin_amdgcn_sched_barrier(0)
; template <class Epi, class Sched, bool I8 = false>
; __device__ __forceinline__ void gemm_phase(LAS unsigned char* lds, const Gemm g, const Sched& S, const Epi& E) {
;     ...
;         for (int t = 0; t < nt; t += 2) {
;             const bool last = (t == nt - 2);
;             const char* a1 = cA + (size_t)(t + 1) * kstep;
;             const char* a2 = last ? nA : cA + (size_t)(t + 2) * kstep; const char* b2 = last ? nB : cB + (size_t)(t + 2) * kstep;
;             const char* a3 = a2 + kstep; const char* b3 = b2 + kstep;
;             if (PG8_SP2) {
;             PG8_LDB(B0, 0, 0); PG8_LDB(B1, 0, 1); PG8_SCHED; PG8_LDA(At, 0, 0); PG8_STAGE(PG8_SA(1, 1), a1 + hstepA, voffA);
;             PG8_WAIT_V(8); PG8_WAIT_L(0); PG8_BAR; PG8_MMA(0, 0, At, B0); PG8_MMA(0, 1, At, B1); PG8_BAR; PG8_SCHED;
;             PG8_LDA(At, 0, 1); PG8_STAGE(PG8_SB(0, 0), b2, voffB); PG8_STAGE(PG8_SB(0, 1), b2 + hstepB, voffB); PG8_STAGE(PG8_SA(0, 0), a2, voffA);
;             PG8_WAIT_V(8); PG8_WAIT_L(0); PG8_BAR; PG8_MMA(1, 0, At, B0); PG8_MMA(1, 1, At, B1); PG8_BAR; PG8_SCHED;
.LBB0_768:
	s_add_u32 s40, s0, 0xfffc0080
	s_addc_u32 s41, s1, -1
	s_add_i32 s46, 0, 0x10000
	s_cmp_eq_u32 s45, 12
	s_cselect_b32 s43, s37, s41
	s_cselect_b32 s42, s36, s40
	s_cselect_b32 s41, s9, s44
	s_cselect_b32 s40, s17, s27
	s_add_i32 s49, 0, 0x14000
	v_lshl_add_u64 v[136:137], s[0:1], 0, v[170:171]
	s_add_i32 m0, s14, 0xc000
	s_nop 0
	global_load_lds_dwordx4 v[136:137], off
	v_lshl_add_u64 v[136:137], s[0:1], 0, v[172:173]
	s_add_i32 m0, s14, 0xe000
	s_nop 0
	global_load_lds_dwordx4 v[136:137], off
	v_add_u32_e32 v14, s46, v163
	v_add_u32_e32 v130, s49, v163
	ds_read_b128 v[2:5], v14
	ds_read_b128 v[6:9], v14 offset:1024
	ds_read_b128 v[10:13], v14 offset:2048
	ds_read_b128 v[14:17], v14 offset:3072
	ds_read_b128 v[132:135], v130
	ds_read_b128 v[174:177], v130 offset:1024
	ds_read_b128 v[178:181], v130 offset:2048
	ds_read_b128 v[182:185], v130 offset:3072
	ds_read_b128 v[186:189], v167
	ds_read_b128 v[190:193], v167 offset:1024
	ds_read_b128 v[194:197], v167 offset:2048
	ds_read_b128 v[198:201], v167 offset:3072
	ds_read_b128 v[212:215], v167 offset:4096
	ds_read_b128 v[216:219], v167 offset:5120
	ds_read_b128 v[220:223], v167 offset:6144
	ds_read_b128 v[224:227], v167 offset:7168
	s_waitcnt vmcnt(8)
	s_waitcnt lgkmcnt(0)
	s_barrier
	s_setprio 1
	s_waitcnt lgkmcnt(0)
	v_mfma_f32_16x16x32_bf16 v[150:153], v[2:5], v[186:189], v[150:153]
	v_mfma_f32_16x16x32_bf16 v[146:149], v[10:13], v[186:189], v[146:149]
	v_mfma_f32_16x16x32_bf16 v[142:145], v[2:5], v[194:197], v[142:145]
	v_mfma_f32_16x16x32_bf16 v[136:139], v[10:13], v[194:197], v[138:141]
	v_mfma_f32_16x16x32_bf16 v[126:129], v[2:5], v[212:215], v[126:129]
	v_mfma_f32_16x16x32_bf16 v[122:125], v[10:13], v[212:215], v[122:125]
	v_mfma_f32_16x16x32_bf16 v[118:121], v[2:5], v[220:223], v[118:121]
	v_mfma_f32_16x16x32_bf16 v[114:117], v[10:13], v[220:223], v[114:117]
	v_mfma_f32_16x16x32_bf16 v[150:153], v[6:9], v[190:193], v[150:153]
	v_mfma_f32_16x16x32_bf16 v[146:149], v[14:17], v[190:193], v[146:149]
	v_mfma_f32_16x16x32_bf16 v[142:145], v[6:9], v[198:201], v[142:145]
	v_mfma_f32_16x16x32_bf16 v[136:139], v[14:17], v[198:201], v[136:139]
	v_mfma_f32_16x16x32_bf16 v[126:129], v[6:9], v[216:219], v[126:129]
	v_mfma_f32_16x16x32_bf16 v[122:125], v[14:17], v[216:219], v[122:125]
	v_mfma_f32_16x16x32_bf16 v[118:121], v[6:9], v[224:227], v[118:121]
	v_mfma_f32_16x16x32_bf16 v[114:117], v[14:17], v[224:227], v[114:117]
	s_setprio 0
	s_setprio 1
	v_mfma_f32_16x16x32_bf16 v[110:113], v[132:135], v[186:189], v[110:113]
	v_mfma_f32_16x16x32_bf16 v[106:109], v[178:181], v[186:189], v[106:109]
	v_mfma_f32_16x16x32_bf16 v[102:105], v[132:135], v[194:197], v[102:105]
	v_mfma_f32_16x16x32_bf16 v[98:101], v[178:181], v[194:197], v[98:101]
	v_mfma_f32_16x16x32_bf16 v[94:97], v[132:135], v[212:215], v[94:97]
	v_mfma_f32_16x16x32_bf16 v[90:93], v[178:181], v[212:215], v[90:93]
	v_mfma_f32_16x16x32_bf16 v[86:89], v[132:135], v[220:223], v[86:89]
	v_mfma_f32_16x16x32_bf16 v[82:85], v[178:181], v[220:223], v[82:85]
	v_mfma_f32_16x16x32_bf16 v[110:113], v[174:177], v[190:193], v[110:113]
	v_mfma_f32_16x16x32_bf16 v[106:109], v[182:185], v[190:193], v[106:109]
	v_mfma_f32_16x16x32_bf16 v[102:105], v[174:177], v[198:201], v[102:105]
	v_mfma_f32_16x16x32_bf16 v[98:101], v[182:185], v[198:201], v[98:101]
	v_mfma_f32_16x16x32_bf16 v[94:97], v[174:177], v[216:219], v[94:97]
	v_mfma_f32_16x16x32_bf16 v[90:93], v[182:185], v[216:219], v[90:93]
	v_mfma_f32_16x16x32_bf16 v[86:89], v[174:177], v[224:227], v[86:89]
	v_mfma_f32_16x16x32_bf16 v[82:85], v[182:185], v[224:227], v[82:85]
	s_setprio 0
	s_barrier
	s_add_i32 s46, s46, s21
	v_lshl_add_u64 v[202:203], s[40:41], 0, v[158:159]
	s_mov_b32 m0, s46
	s_nop 0
	global_load_lds_dwordx4 v[202:203], off
	s_add_i32 m0, s46, 0x2000
	s_add_u32 s46, s40, 0x10000
	v_lshl_add_u64 v[232:233], s[40:41], 0, v[154:155]
	s_addc_u32 s47, s41, 0
	s_add_i32 s49, s49, s21
	global_load_lds_dwordx4 v[232:233], off
	v_lshl_add_u64 v[140:141], s[46:47], 0, v[158:159]
	s_mov_b32 m0, s49
	v_lshl_add_u64 v[234:235], s[42:43], 0, v[160:161]
	global_load_lds_dwordx4 v[140:141], off
	v_lshl_add_u64 v[140:141], s[46:47], 0, v[154:155]
	s_add_i32 m0, s49, 0x2000
	v_lshl_add_u64 v[236:237], s[42:43], 0, v[156:157]
	global_load_lds_dwordx4 v[140:141], off
	s_mov_b32 m0, s14
	s_nop 0
	global_load_lds_dwordx4 v[234:235], off
	s_mov_b32 m0, s22
	s_nop 0
	global_load_lds_dwordx4 v[236:237], off
	ds_read_b128 v[186:189], v167 offset:16384
	ds_read_b128 v[190:193], v167 offset:17408
	ds_read_b128 v[194:197], v167 offset:18432
	ds_read_b128 v[198:201], v167 offset:19456
	ds_read_b128 v[212:215], v167 offset:20480
	ds_read_b128 v[216:219], v167 offset:21504
	ds_read_b128 v[220:223], v167 offset:22528
	ds_read_b128 v[224:227], v167 offset:23552
	s_waitcnt vmcnt(8)
	s_waitcnt lgkmcnt(0)
	s_barrier
; #define PG8_STAGE(bufoff, gbase, voff) do { _Pragma("unroll") for (int _i = 0; _i < 2; ++_i) \
;         __builtin_amdgcn_global_load_lds((const unsigned*)((const char*)(gbase) + (voff)[_i]), (LAS unsigned*)(lds + (bufoff) + ldsw + _i * 8192), 16, 0, 0); } while (0)
; #define PG8_LDA(dst, b, h) do { _Pragma("unroll") for (int m = 0; m < 4; ++m) _Pragma("unroll") for (int k = 0; k < 2; ++k) dst[m][k] = *(const LAS bf16x8*)(lds + PG8_SA(b, h) + aoff + m * 2048 + k * 1024); } while (0)
; #define PG8_LDB(dst, b, h) do { _Pragma("unroll") for (int n = 0; n < 2; ++n) _Pragma("unroll") for (int k = 0; k < 2; ++k) dst[n][k] = *(const LAS bf16x8*)(lds + PG8_SB(b, h) + boff + n * 2048 + k * 1024); } while (0)
; #define PG8_MMA(ai, bj, At, Bt) do { __builtin_amdgcn_s_setprio(1); _Pragma("unroll") for (int m = 0; m < 4; ++m) _Pragma("unroll") for (int n = 0; n < 2; ++n) _Pragma("unroll") for (int k = 0; k < 2; ++k) \
;         acc[ai][bj][m][n] = mma16<I8>(Bt[n][k], At[m][k], acc[ai][bj][m][n]); __builtin_amdgcn_s_setprio(0); } while (0)
; #define PG8_WAIT_V(n) asm volatile("s_waitcnt vmcnt(" #n ")" ::: "memory")
; #define PG8_WAIT_L(n) asm volatile("s_waitcnt lgkmcnt(" #n ")" ::: "memory")
; #define PG8_BAR __builtin_amdgcn_s_barrier()
; #define PG8_SCHED __builtin_amdgcn_sched_barrier(0)
; template <class Epi, class Sched, bool I8 = false>
; __device__ __forceinline__ void gemm_phase(LAS unsigned char* lds, const Gemm g, const Sched& S, const Epi& E) {
;     ...
;             PG8_WAIT_V(8); PG8_WAIT_L(0); PG8_BAR; PG8_MMA(1, 0, At, B0); PG8_MMA(1, 1, At, B1); PG8_BAR; PG8_SCHED;
;             PG8_LDB(B0, 1, 0); PG8_LDB(B1, 1, 1); PG8_SCHED; PG8_LDA(At, 1, 0); PG8_STAGE(PG8_SA(0, 1), a2 + hstepA, voffA);
;             PG8_WAIT_V(8); PG8_WAIT_L(0); PG8_BAR; PG8_MMA(0, 0, At, B0); PG8_MMA(0, 1, At, B1); PG8_BAR; PG8_SCHED;
	s_setprio 1
	s_waitcnt lgkmcnt(0)
	v_mfma_f32_16x16x32_bf16 v[78:81], v[2:5], v[186:189], v[78:81]
	v_mfma_f32_16x16x32_bf16 v[74:77], v[10:13], v[186:189], v[74:77]
	v_mfma_f32_16x16x32_bf16 v[70:73], v[2:5], v[194:197], v[70:73]
	v_mfma_f32_16x16x32_bf16 v[66:69], v[10:13], v[194:197], v[66:69]
	v_mfma_f32_16x16x32_bf16 v[62:65], v[2:5], v[212:215], v[62:65]
	v_mfma_f32_16x16x32_bf16 v[58:61], v[10:13], v[212:215], v[58:61]
	v_mfma_f32_16x16x32_bf16 v[2:5], v[2:5], v[220:223], v[54:57]
	v_mfma_f32_16x16x32_bf16 v[78:81], v[6:9], v[190:193], v[78:81]
	v_mfma_f32_16x16x32_bf16 v[74:77], v[14:17], v[190:193], v[74:77]
	v_mfma_f32_16x16x32_bf16 v[70:73], v[6:9], v[198:201], v[70:73]
	v_mfma_f32_16x16x32_bf16 v[66:69], v[14:17], v[198:201], v[66:69]
	v_mfma_f32_16x16x32_bf16 v[62:65], v[6:9], v[216:219], v[62:65]
	v_mfma_f32_16x16x32_bf16 v[58:61], v[14:17], v[216:219], v[58:61]
	v_mfma_f32_16x16x32_bf16 v[2:5], v[6:9], v[224:227], v[2:5]
	v_mfma_f32_16x16x32_bf16 v[6:9], v[10:13], v[220:223], v[50:53]
	v_mfma_f32_16x16x32_bf16 v[6:9], v[14:17], v[224:227], v[6:9]
	s_setprio 0
	s_setprio 1
	v_mfma_f32_16x16x32_bf16 v[38:41], v[132:135], v[194:197], v[38:41]
	v_mfma_f32_16x16x32_bf16 v[34:37], v[178:181], v[194:197], v[34:37]
	v_mfma_f32_16x16x32_bf16 v[30:33], v[132:135], v[212:215], v[30:33]
	v_mfma_f32_16x16x32_bf16 v[26:29], v[178:181], v[212:215], v[26:29]
	v_mfma_f32_16x16x32_bf16 v[22:25], v[132:135], v[220:223], v[22:25]
	v_mfma_f32_16x16x32_bf16 v[18:21], v[178:181], v[220:223], v[18:21]
	v_mfma_f32_16x16x32_bf16 v[10:13], v[132:135], v[186:189], v[46:49]
	v_mfma_f32_16x16x32_bf16 v[14:17], v[178:181], v[186:189], v[42:45]
	v_mfma_f32_16x16x32_bf16 v[38:41], v[174:177], v[198:201], v[38:41]
	v_mfma_f32_16x16x32_bf16 v[34:37], v[182:185], v[198:201], v[34:37]
	v_mfma_f32_16x16x32_bf16 v[30:33], v[174:177], v[216:219], v[30:33]
	v_mfma_f32_16x16x32_bf16 v[26:29], v[182:185], v[216:219], v[26:29]
	v_mfma_f32_16x16x32_bf16 v[22:25], v[174:177], v[224:227], v[22:25]
	v_mfma_f32_16x16x32_bf16 v[18:21], v[182:185], v[224:227], v[18:21]
	v_mfma_f32_16x16x32_bf16 v[10:13], v[174:177], v[190:193], v[10:13]
	v_mfma_f32_16x16x32_bf16 v[14:17], v[182:185], v[190:193], v[14:17]
	s_setprio 0
	s_barrier
	s_add_i32 s46, 0, 0x18000
	s_add_i32 s47, 0, 0x1c000
	s_add_u32 s42, s42, 0x40000
	s_addc_u32 s43, s43, 0
	s_mov_b32 m0, s23
	v_lshl_add_u64 v[140:141], s[42:43], 0, v[160:161]
	global_load_lds_dwordx4 v[140:141], off
	v_lshl_add_u64 v[140:141], s[42:43], 0, v[156:157]
	s_mov_b32 m0, s24
	s_nop 0
	global_load_lds_dwordx4 v[140:141], off
	v_add_u32_e32 v54, s46, v163
	ds_read_b128 v[42:45], v54
	ds_read_b128 v[46:49], v54 offset:1024
	ds_read_b128 v[50:53], v54 offset:2048
	ds_read_b128 v[132:135], v54 offset:3072
	v_add_u32_e32 v54, s47, v163
	ds_read_b128 v[174:177], v54
	ds_read_b128 v[178:181], v54 offset:1024
	ds_read_b128 v[182:185], v54 offset:2048
	ds_read_b128 v[186:189], v54 offset:3072
	ds_read_b128 v[54:57], v167 offset:32768
	ds_read_b128 v[190:193], v167 offset:33792
	ds_read_b128 v[194:197], v167 offset:34816
	ds_read_b128 v[198:201], v167 offset:35840
	ds_read_b128 v[212:215], v167 offset:36864
	ds_read_b128 v[216:219], v167 offset:37888
	ds_read_b128 v[220:223], v167 offset:38912
	ds_read_b128 v[224:227], v167 offset:39936
	s_waitcnt vmcnt(8)
	s_waitcnt lgkmcnt(0)
	s_barrier
	s_setprio 1
	s_waitcnt lgkmcnt(0)
	v_mfma_f32_16x16x32_bf16 v[150:153], v[42:45], v[54:57], v[150:153]
	v_mfma_f32_16x16x32_bf16 v[146:149], v[50:53], v[54:57], v[146:149]
	v_mfma_f32_16x16x32_bf16 v[140:143], v[42:45], v[194:197], v[142:145]
	v_mfma_f32_16x16x32_bf16 v[136:139], v[50:53], v[194:197], v[136:139]
	v_mfma_f32_16x16x32_bf16 v[126:129], v[42:45], v[212:215], v[126:129]
	v_mfma_f32_16x16x32_bf16 v[122:125], v[50:53], v[212:215], v[122:125]
	v_mfma_f32_16x16x32_bf16 v[118:121], v[42:45], v[220:223], v[118:121]
	v_mfma_f32_16x16x32_bf16 v[114:117], v[50:53], v[220:223], v[114:117]
	v_mfma_f32_16x16x32_bf16 v[150:153], v[46:49], v[190:193], v[150:153]
	v_mfma_f32_16x16x32_bf16 v[146:149], v[132:135], v[190:193], v[146:149]
	v_mfma_f32_16x16x32_bf16 v[142:145], v[46:49], v[198:201], v[140:143]
	v_mfma_f32_16x16x32_bf16 v[138:141], v[132:135], v[198:201], v[136:139]
	v_mfma_f32_16x16x32_bf16 v[126:129], v[46:49], v[216:219], v[126:129]
	v_mfma_f32_16x16x32_bf16 v[122:125], v[132:135], v[216:219], v[122:125]
	v_mfma_f32_16x16x32_bf16 v[118:121], v[46:49], v[224:227], v[118:121]
	v_mfma_f32_16x16x32_bf16 v[114:117], v[132:135], v[224:227], v[114:117]
	s_setprio 0
	s_setprio 1
	v_mfma_f32_16x16x32_bf16 v[110:113], v[174:177], v[54:57], v[110:113]
	v_mfma_f32_16x16x32_bf16 v[54:57], v[182:185], v[54:57], v[106:109]
	v_mfma_f32_16x16x32_bf16 v[106:109], v[186:189], v[190:193], v[54:57]
	v_mfma_f32_16x16x32_bf16 v[54:57], v[174:177], v[194:197], v[102:105]
	v_mfma_f32_16x16x32_bf16 v[102:105], v[178:181], v[198:201], v[54:57]
	v_mfma_f32_16x16x32_bf16 v[54:57], v[182:185], v[194:197], v[98:101]
	v_mfma_f32_16x16x32_bf16 v[98:101], v[186:189], v[198:201], v[54:57]
	v_mfma_f32_16x16x32_bf16 v[54:57], v[174:177], v[212:215], v[94:97]
	v_mfma_f32_16x16x32_bf16 v[94:97], v[178:181], v[216:219], v[54:57]
	v_mfma_f32_16x16x32_bf16 v[54:57], v[182:185], v[212:215], v[90:93]
	v_mfma_f32_16x16x32_bf16 v[90:93], v[186:189], v[216:219], v[54:57]
	v_mfma_f32_16x16x32_bf16 v[54:57], v[174:177], v[220:223], v[86:89]
	v_mfma_f32_16x16x32_bf16 v[86:89], v[178:181], v[224:227], v[54:57]
	v_mfma_f32_16x16x32_bf16 v[54:57], v[182:185], v[220:223], v[82:85]
	v_mfma_f32_16x16x32_bf16 v[110:113], v[178:181], v[190:193], v[110:113]
	v_mfma_f32_16x16x32_bf16 v[82:85], v[186:189], v[224:227], v[54:57]
	s_setprio 0
	s_barrier
; #define PG8_STAGE(bufoff, gbase, voff) do { _Pragma("unroll") for (int _i = 0; _i < 2; ++_i) \
;         __builtin_amdgcn_global_load_lds((const unsigned*)((const char*)(gbase) + (voff)[_i]), (LAS unsigned*)(lds + (bufoff) + ldsw + _i * 8192), 16, 0, 0); } while (0)
; #define PG8_LDA(dst, b, h) do { _Pragma("unroll") for (int m = 0; m < 4; ++m) _Pragma("unroll") for (int k = 0; k < 2; ++k) dst[m][k] = *(const LAS bf16x8*)(lds + PG8_SA(b, h) + aoff + m * 2048 + k * 1024); } while (0)
; #define PG8_MMA(ai, bj, At, Bt) do { __builtin_amdgcn_s_setprio(1); _Pragma("unroll") for (int m = 0; m < 4; ++m) _Pragma("unroll") for (int n = 0; n < 2; ++n) _Pragma("unroll") for (int k = 0; k < 2; ++k) \
;         acc[ai][bj][m][n] = mma16<I8>(Bt[n][k], At[m][k], acc[ai][bj][m][n]); __builtin_amdgcn_s_setprio(0); } while (0)
; #define PG8_WAIT_V(n) asm volatile("s_waitcnt vmcnt(" #n ")" ::: "memory")
; #define PG8_WAIT_L(n) asm volatile("s_waitcnt lgkmcnt(" #n ")" ::: "memory")
; #define PG8_BAR __builtin_amdgcn_s_barrier()
; #define PG8_SCHED __builtin_amdgcn_sched_barrier(0)
; template <class Epi, class Sched, bool I8 = false>
; __device__ __forceinline__ void gemm_phase(LAS unsigned char* lds, const Gemm g, const Sched& S, const Epi& E) {
;     ...
;             PG8_LDA(At, 1, 1); PG8_STAGE(PG8_SB(1, 0), b3, voffB); PG8_STAGE(PG8_SB(1, 1), b3 + hstepB, voffB); PG8_STAGE(PG8_SA(1, 0), a3, voffA);
;             PG8_WAIT_V(8); PG8_WAIT_L(0); PG8_BAR; PG8_MMA(1, 0, At, B0); PG8_MMA(1, 1, At, B1); PG8_BAR; PG8_SCHED;
;     ...
;         if (PG8_ALIGN) { if (wr == 0) PG8_BAR; }
	s_add_i32 s42, s46, s21
	s_nop 2
	v_lshl_add_u64 v[54:55], v[202:203], 0, s[12:13]
	s_mov_b32 m0, s42
	s_nop 0
	global_load_lds_dwordx4 v[54:55], off
	s_add_i32 m0, s42, 0x2000
	s_add_u32 s40, s40, 0x10080
	v_lshl_add_u64 v[54:55], v[232:233], 0, s[12:13]
	s_addc_u32 s41, s41, 0
	s_add_i32 s42, s47, s21
	global_load_lds_dwordx4 v[54:55], off
	v_lshl_add_u64 v[54:55], s[40:41], 0, v[158:159]
	s_mov_b32 m0, s42
	s_nop 0
	global_load_lds_dwordx4 v[54:55], off
	v_lshl_add_u64 v[54:55], s[40:41], 0, v[154:155]
	s_add_i32 m0, s42, 0x2000
	s_nop 0
	global_load_lds_dwordx4 v[54:55], off
	v_lshl_add_u64 v[54:55], v[234:235], 0, s[12:13]
	s_mov_b32 m0, s29
	s_nop 0
	global_load_lds_dwordx4 v[54:55], off
	v_lshl_add_u64 v[54:55], v[236:237], 0, s[12:13]
	s_mov_b32 m0, s30
	s_nop 0
	global_load_lds_dwordx4 v[54:55], off
	ds_read_b128 v[190:193], v167 offset:49152
	ds_read_b128 v[194:197], v167 offset:50176
	ds_read_b128 v[198:201], v167 offset:51200
	ds_read_b128 v[212:215], v167 offset:52224
	ds_read_b128 v[216:219], v167 offset:53248
	ds_read_b128 v[220:223], v167 offset:54272
	ds_read_b128 v[224:227], v167 offset:55296
	ds_read_b128 v[228:231], v167 offset:56320
	s_waitcnt vmcnt(8)
	s_waitcnt lgkmcnt(0)
	s_barrier
	s_setprio 1
	s_waitcnt lgkmcnt(0)
	v_mfma_f32_16x16x32_bf16 v[54:57], v[42:45], v[190:193], v[78:81]
	v_mfma_f32_16x16x32_bf16 v[78:81], v[46:49], v[194:197], v[54:57]
	v_mfma_f32_16x16x32_bf16 v[54:57], v[50:53], v[190:193], v[74:77]
	v_mfma_f32_16x16x32_bf16 v[74:77], v[132:135], v[194:197], v[54:57]
	v_mfma_f32_16x16x32_bf16 v[54:57], v[42:45], v[198:201], v[70:73]
	v_mfma_f32_16x16x32_bf16 v[70:73], v[46:49], v[212:215], v[54:57]
	v_mfma_f32_16x16x32_bf16 v[54:57], v[50:53], v[198:201], v[66:69]
	v_mfma_f32_16x16x32_bf16 v[66:69], v[132:135], v[212:215], v[54:57]
	v_mfma_f32_16x16x32_bf16 v[54:57], v[42:45], v[216:219], v[62:65]
	v_mfma_f32_16x16x32_bf16 v[62:65], v[46:49], v[220:223], v[54:57]
	v_mfma_f32_16x16x32_bf16 v[54:57], v[50:53], v[216:219], v[58:61]
	v_mfma_f32_16x16x32_bf16 v[2:5], v[42:45], v[224:227], v[2:5]
	v_mfma_f32_16x16x32_bf16 v[58:61], v[132:135], v[220:223], v[54:57]
	v_mfma_f32_16x16x32_bf16 v[54:57], v[46:49], v[228:231], v[2:5]
	v_mfma_f32_16x16x32_bf16 v[2:5], v[50:53], v[224:227], v[6:9]
	v_mfma_f32_16x16x32_bf16 v[50:53], v[132:135], v[228:231], v[2:5]
	s_setprio 0
	s_setprio 1
	v_mfma_f32_16x16x32_bf16 v[2:5], v[174:177], v[190:193], v[10:13]
	v_mfma_f32_16x16x32_bf16 v[46:49], v[178:181], v[194:197], v[2:5]
	v_mfma_f32_16x16x32_bf16 v[2:5], v[182:185], v[190:193], v[14:17]
	v_mfma_f32_16x16x32_bf16 v[42:45], v[186:189], v[194:197], v[2:5]
	v_mfma_f32_16x16x32_bf16 v[2:5], v[174:177], v[198:201], v[38:41]
	v_mfma_f32_16x16x32_bf16 v[38:41], v[178:181], v[212:215], v[2:5]
	v_mfma_f32_16x16x32_bf16 v[2:5], v[182:185], v[198:201], v[34:37]
	v_mfma_f32_16x16x32_bf16 v[34:37], v[186:189], v[212:215], v[2:5]
	v_mfma_f32_16x16x32_bf16 v[2:5], v[174:177], v[216:219], v[30:33]
	v_mfma_f32_16x16x32_bf16 v[30:33], v[178:181], v[220:223], v[2:5]
	v_mfma_f32_16x16x32_bf16 v[2:5], v[182:185], v[216:219], v[26:29]
	v_mfma_f32_16x16x32_bf16 v[26:29], v[186:189], v[220:223], v[2:5]
	v_mfma_f32_16x16x32_bf16 v[2:5], v[174:177], v[224:227], v[22:25]
	v_mfma_f32_16x16x32_bf16 v[22:25], v[178:181], v[228:231], v[2:5]
	v_mfma_f32_16x16x32_bf16 v[2:5], v[182:185], v[224:227], v[18:21]
	v_mfma_f32_16x16x32_bf16 v[18:21], v[186:189], v[228:231], v[2:5]
	s_setprio 0
	s_barrier
	s_add_i32 s45, s45, 2
	s_add_u32 s0, s0, 0x100
	s_addc_u32 s1, s1, 0
	s_add_u32 s27, s27, 0x100
	s_addc_u32 s44, s44, 0
	s_cmp_gt_u32 s45, 13
	s_cbranch_scc0 .LBB0_768
	s_and_b64 vcc, exec, s[6:7]
	s_cbranch_vccz .LBB0_771
	s_barrier

; #define PG8_STAGE(bufoff, gbase, voff) do { _Pragma("unroll") for (int _i = 0; _i < 2; ++_i) \
;         __builtin_amdgcn_global_load_lds((const unsigned*)((const char*)(gbase) + (voff)[_i]), (LAS unsigned*)(lds + (bufoff) + ldsw + _i * 8192), 16, 0, 0); } while (0)
; #define PG8_LDA(dst, b, h) do { _Pragma("unroll") for (int m = 0; m < 4; ++m) _Pragma("unroll") for (int k = 0; k < 2; ++k) dst[m][k] = *(const LAS bf16x8*)(lds + PG8_SA(b, h) + aoff + m * 2048 + k * 1024); } while (0)
; #define PG8_LDB(dst, b, h) do { _Pragma("unroll") for (int n = 0; n < 2; ++n) _Pragma("unroll") for (int k = 0; k < 2; ++k) dst[n][k] = *(const LAS bf16x8*)(lds + PG8_SB(b, h) + boff + n * 2048 + k * 1024); } while (0)
; #define PG8_MMA(ai, bj, At, Bt) do { __builtin_amdgcn_s_setprio(1); _Pragma("unroll") for (int m = 0; m < 4; ++m) _Pragma("unroll") for (int n = 0; n < 2; ++n) _Pragma("unroll") for (int k = 0; k < 2; ++k) \
;         acc[ai][bj][m][n] = mma16<I8>(Bt[n][k], At[m][k], acc[ai][bj][m][n]); __builtin_amdgcn_s_setprio(0); } while (0)
; #define PG8_WAIT_V(n) asm volatile("s_waitcnt vmcnt(" #n ")" ::: "memory")
; #define PG8_WAIT_L(n) asm volatile("s_waitcnt lgkmcnt(" #n ")" ::: "memory")
; #define PG8_BAR __builtin_amdgcn_s_barrier()
; #define PG8_SCHED __builtin_amdgcn_sched_barrier(0)
; template <class Epi, class Sched, bool I8 = false>
; __device__ __forceinline__ void gemm_phase(LAS unsigned char* lds, const Gemm g, const Sched& S, const Epi& E) {
;     ...
;         for (int t = 0; t < nt; t += 2) {
;             const bool last = (t == nt - 2);
;             const char* a1 = cA + (size_t)(t + 1) * kstep;
;             const char* a2 = last ? nA : cA + (size_t)(t + 2) * kstep; const char* b2 = last ? nB : cB + (size_t)(t + 2) * kstep;
;             const char* a3 = a2 + kstep; const char* b3 = b2 + kstep;
;             if (PG8_SP2) {
;             PG8_LDB(B0, 0, 0); PG8_LDB(B1, 0, 1); PG8_SCHED; PG8_LDA(At, 0, 0); PG8_STAGE(PG8_SA(1, 1), a1 + hstepA, voffA);
;             PG8_WAIT_V(8); PG8_WAIT_L(0); PG8_BAR; PG8_MMA(0, 0, At, B0); PG8_MMA(0, 1, At, B1); PG8_BAR; PG8_SCHED;
;             PG8_LDA(At, 0, 1); PG8_STAGE(PG8_SB(0, 0), b2, voffB); PG8_STAGE(PG8_SB(0, 1), b2 + hstepB, voffB); PG8_STAGE(PG8_SA(0, 0), a2, voffA);
;             PG8_WAIT_V(8); PG8_WAIT_L(0); PG8_BAR; PG8_MMA(1, 0, At, B0); PG8_MMA(1, 1, At, B1); PG8_BAR; PG8_SCHED;
.LBB0_901:
	s_add_u32 s6, s4, 0x100
	s_addc_u32 s7, s5, 0
	s_cmp_lg_u32 s29, 12
	s_cselect_b32 s8, s6, 0
	s_add_u32 s16, s40, s8
	s_addc_u32 s17, s41, 0
	s_add_i32 s30, 0, 0x10000
	s_add_u32 s8, s0, s8
	s_addc_u32 s9, s1, 0
	s_add_i32 s31, 0, 0x14000
	v_lshl_add_u64 v[202:203], v[138:139], 0, s[4:5]
	s_add_i32 m0, s2, 0xc000
	s_nop 0
	global_load_lds_dwordx4 v[202:203], off
	v_lshl_add_u64 v[202:203], v[140:141], 0, s[4:5]
	s_add_i32 m0, s2, 0xe000
	s_nop 0
	global_load_lds_dwordx4 v[202:203], off
	v_add_u32_e32 v158, s30, v144
	v_add_u32_e32 v174, s31, v144
	ds_read_b128 v[146:149], v158
	ds_read_b128 v[150:153], v158 offset:1024
	ds_read_b128 v[154:157], v158 offset:2048
	ds_read_b128 v[158:161], v158 offset:3072
	ds_read_b128 v[162:165], v174
	ds_read_b128 v[166:169], v174 offset:1024
	ds_read_b128 v[170:173], v174 offset:2048
	ds_read_b128 v[174:177], v174 offset:3072
	ds_read_b128 v[178:181], v145
	ds_read_b128 v[182:185], v145 offset:1024
	ds_read_b128 v[186:189], v145 offset:2048
	ds_read_b128 v[190:193], v145 offset:3072
	ds_read_b128 v[194:197], v145 offset:4096
	ds_read_b128 v[198:201], v145 offset:5120
	ds_read_b128 v[212:215], v145 offset:6144
	ds_read_b128 v[216:219], v145 offset:7168
	s_waitcnt vmcnt(8)
	s_waitcnt lgkmcnt(0)
	s_barrier
	s_setprio 1
	s_waitcnt lgkmcnt(0)
	v_mfma_f32_16x16x32_bf16 v[126:129], v[146:149], v[178:181], v[126:129]
	v_mfma_f32_16x16x32_bf16 v[122:125], v[154:157], v[178:181], v[122:125]
	v_mfma_f32_16x16x32_bf16 v[118:121], v[146:149], v[186:189], v[118:121]
	v_mfma_f32_16x16x32_bf16 v[114:117], v[154:157], v[186:189], v[114:117]
	v_mfma_f32_16x16x32_bf16 v[110:113], v[146:149], v[194:197], v[110:113]
	v_mfma_f32_16x16x32_bf16 v[102:105], v[154:157], v[194:197], v[102:105]
	v_mfma_f32_16x16x32_bf16 v[94:97], v[146:149], v[212:215], v[94:97]
	v_mfma_f32_16x16x32_bf16 v[86:89], v[154:157], v[212:215], v[86:89]
	v_mfma_f32_16x16x32_bf16 v[126:129], v[150:153], v[182:185], v[126:129]
	v_mfma_f32_16x16x32_bf16 v[122:125], v[158:161], v[182:185], v[122:125]
	v_mfma_f32_16x16x32_bf16 v[118:121], v[150:153], v[190:193], v[118:121]
	v_mfma_f32_16x16x32_bf16 v[114:117], v[158:161], v[190:193], v[114:117]
	v_mfma_f32_16x16x32_bf16 v[110:113], v[150:153], v[198:201], v[110:113]
	v_mfma_f32_16x16x32_bf16 v[102:105], v[158:161], v[198:201], v[102:105]
	v_mfma_f32_16x16x32_bf16 v[94:97], v[150:153], v[216:219], v[94:97]
	v_mfma_f32_16x16x32_bf16 v[86:89], v[158:161], v[216:219], v[86:89]
	s_setprio 0
	s_setprio 1
	v_mfma_f32_16x16x32_bf16 v[106:109], v[162:165], v[178:181], v[106:109]
	v_mfma_f32_16x16x32_bf16 v[98:101], v[170:173], v[178:181], v[98:101]
	v_mfma_f32_16x16x32_bf16 v[90:93], v[162:165], v[186:189], v[90:93]
	v_mfma_f32_16x16x32_bf16 v[82:85], v[170:173], v[186:189], v[82:85]
	v_mfma_f32_16x16x32_bf16 v[78:81], v[162:165], v[194:197], v[78:81]
	v_mfma_f32_16x16x32_bf16 v[74:77], v[170:173], v[194:197], v[74:77]
	v_mfma_f32_16x16x32_bf16 v[70:73], v[162:165], v[212:215], v[70:73]
	v_mfma_f32_16x16x32_bf16 v[66:69], v[170:173], v[212:215], v[66:69]
	v_mfma_f32_16x16x32_bf16 v[106:109], v[166:169], v[182:185], v[106:109]
	v_mfma_f32_16x16x32_bf16 v[98:101], v[174:177], v[182:185], v[98:101]
	v_mfma_f32_16x16x32_bf16 v[90:93], v[166:169], v[190:193], v[90:93]
	v_mfma_f32_16x16x32_bf16 v[82:85], v[174:177], v[190:193], v[82:85]
	v_mfma_f32_16x16x32_bf16 v[78:81], v[166:169], v[198:201], v[78:81]
	v_mfma_f32_16x16x32_bf16 v[74:77], v[174:177], v[198:201], v[74:77]
	v_mfma_f32_16x16x32_bf16 v[70:73], v[166:169], v[216:219], v[70:73]
	v_mfma_f32_16x16x32_bf16 v[66:69], v[174:177], v[216:219], v[66:69]
	s_setprio 0
	s_barrier
	s_add_i32 s4, s30, s21
	v_lshl_add_u64 v[202:203], s[8:9], 0, v[130:131]
	s_mov_b32 m0, s4
	s_nop 0
	global_load_lds_dwordx4 v[202:203], off
	s_add_i32 m0, s4, 0x2000
	s_add_u32 s4, s8, 0x10000
	v_lshl_add_u64 v[220:221], s[8:9], 0, v[132:133]
	s_addc_u32 s5, s9, 0
	s_add_i32 s30, s31, s21
	global_load_lds_dwordx4 v[220:221], off
	v_lshl_add_u64 v[222:223], s[4:5], 0, v[130:131]
	s_mov_b32 m0, s30
	v_lshl_add_u64 v[224:225], s[16:17], 0, v[134:135]
	global_load_lds_dwordx4 v[222:223], off
	v_lshl_add_u64 v[222:223], s[4:5], 0, v[132:133]
	s_add_i32 m0, s30, 0x2000
	s_nop 0
	global_load_lds_dwordx4 v[222:223], off
	v_lshl_add_u64 v[222:223], s[16:17], 0, v[136:137]
	s_mov_b32 m0, s2
	s_nop 0
	global_load_lds_dwordx4 v[222:223], off
	s_mov_b32 m0, s3
	s_nop 0
	global_load_lds_dwordx4 v[224:225], off
	ds_read_b128 v[178:181], v145 offset:16384
	ds_read_b128 v[182:185], v145 offset:17408
	ds_read_b128 v[186:189], v145 offset:18432
	ds_read_b128 v[190:193], v145 offset:19456
	ds_read_b128 v[194:197], v145 offset:20480
	ds_read_b128 v[198:201], v145 offset:21504
	ds_read_b128 v[212:215], v145 offset:22528
	ds_read_b128 v[216:219], v145 offset:23552
	s_waitcnt vmcnt(8)
	s_waitcnt lgkmcnt(0)
	s_barrier
; #define PG8_STAGE(bufoff, gbase, voff) do { _Pragma("unroll") for (int _i = 0; _i < 2; ++_i) \
;         __builtin_amdgcn_global_load_lds((const unsigned*)((const char*)(gbase) + (voff)[_i]), (LAS unsigned*)(lds + (bufoff) + ldsw + _i * 8192), 16, 0, 0); } while (0)
; #define PG8_LDA(dst, b, h) do { _Pragma("unroll") for (int m = 0; m < 4; ++m) _Pragma("unroll") for (int k = 0; k < 2; ++k) dst[m][k] = *(const LAS bf16x8*)(lds + PG8_SA(b, h) + aoff + m * 2048 + k * 1024); } while (0)
; #define PG8_LDB(dst, b, h) do { _Pragma("unroll") for (int n = 0; n < 2; ++n) _Pragma("unroll") for (int k = 0; k < 2; ++k) dst[n][k] = *(const LAS bf16x8*)(lds + PG8_SB(b, h) + boff + n * 2048 + k * 1024); } while (0)
; #define PG8_MMA(ai, bj, At, Bt) do { __builtin_amdgcn_s_setprio(1); _Pragma("unroll") for (int m = 0; m < 4; ++m) _Pragma("unroll") for (int n = 0; n < 2; ++n) _Pragma("unroll") for (int k = 0; k < 2; ++k) \
;         acc[ai][bj][m][n] = mma16<I8>(Bt[n][k], At[m][k], acc[ai][bj][m][n]); __builtin_amdgcn_s_setprio(0); } while (0)
; #define PG8_WAIT_V(n) asm volatile("s_waitcnt vmcnt(" #n ")" ::: "memory")
; #define PG8_WAIT_L(n) asm volatile("s_waitcnt lgkmcnt(" #n ")" ::: "memory")
; #define PG8_BAR __builtin_amdgcn_s_barrier()
; #define PG8_SCHED __builtin_amdgcn_sched_barrier(0)
; template <class Epi, class Sched, bool I8 = false>
; __device__ __forceinline__ void gemm_phase(LAS unsigned char* lds, const Gemm g, const Sched& S, const Epi& E) {
;     ...
;             PG8_WAIT_V(8); PG8_WAIT_L(0); PG8_BAR; PG8_MMA(1, 0, At, B0); PG8_MMA(1, 1, At, B1); PG8_BAR; PG8_SCHED;
;             PG8_LDB(B0, 1, 0); PG8_LDB(B1, 1, 1); PG8_SCHED; PG8_LDA(At, 1, 0); PG8_STAGE(PG8_SA(0, 1), a2 + hstepA, voffA);
;             PG8_WAIT_V(8); PG8_WAIT_L(0); PG8_BAR; PG8_MMA(0, 0, At, B0); PG8_MMA(0, 1, At, B1); PG8_BAR; PG8_SCHED;
	s_setprio 1
	s_waitcnt lgkmcnt(0)
	v_mfma_f32_16x16x32_bf16 v[62:65], v[146:149], v[178:181], v[62:65]
	v_mfma_f32_16x16x32_bf16 v[58:61], v[154:157], v[178:181], v[58:61]
	v_mfma_f32_16x16x32_bf16 v[54:57], v[146:149], v[186:189], v[54:57]
	v_mfma_f32_16x16x32_bf16 v[50:53], v[154:157], v[186:189], v[50:53]
	v_mfma_f32_16x16x32_bf16 v[42:45], v[146:149], v[194:197], v[42:45]
	v_mfma_f32_16x16x32_bf16 v[34:37], v[154:157], v[194:197], v[34:37]
	v_mfma_f32_16x16x32_bf16 v[26:29], v[146:149], v[212:215], v[26:29]
	v_mfma_f32_16x16x32_bf16 v[18:21], v[154:157], v[212:215], v[18:21]
	v_mfma_f32_16x16x32_bf16 v[62:65], v[150:153], v[182:185], v[62:65]
	v_mfma_f32_16x16x32_bf16 v[58:61], v[158:161], v[182:185], v[58:61]
	v_mfma_f32_16x16x32_bf16 v[54:57], v[150:153], v[190:193], v[54:57]
	v_mfma_f32_16x16x32_bf16 v[50:53], v[158:161], v[190:193], v[50:53]
	v_mfma_f32_16x16x32_bf16 v[42:45], v[150:153], v[198:201], v[42:45]
	v_mfma_f32_16x16x32_bf16 v[34:37], v[158:161], v[198:201], v[34:37]
	v_mfma_f32_16x16x32_bf16 v[26:29], v[150:153], v[216:219], v[26:29]
	v_mfma_f32_16x16x32_bf16 v[18:21], v[158:161], v[216:219], v[18:21]
	s_setprio 0
	s_setprio 1
	v_mfma_f32_16x16x32_bf16 v[46:49], v[162:165], v[178:181], v[46:49]
	v_mfma_f32_16x16x32_bf16 v[38:41], v[170:173], v[178:181], v[38:41]
	v_mfma_f32_16x16x32_bf16 v[30:33], v[162:165], v[186:189], v[30:33]
	v_mfma_f32_16x16x32_bf16 v[22:25], v[170:173], v[186:189], v[22:25]
	v_mfma_f32_16x16x32_bf16 v[14:17], v[162:165], v[194:197], v[14:17]
	v_mfma_f32_16x16x32_bf16 v[10:13], v[170:173], v[194:197], v[10:13]
	v_mfma_f32_16x16x32_bf16 v[6:9], v[162:165], v[212:215], v[6:9]
	v_mfma_f32_16x16x32_bf16 v[2:5], v[170:173], v[212:215], v[2:5]
	v_mfma_f32_16x16x32_bf16 v[46:49], v[166:169], v[182:185], v[46:49]
	v_mfma_f32_16x16x32_bf16 v[38:41], v[174:177], v[182:185], v[38:41]
	v_mfma_f32_16x16x32_bf16 v[30:33], v[166:169], v[190:193], v[30:33]
	v_mfma_f32_16x16x32_bf16 v[22:25], v[174:177], v[190:193], v[22:25]
	v_mfma_f32_16x16x32_bf16 v[14:17], v[166:169], v[198:201], v[14:17]
	v_mfma_f32_16x16x32_bf16 v[10:13], v[174:177], v[198:201], v[10:13]
	v_mfma_f32_16x16x32_bf16 v[6:9], v[166:169], v[216:219], v[6:9]
	v_mfma_f32_16x16x32_bf16 v[2:5], v[174:177], v[216:219], v[2:5]
	s_setprio 0
	s_barrier
	s_add_i32 s30, 0, 0x18000
	s_add_i32 s31, 0, 0x1c000
	s_add_u32 s4, s16, 0x40000
	s_addc_u32 s5, s17, 0
	s_mov_b32 m0, s22
	v_lshl_add_u64 v[226:227], s[4:5], 0, v[136:137]
	global_load_lds_dwordx4 v[226:227], off
	v_lshl_add_u64 v[226:227], s[4:5], 0, v[134:135]
	s_mov_b32 m0, s23
	s_nop 0
	global_load_lds_dwordx4 v[226:227], off
	v_add_u32_e32 v158, s30, v144
	v_add_u32_e32 v174, s31, v144
	ds_read_b128 v[146:149], v158
	ds_read_b128 v[150:153], v158 offset:1024
	ds_read_b128 v[154:157], v158 offset:2048
	ds_read_b128 v[158:161], v158 offset:3072
	ds_read_b128 v[162:165], v174
	ds_read_b128 v[166:169], v174 offset:1024
	ds_read_b128 v[170:173], v174 offset:2048
	ds_read_b128 v[174:177], v174 offset:3072
	ds_read_b128 v[178:181], v145 offset:32768
	ds_read_b128 v[182:185], v145 offset:33792
	ds_read_b128 v[186:189], v145 offset:34816
	ds_read_b128 v[190:193], v145 offset:35840
	ds_read_b128 v[194:197], v145 offset:36864
	ds_read_b128 v[198:201], v145 offset:37888
	ds_read_b128 v[212:215], v145 offset:38912
	ds_read_b128 v[216:219], v145 offset:39936
	s_waitcnt vmcnt(8)
	s_waitcnt lgkmcnt(0)
	s_barrier
	s_setprio 1
	s_waitcnt lgkmcnt(0)
	v_mfma_f32_16x16x32_bf16 v[126:129], v[146:149], v[178:181], v[126:129]
	v_mfma_f32_16x16x32_bf16 v[122:125], v[154:157], v[178:181], v[122:125]
	v_mfma_f32_16x16x32_bf16 v[118:121], v[146:149], v[186:189], v[118:121]
	v_mfma_f32_16x16x32_bf16 v[114:117], v[154:157], v[186:189], v[114:117]
	v_mfma_f32_16x16x32_bf16 v[110:113], v[146:149], v[194:197], v[110:113]
	v_mfma_f32_16x16x32_bf16 v[102:105], v[154:157], v[194:197], v[102:105]
	v_mfma_f32_16x16x32_bf16 v[94:97], v[146:149], v[212:215], v[94:97]
	v_mfma_f32_16x16x32_bf16 v[86:89], v[154:157], v[212:215], v[86:89]
	v_mfma_f32_16x16x32_bf16 v[126:129], v[150:153], v[182:185], v[126:129]
	v_mfma_f32_16x16x32_bf16 v[122:125], v[158:161], v[182:185], v[122:125]
	v_mfma_f32_16x16x32_bf16 v[118:121], v[150:153], v[190:193], v[118:121]
	v_mfma_f32_16x16x32_bf16 v[114:117], v[158:161], v[190:193], v[114:117]
	v_mfma_f32_16x16x32_bf16 v[110:113], v[150:153], v[198:201], v[110:113]
	v_mfma_f32_16x16x32_bf16 v[102:105], v[158:161], v[198:201], v[102:105]
	v_mfma_f32_16x16x32_bf16 v[94:97], v[150:153], v[216:219], v[94:97]
	v_mfma_f32_16x16x32_bf16 v[86:89], v[158:161], v[216:219], v[86:89]
	s_setprio 0
	s_setprio 1
	v_mfma_f32_16x16x32_bf16 v[106:109], v[162:165], v[178:181], v[106:109]
	v_mfma_f32_16x16x32_bf16 v[98:101], v[170:173], v[178:181], v[98:101]
	v_mfma_f32_16x16x32_bf16 v[90:93], v[162:165], v[186:189], v[90:93]
	v_mfma_f32_16x16x32_bf16 v[82:85], v[170:173], v[186:189], v[82:85]
	v_mfma_f32_16x16x32_bf16 v[78:81], v[162:165], v[194:197], v[78:81]
	v_mfma_f32_16x16x32_bf16 v[74:77], v[170:173], v[194:197], v[74:77]
	v_mfma_f32_16x16x32_bf16 v[70:73], v[162:165], v[212:215], v[70:73]
	v_mfma_f32_16x16x32_bf16 v[66:69], v[170:173], v[212:215], v[66:69]
	v_mfma_f32_16x16x32_bf16 v[106:109], v[166:169], v[182:185], v[106:109]
	v_mfma_f32_16x16x32_bf16 v[98:101], v[174:177], v[182:185], v[98:101]
	v_mfma_f32_16x16x32_bf16 v[90:93], v[166:169], v[190:193], v[90:93]
	v_mfma_f32_16x16x32_bf16 v[82:85], v[174:177], v[190:193], v[82:85]
	v_mfma_f32_16x16x32_bf16 v[78:81], v[166:169], v[198:201], v[78:81]
	v_mfma_f32_16x16x32_bf16 v[74:77], v[174:177], v[198:201], v[74:77]
	v_mfma_f32_16x16x32_bf16 v[70:73], v[166:169], v[216:219], v[70:73]
	v_mfma_f32_16x16x32_bf16 v[66:69], v[174:177], v[216:219], v[66:69]
	s_setprio 0
	s_barrier
; #define PG8_STAGE(bufoff, gbase, voff) do { _Pragma("unroll") for (int _i = 0; _i < 2; ++_i) \
;         __builtin_amdgcn_global_load_lds((const unsigned*)((const char*)(gbase) + (voff)[_i]), (LAS unsigned*)(lds + (bufoff) + ldsw + _i * 8192), 16, 0, 0); } while (0)
; #define PG8_LDA(dst, b, h) do { _Pragma("unroll") for (int m = 0; m < 4; ++m) _Pragma("unroll") for (int k = 0; k < 2; ++k) dst[m][k] = *(const LAS bf16x8*)(lds + PG8_SA(b, h) + aoff + m * 2048 + k * 1024); } while (0)
; #define PG8_MMA(ai, bj, At, Bt) do { __builtin_amdgcn_s_setprio(1); _Pragma("unroll") for (int m = 0; m < 4; ++m) _Pragma("unroll") for (int n = 0; n < 2; ++n) _Pragma("unroll") for (int k = 0; k < 2; ++k) \
;         acc[ai][bj][m][n] = mma16<I8>(Bt[n][k], At[m][k], acc[ai][bj][m][n]); __builtin_amdgcn_s_setprio(0); } while (0)
; #define PG8_WAIT_V(n) asm volatile("s_waitcnt vmcnt(" #n ")" ::: "memory")
; #define PG8_WAIT_L(n) asm volatile("s_waitcnt lgkmcnt(" #n ")" ::: "memory")
; #define PG8_BAR __builtin_amdgcn_s_barrier()
; #define PG8_SCHED __builtin_amdgcn_sched_barrier(0)
; template <class Epi, class Sched, bool I8 = false>
; __device__ __forceinline__ void gemm_phase(LAS unsigned char* lds, const Gemm g, const Sched& S, const Epi& E) {
;     ...
;             PG8_LDA(At, 1, 1); PG8_STAGE(PG8_SB(1, 0), b3, voffB); PG8_STAGE(PG8_SB(1, 1), b3 + hstepB, voffB); PG8_STAGE(PG8_SA(1, 0), a3, voffA);
;             PG8_WAIT_V(8); PG8_WAIT_L(0); PG8_BAR; PG8_MMA(1, 0, At, B0); PG8_MMA(1, 1, At, B1); PG8_BAR; PG8_SCHED;
;     ...
;         if (PG8_ALIGN) { if (wr == 0) PG8_BAR; }
	s_add_i32 s4, s30, s21
	v_lshl_add_u64 v[202:203], v[202:203], 0, s[12:13]
	s_mov_b32 m0, s4
	s_nop 0
	global_load_lds_dwordx4 v[202:203], off
	s_add_i32 m0, s4, 0x2000
	s_add_u32 s4, s8, 0x10080
	v_lshl_add_u64 v[202:203], v[220:221], 0, s[12:13]
	s_addc_u32 s5, s9, 0
	s_add_i32 s8, s31, s21
	global_load_lds_dwordx4 v[202:203], off
	v_lshl_add_u64 v[202:203], s[4:5], 0, v[130:131]
	s_mov_b32 m0, s8
	s_nop 0
	global_load_lds_dwordx4 v[202:203], off
	v_lshl_add_u64 v[202:203], s[4:5], 0, v[132:133]
	s_add_i32 m0, s8, 0x2000
	s_nop 0
	global_load_lds_dwordx4 v[202:203], off
	v_lshl_add_u64 v[202:203], v[222:223], 0, s[12:13]
	s_mov_b32 m0, s26
	s_nop 0
	global_load_lds_dwordx4 v[202:203], off
	v_lshl_add_u64 v[202:203], v[224:225], 0, s[12:13]
	s_mov_b32 m0, s27
	s_nop 0
	global_load_lds_dwordx4 v[202:203], off
	ds_read_b128 v[178:181], v145 offset:49152
	ds_read_b128 v[182:185], v145 offset:50176
	ds_read_b128 v[186:189], v145 offset:51200
	ds_read_b128 v[190:193], v145 offset:52224
	ds_read_b128 v[194:197], v145 offset:53248
	ds_read_b128 v[198:201], v145 offset:54272
	ds_read_b128 v[212:215], v145 offset:55296
	ds_read_b128 v[216:219], v145 offset:56320
	s_waitcnt vmcnt(8)
	s_waitcnt lgkmcnt(0)
	s_barrier
	s_setprio 1
	s_waitcnt lgkmcnt(0)
	v_mfma_f32_16x16x32_bf16 v[62:65], v[146:149], v[178:181], v[62:65]
	v_mfma_f32_16x16x32_bf16 v[58:61], v[154:157], v[178:181], v[58:61]
	v_mfma_f32_16x16x32_bf16 v[54:57], v[146:149], v[186:189], v[54:57]
	v_mfma_f32_16x16x32_bf16 v[50:53], v[154:157], v[186:189], v[50:53]
	v_mfma_f32_16x16x32_bf16 v[42:45], v[146:149], v[194:197], v[42:45]
	v_mfma_f32_16x16x32_bf16 v[34:37], v[154:157], v[194:197], v[34:37]
	v_mfma_f32_16x16x32_bf16 v[26:29], v[146:149], v[212:215], v[26:29]
	v_mfma_f32_16x16x32_bf16 v[18:21], v[154:157], v[212:215], v[18:21]
	v_mfma_f32_16x16x32_bf16 v[62:65], v[150:153], v[182:185], v[62:65]
	v_mfma_f32_16x16x32_bf16 v[58:61], v[158:161], v[182:185], v[58:61]
	v_mfma_f32_16x16x32_bf16 v[54:57], v[150:153], v[190:193], v[54:57]
	v_mfma_f32_16x16x32_bf16 v[50:53], v[158:161], v[190:193], v[50:53]
	v_mfma_f32_16x16x32_bf16 v[42:45], v[150:153], v[198:201], v[42:45]
	v_mfma_f32_16x16x32_bf16 v[34:37], v[158:161], v[198:201], v[34:37]
	v_mfma_f32_16x16x32_bf16 v[26:29], v[150:153], v[216:219], v[26:29]
	v_mfma_f32_16x16x32_bf16 v[18:21], v[158:161], v[216:219], v[18:21]
	s_setprio 0
	s_setprio 1
	v_mfma_f32_16x16x32_bf16 v[46:49], v[162:165], v[178:181], v[46:49]
	v_mfma_f32_16x16x32_bf16 v[38:41], v[170:173], v[178:181], v[38:41]
	v_mfma_f32_16x16x32_bf16 v[30:33], v[162:165], v[186:189], v[30:33]
	v_mfma_f32_16x16x32_bf16 v[22:25], v[170:173], v[186:189], v[22:25]
	v_mfma_f32_16x16x32_bf16 v[14:17], v[162:165], v[194:197], v[14:17]
	v_mfma_f32_16x16x32_bf16 v[10:13], v[170:173], v[194:197], v[10:13]
	v_mfma_f32_16x16x32_bf16 v[6:9], v[162:165], v[212:215], v[6:9]
	v_mfma_f32_16x16x32_bf16 v[2:5], v[170:173], v[212:215], v[2:5]
	v_mfma_f32_16x16x32_bf16 v[46:49], v[166:169], v[182:185], v[46:49]
	v_mfma_f32_16x16x32_bf16 v[38:41], v[174:177], v[182:185], v[38:41]
	v_mfma_f32_16x16x32_bf16 v[30:33], v[166:169], v[190:193], v[30:33]
	v_mfma_f32_16x16x32_bf16 v[22:25], v[174:177], v[190:193], v[22:25]
	v_mfma_f32_16x16x32_bf16 v[14:17], v[166:169], v[198:201], v[14:17]
	v_mfma_f32_16x16x32_bf16 v[10:13], v[174:177], v[198:201], v[10:13]
	v_mfma_f32_16x16x32_bf16 v[6:9], v[166:169], v[216:219], v[6:9]
	v_mfma_f32_16x16x32_bf16 v[2:5], v[174:177], v[216:219], v[2:5]
	s_setprio 0
	s_barrier
	s_add_i32 s29, s29, 2
	s_cmp_gt_u32 s29, 13
	s_mov_b64 s[4:5], s[6:7]
	s_cbranch_scc0 .LBB0_901
	s_cmpk_lt_u32 s14, 0x100
	s_cbranch_scc0 .LBB0_904
	s_barrier

; #define PG8_STAGE(bufoff, gbase, voff) do { _Pragma("unroll") for (int _i = 0; _i < 2; ++_i) \
;         __builtin_amdgcn_global_load_lds((const unsigned*)((const char*)(gbase) + (voff)[_i]), (LAS unsigned*)(lds + (bufoff) + ldsw + _i * 8192), 16, 0, 0); } while (0)
; #define PG8_LDA(dst, b, h) do { _Pragma("unroll") for (int m = 0; m < 4; ++m) _Pragma("unroll") for (int k = 0; k < 2; ++k) dst[m][k] = *(const LAS bf16x8*)(lds + PG8_SA(b, h) + aoff + m * 2048 + k * 1024); } while (0)
; #define PG8_LDB(dst, b, h) do { _Pragma("unroll") for (int n = 0; n < 2; ++n) _Pragma("unroll") for (int k = 0; k < 2; ++k) dst[n][k] = *(const LAS bf16x8*)(lds + PG8_SB(b, h) + boff + n * 2048 + k * 1024); } while (0)
; #define PG8_MMA(ai, bj, At, Bt) do { __builtin_amdgcn_s_setprio(1); _Pragma("unroll") for (int m = 0; m < 4; ++m) _Pragma("unroll") for (int n = 0; n < 2; ++n) _Pragma("unroll") for (int k = 0; k < 2; ++k) \
;         acc[ai][bj][m][n] = mma16<I8>(Bt[n][k], At[m][k], acc[ai][bj][m][n]); __builtin_amdgcn_s_setprio(0); } while (0)
; #define PG8_WAIT_V(n) asm volatile("s_waitcnt vmcnt(" #n ")" ::: "memory")
; #define PG8_WAIT_L(n) asm volatile("s_waitcnt lgkmcnt(" #n ")" ::: "memory")
; #define PG8_BAR __builtin_amdgcn_s_barrier()
; #define PG8_SCHED __builtin_amdgcn_sched_barrier(0)
; template <class Epi, class Sched, bool I8 = false>
; __device__ __forceinline__ void gemm_phase(LAS unsigned char* lds, const Gemm g, const Sched& S, const Epi& E) {
;     ...
;         for (int t = 0; t < nt; t += 2) {
;             const bool last = (t == nt - 2);
;             const char* a1 = cA + (size_t)(t + 1) * kstep;
;             const char* a2 = last ? nA : cA + (size_t)(t + 2) * kstep; const char* b2 = last ? nB : cB + (size_t)(t + 2) * kstep;
;             const char* a3 = a2 + kstep; const char* b3 = b2 + kstep;
;             if (PG8_SP2) {
;             PG8_LDB(B0, 0, 0); PG8_LDB(B1, 0, 1); PG8_SCHED; PG8_LDA(At, 0, 0); PG8_STAGE(PG8_SA(1, 1), a1 + hstepA, voffA);
;             PG8_WAIT_V(8); PG8_WAIT_L(0); PG8_BAR; PG8_MMA(0, 0, At, B0); PG8_MMA(0, 1, At, B1); PG8_BAR; PG8_SCHED;
;             PG8_LDA(At, 0, 1); PG8_STAGE(PG8_SB(0, 0), b2, voffB); PG8_STAGE(PG8_SB(0, 1), b2 + hstepB, voffB); PG8_STAGE(PG8_SA(0, 0), a2, voffA);
;             PG8_WAIT_V(8); PG8_WAIT_L(0); PG8_BAR; PG8_MMA(1, 0, At, B0); PG8_MMA(1, 1, At, B1); PG8_BAR; PG8_SCHED;
.LBB0_1153:
	s_add_i32 s63, s58, 2
	s_add_u32 s42, s40, 0xfff80080
	s_addc_u32 s43, s41, -1
	s_add_i32 s82, 0, 0x10000
	s_cmp_eq_u32 s47, s58
	s_cselect_b32 s59, s9, s43
	s_cselect_b32 s58, s45, s42
	s_cselect_b32 s43, s17, s62
	s_cselect_b32 s42, s46, s49
	s_add_i32 s84, 0, 0x14000
	v_lshl_add_u64 v[202:203], s[40:41], 0, v[146:147]
	s_add_i32 m0, s21, 0xc000
	s_nop 0
	global_load_lds_dwordx4 v[202:203], off
	v_lshl_add_u64 v[202:203], s[40:41], 0, v[148:149]
	s_add_i32 m0, s21, 0xe000
	s_nop 0
	global_load_lds_dwordx4 v[202:203], off
	v_add_u32_e32 v130, s82, v143
	ds_read_b128 v[150:153], v130
	ds_read_b128 v[154:157], v130 offset:1024
	ds_read_b128 v[158:161], v130 offset:2048
	ds_read_b128 v[162:165], v130 offset:3072
	v_add_u32_e32 v130, s84, v143
	ds_read_b128 v[166:169], v130
	ds_read_b128 v[170:173], v130 offset:1024
	ds_read_b128 v[174:177], v130 offset:2048
	ds_read_b128 v[178:181], v130 offset:3072
	ds_read_b128 v[182:185], v145
	ds_read_b128 v[186:189], v145 offset:1024
	ds_read_b128 v[190:193], v145 offset:2048
	ds_read_b128 v[194:197], v145 offset:3072
	ds_read_b128 v[198:201], v145 offset:4096
	ds_read_b128 v[212:215], v145 offset:5120
	ds_read_b128 v[216:219], v145 offset:6144
	ds_read_b128 v[220:223], v145 offset:7168
	s_waitcnt vmcnt(8)
	s_waitcnt lgkmcnt(0)
	s_barrier
	s_setprio 1
	s_waitcnt lgkmcnt(0)
	v_mfma_f32_16x16x32_bf16 v[126:129], v[150:153], v[182:185], v[126:129]
	v_mfma_f32_16x16x32_bf16 v[122:125], v[158:161], v[182:185], v[122:125]
	v_mfma_f32_16x16x32_bf16 v[110:113], v[150:153], v[190:193], v[110:113]
	v_mfma_f32_16x16x32_bf16 v[106:109], v[158:161], v[190:193], v[106:109]
	v_mfma_f32_16x16x32_bf16 v[94:97], v[150:153], v[198:201], v[94:97]
	v_mfma_f32_16x16x32_bf16 v[90:93], v[158:161], v[198:201], v[90:93]
	v_mfma_f32_16x16x32_bf16 v[78:81], v[150:153], v[216:219], v[78:81]
	v_mfma_f32_16x16x32_bf16 v[74:77], v[158:161], v[216:219], v[74:77]
	v_mfma_f32_16x16x32_bf16 v[126:129], v[154:157], v[186:189], v[126:129]
	v_mfma_f32_16x16x32_bf16 v[122:125], v[162:165], v[186:189], v[122:125]
	v_mfma_f32_16x16x32_bf16 v[110:113], v[154:157], v[194:197], v[110:113]
	v_mfma_f32_16x16x32_bf16 v[106:109], v[162:165], v[194:197], v[106:109]
	v_mfma_f32_16x16x32_bf16 v[94:97], v[154:157], v[212:215], v[94:97]
	v_mfma_f32_16x16x32_bf16 v[90:93], v[162:165], v[212:215], v[90:93]
	v_mfma_f32_16x16x32_bf16 v[78:81], v[154:157], v[220:223], v[78:81]
	v_mfma_f32_16x16x32_bf16 v[74:77], v[162:165], v[220:223], v[74:77]
	s_setprio 0
	s_setprio 1
	v_mfma_f32_16x16x32_bf16 v[118:121], v[166:169], v[182:185], v[118:121]
	v_mfma_f32_16x16x32_bf16 v[114:117], v[174:177], v[182:185], v[114:117]
	v_mfma_f32_16x16x32_bf16 v[102:105], v[166:169], v[190:193], v[102:105]
	v_mfma_f32_16x16x32_bf16 v[98:101], v[174:177], v[190:193], v[98:101]
	v_mfma_f32_16x16x32_bf16 v[86:89], v[166:169], v[198:201], v[86:89]
	v_mfma_f32_16x16x32_bf16 v[82:85], v[174:177], v[198:201], v[82:85]
	v_mfma_f32_16x16x32_bf16 v[70:73], v[166:169], v[216:219], v[70:73]
	v_mfma_f32_16x16x32_bf16 v[66:69], v[174:177], v[216:219], v[66:69]
	v_mfma_f32_16x16x32_bf16 v[118:121], v[170:173], v[186:189], v[118:121]
	v_mfma_f32_16x16x32_bf16 v[114:117], v[178:181], v[186:189], v[114:117]
	v_mfma_f32_16x16x32_bf16 v[102:105], v[170:173], v[194:197], v[102:105]
	v_mfma_f32_16x16x32_bf16 v[98:101], v[178:181], v[194:197], v[98:101]
	v_mfma_f32_16x16x32_bf16 v[86:89], v[170:173], v[212:215], v[86:89]
	v_mfma_f32_16x16x32_bf16 v[82:85], v[178:181], v[212:215], v[82:85]
	v_mfma_f32_16x16x32_bf16 v[70:73], v[170:173], v[220:223], v[70:73]
	v_mfma_f32_16x16x32_bf16 v[66:69], v[178:181], v[220:223], v[66:69]
	s_setprio 0
	s_barrier
	s_add_i32 s82, s82, s14
	v_lshl_add_u64 v[202:203], s[42:43], 0, v[136:137]
	s_mov_b32 m0, s82
	s_nop 0
	global_load_lds_dwordx4 v[202:203], off
	s_add_i32 m0, s82, 0x2000
	s_add_u32 s82, s42, 0x20000
	v_lshl_add_u64 v[224:225], s[42:43], 0, v[132:133]
	s_addc_u32 s83, s43, 0
	s_add_i32 s84, s84, s14
	global_load_lds_dwordx4 v[224:225], off
	v_lshl_add_u64 v[226:227], s[82:83], 0, v[136:137]
	s_mov_b32 m0, s84
	v_lshl_add_u64 v[228:229], s[58:59], 0, v[134:135]
	global_load_lds_dwordx4 v[226:227], off
	v_lshl_add_u64 v[226:227], s[82:83], 0, v[132:133]
	s_add_i32 m0, s84, 0x2000
	s_nop 0
	global_load_lds_dwordx4 v[226:227], off
	v_lshl_add_u64 v[226:227], s[58:59], 0, v[138:139]
	s_mov_b32 m0, s21
	s_nop 0
	global_load_lds_dwordx4 v[226:227], off
	s_mov_b32 m0, s22
	s_nop 0
	global_load_lds_dwordx4 v[228:229], off
	ds_read_b128 v[182:185], v145 offset:16384
	ds_read_b128 v[186:189], v145 offset:17408
	ds_read_b128 v[190:193], v145 offset:18432
	ds_read_b128 v[194:197], v145 offset:19456
	ds_read_b128 v[198:201], v145 offset:20480
	ds_read_b128 v[212:215], v145 offset:21504
	ds_read_b128 v[216:219], v145 offset:22528
	ds_read_b128 v[220:223], v145 offset:23552
	s_waitcnt vmcnt(8)
	s_waitcnt lgkmcnt(0)
	s_barrier
; #define PG8_STAGE(bufoff, gbase, voff) do { _Pragma("unroll") for (int _i = 0; _i < 2; ++_i) \
;         __builtin_amdgcn_global_load_lds((const unsigned*)((const char*)(gbase) + (voff)[_i]), (LAS unsigned*)(lds + (bufoff) + ldsw + _i * 8192), 16, 0, 0); } while (0)
; #define PG8_LDA(dst, b, h) do { _Pragma("unroll") for (int m = 0; m < 4; ++m) _Pragma("unroll") for (int k = 0; k < 2; ++k) dst[m][k] = *(const LAS bf16x8*)(lds + PG8_SA(b, h) + aoff + m * 2048 + k * 1024); } while (0)
; #define PG8_LDB(dst, b, h) do { _Pragma("unroll") for (int n = 0; n < 2; ++n) _Pragma("unroll") for (int k = 0; k < 2; ++k) dst[n][k] = *(const LAS bf16x8*)(lds + PG8_SB(b, h) + boff + n * 2048 + k * 1024); } while (0)
; #define PG8_MMA(ai, bj, At, Bt) do { __builtin_amdgcn_s_setprio(1); _Pragma("unroll") for (int m = 0; m < 4; ++m) _Pragma("unroll") for (int n = 0; n < 2; ++n) _Pragma("unroll") for (int k = 0; k < 2; ++k) \
;         acc[ai][bj][m][n] = mma16<I8>(Bt[n][k], At[m][k], acc[ai][bj][m][n]); __builtin_amdgcn_s_setprio(0); } while (0)
; #define PG8_WAIT_V(n) asm volatile("s_waitcnt vmcnt(" #n ")" ::: "memory")
; #define PG8_WAIT_L(n) asm volatile("s_waitcnt lgkmcnt(" #n ")" ::: "memory")
; #define PG8_BAR __builtin_amdgcn_s_barrier()
; #define PG8_SCHED __builtin_amdgcn_sched_barrier(0)
; template <class Epi, class Sched, bool I8 = false>
; __device__ __forceinline__ void gemm_phase(LAS unsigned char* lds, const Gemm g, const Sched& S, const Epi& E) {
;     ...
;             PG8_WAIT_V(8); PG8_WAIT_L(0); PG8_BAR; PG8_MMA(1, 0, At, B0); PG8_MMA(1, 1, At, B1); PG8_BAR; PG8_SCHED;
;             PG8_LDB(B0, 1, 0); PG8_LDB(B1, 1, 1); PG8_SCHED; PG8_LDA(At, 1, 0); PG8_STAGE(PG8_SA(0, 1), a2 + hstepA, voffA);
;             PG8_WAIT_V(8); PG8_WAIT_L(0); PG8_BAR; PG8_MMA(0, 0, At, B0); PG8_MMA(0, 1, At, B1); PG8_BAR; PG8_SCHED;
	s_setprio 1
	s_waitcnt lgkmcnt(0)
	v_mfma_f32_16x16x32_bf16 v[62:65], v[150:153], v[182:185], v[62:65]
	v_mfma_f32_16x16x32_bf16 v[58:61], v[158:161], v[182:185], v[58:61]
	v_mfma_f32_16x16x32_bf16 v[46:49], v[150:153], v[190:193], v[46:49]
	v_mfma_f32_16x16x32_bf16 v[42:45], v[158:161], v[190:193], v[42:45]
	v_mfma_f32_16x16x32_bf16 v[30:33], v[150:153], v[198:201], v[30:33]
	v_mfma_f32_16x16x32_bf16 v[26:29], v[158:161], v[198:201], v[26:29]
	v_mfma_f32_16x16x32_bf16 v[14:17], v[150:153], v[216:219], v[14:17]
	v_mfma_f32_16x16x32_bf16 v[10:13], v[158:161], v[216:219], v[10:13]
	v_mfma_f32_16x16x32_bf16 v[62:65], v[154:157], v[186:189], v[62:65]
	v_mfma_f32_16x16x32_bf16 v[58:61], v[162:165], v[186:189], v[58:61]
	v_mfma_f32_16x16x32_bf16 v[46:49], v[154:157], v[194:197], v[46:49]
	v_mfma_f32_16x16x32_bf16 v[42:45], v[162:165], v[194:197], v[42:45]
	v_mfma_f32_16x16x32_bf16 v[30:33], v[154:157], v[212:215], v[30:33]
	v_mfma_f32_16x16x32_bf16 v[26:29], v[162:165], v[212:215], v[26:29]
	v_mfma_f32_16x16x32_bf16 v[14:17], v[154:157], v[220:223], v[14:17]
	v_mfma_f32_16x16x32_bf16 v[10:13], v[162:165], v[220:223], v[10:13]
	s_setprio 0
	s_setprio 1
	v_mfma_f32_16x16x32_bf16 v[54:57], v[166:169], v[182:185], v[54:57]
	v_mfma_f32_16x16x32_bf16 v[50:53], v[174:177], v[182:185], v[50:53]
	v_mfma_f32_16x16x32_bf16 v[38:41], v[166:169], v[190:193], v[38:41]
	v_mfma_f32_16x16x32_bf16 v[34:37], v[174:177], v[190:193], v[34:37]
	v_mfma_f32_16x16x32_bf16 v[22:25], v[166:169], v[198:201], v[22:25]
	v_mfma_f32_16x16x32_bf16 v[18:21], v[174:177], v[198:201], v[18:21]
	v_mfma_f32_16x16x32_bf16 v[6:9], v[166:169], v[216:219], v[6:9]
	v_mfma_f32_16x16x32_bf16 v[2:5], v[174:177], v[216:219], v[2:5]
	v_mfma_f32_16x16x32_bf16 v[54:57], v[170:173], v[186:189], v[54:57]
	v_mfma_f32_16x16x32_bf16 v[50:53], v[178:181], v[186:189], v[50:53]
	v_mfma_f32_16x16x32_bf16 v[38:41], v[170:173], v[194:197], v[38:41]
	v_mfma_f32_16x16x32_bf16 v[34:37], v[178:181], v[194:197], v[34:37]
	v_mfma_f32_16x16x32_bf16 v[22:25], v[170:173], v[212:215], v[22:25]
	v_mfma_f32_16x16x32_bf16 v[18:21], v[178:181], v[212:215], v[18:21]
	v_mfma_f32_16x16x32_bf16 v[6:9], v[170:173], v[220:223], v[6:9]
	v_mfma_f32_16x16x32_bf16 v[2:5], v[178:181], v[220:223], v[2:5]
	s_setprio 0
	s_barrier
	s_add_i32 s82, 0, 0x18000
	s_add_i32 s83, 0, 0x1c000
	s_add_u32 s58, s58, 0x80000
	s_addc_u32 s59, s59, 0
	s_mov_b32 m0, s23
	v_lshl_add_u64 v[230:231], s[58:59], 0, v[138:139]
	global_load_lds_dwordx4 v[230:231], off
	v_lshl_add_u64 v[230:231], s[58:59], 0, v[134:135]
	s_mov_b32 m0, s24
	s_nop 0
	global_load_lds_dwordx4 v[230:231], off
	v_add_u32_e32 v130, s82, v143
	ds_read_b128 v[150:153], v130
	ds_read_b128 v[154:157], v130 offset:1024
	ds_read_b128 v[158:161], v130 offset:2048
	ds_read_b128 v[162:165], v130 offset:3072
	v_add_u32_e32 v130, s83, v143
	ds_read_b128 v[166:169], v130
	ds_read_b128 v[170:173], v130 offset:1024
	ds_read_b128 v[174:177], v130 offset:2048
	ds_read_b128 v[178:181], v130 offset:3072
	ds_read_b128 v[182:185], v145 offset:32768
	ds_read_b128 v[186:189], v145 offset:33792
	ds_read_b128 v[190:193], v145 offset:34816
	ds_read_b128 v[194:197], v145 offset:35840
	ds_read_b128 v[198:201], v145 offset:36864
	ds_read_b128 v[212:215], v145 offset:37888
	ds_read_b128 v[216:219], v145 offset:38912
	ds_read_b128 v[220:223], v145 offset:39936
	s_waitcnt vmcnt(8)
	s_waitcnt lgkmcnt(0)
	s_barrier
	s_setprio 1
	s_waitcnt lgkmcnt(0)
	v_mfma_f32_16x16x32_bf16 v[126:129], v[150:153], v[182:185], v[126:129]
	v_mfma_f32_16x16x32_bf16 v[122:125], v[158:161], v[182:185], v[122:125]
	v_mfma_f32_16x16x32_bf16 v[110:113], v[150:153], v[190:193], v[110:113]
	v_mfma_f32_16x16x32_bf16 v[106:109], v[158:161], v[190:193], v[106:109]
	v_mfma_f32_16x16x32_bf16 v[94:97], v[150:153], v[198:201], v[94:97]
	v_mfma_f32_16x16x32_bf16 v[90:93], v[158:161], v[198:201], v[90:93]
	v_mfma_f32_16x16x32_bf16 v[78:81], v[150:153], v[216:219], v[78:81]
	v_mfma_f32_16x16x32_bf16 v[74:77], v[158:161], v[216:219], v[74:77]
	v_mfma_f32_16x16x32_bf16 v[126:129], v[154:157], v[186:189], v[126:129]
	v_mfma_f32_16x16x32_bf16 v[122:125], v[162:165], v[186:189], v[122:125]
	v_mfma_f32_16x16x32_bf16 v[110:113], v[154:157], v[194:197], v[110:113]
	v_mfma_f32_16x16x32_bf16 v[106:109], v[162:165], v[194:197], v[106:109]
	v_mfma_f32_16x16x32_bf16 v[94:97], v[154:157], v[212:215], v[94:97]
	v_mfma_f32_16x16x32_bf16 v[90:93], v[162:165], v[212:215], v[90:93]
	v_mfma_f32_16x16x32_bf16 v[78:81], v[154:157], v[220:223], v[78:81]
	v_mfma_f32_16x16x32_bf16 v[74:77], v[162:165], v[220:223], v[74:77]
	s_setprio 0
	s_setprio 1
	v_mfma_f32_16x16x32_bf16 v[118:121], v[166:169], v[182:185], v[118:121]
	v_mfma_f32_16x16x32_bf16 v[114:117], v[174:177], v[182:185], v[114:117]
	v_mfma_f32_16x16x32_bf16 v[102:105], v[166:169], v[190:193], v[102:105]
	v_mfma_f32_16x16x32_bf16 v[98:101], v[174:177], v[190:193], v[98:101]
	v_mfma_f32_16x16x32_bf16 v[86:89], v[166:169], v[198:201], v[86:89]
	v_mfma_f32_16x16x32_bf16 v[82:85], v[174:177], v[198:201], v[82:85]
	v_mfma_f32_16x16x32_bf16 v[70:73], v[166:169], v[216:219], v[70:73]
	v_mfma_f32_16x16x32_bf16 v[66:69], v[174:177], v[216:219], v[66:69]
	v_mfma_f32_16x16x32_bf16 v[118:121], v[170:173], v[186:189], v[118:121]
	v_mfma_f32_16x16x32_bf16 v[114:117], v[178:181], v[186:189], v[114:117]
	v_mfma_f32_16x16x32_bf16 v[102:105], v[170:173], v[194:197], v[102:105]
	v_mfma_f32_16x16x32_bf16 v[98:101], v[178:181], v[194:197], v[98:101]
	v_mfma_f32_16x16x32_bf16 v[86:89], v[170:173], v[212:215], v[86:89]
	v_mfma_f32_16x16x32_bf16 v[82:85], v[178:181], v[212:215], v[82:85]
	v_mfma_f32_16x16x32_bf16 v[70:73], v[170:173], v[220:223], v[70:73]
	v_mfma_f32_16x16x32_bf16 v[66:69], v[178:181], v[220:223], v[66:69]
	s_setprio 0
	s_barrier
; #define PG8_STAGE(bufoff, gbase, voff) do { _Pragma("unroll") for (int _i = 0; _i < 2; ++_i) \
;         __builtin_amdgcn_global_load_lds((const unsigned*)((const char*)(gbase) + (voff)[_i]), (LAS unsigned*)(lds + (bufoff) + ldsw + _i * 8192), 16, 0, 0); } while (0)
; #define PG8_LDA(dst, b, h) do { _Pragma("unroll") for (int m = 0; m < 4; ++m) _Pragma("unroll") for (int k = 0; k < 2; ++k) dst[m][k] = *(const LAS bf16x8*)(lds + PG8_SA(b, h) + aoff + m * 2048 + k * 1024); } while (0)
; #define PG8_MMA(ai, bj, At, Bt) do { __builtin_amdgcn_s_setprio(1); _Pragma("unroll") for (int m = 0; m < 4; ++m) _Pragma("unroll") for (int n = 0; n < 2; ++n) _Pragma("unroll") for (int k = 0; k < 2; ++k) \
;         acc[ai][bj][m][n] = mma16<I8>(Bt[n][k], At[m][k], acc[ai][bj][m][n]); __builtin_amdgcn_s_setprio(0); } while (0)
; #define PG8_WAIT_V(n) asm volatile("s_waitcnt vmcnt(" #n ")" ::: "memory")
; #define PG8_WAIT_L(n) asm volatile("s_waitcnt lgkmcnt(" #n ")" ::: "memory")
; #define PG8_BAR __builtin_amdgcn_s_barrier()
; #define PG8_SCHED __builtin_amdgcn_sched_barrier(0)
; template <class Epi, class Sched, bool I8 = false>
; __device__ __forceinline__ void gemm_phase(LAS unsigned char* lds, const Gemm g, const Sched& S, const Epi& E) {
;     ...
;             PG8_LDA(At, 1, 1); PG8_STAGE(PG8_SB(1, 0), b3, voffB); PG8_STAGE(PG8_SB(1, 1), b3 + hstepB, voffB); PG8_STAGE(PG8_SA(1, 0), a3, voffA);
;             PG8_WAIT_V(8); PG8_WAIT_L(0); PG8_BAR; PG8_MMA(1, 0, At, B0); PG8_MMA(1, 1, At, B1); PG8_BAR; PG8_SCHED;
;     ...
;         if (PG8_ALIGN) { if (wr == 0) PG8_BAR; }
	s_add_i32 s58, s82, s14
	v_lshl_add_u64 v[202:203], v[202:203], 0, s[12:13]
	s_mov_b32 m0, s58
	s_nop 0
	global_load_lds_dwordx4 v[202:203], off
	s_add_i32 m0, s58, 0x2000
	s_add_u32 s42, s42, 0x20080
	v_lshl_add_u64 v[202:203], v[224:225], 0, s[12:13]
	s_addc_u32 s43, s43, 0
	s_add_i32 s58, s83, s14
	global_load_lds_dwordx4 v[202:203], off
	v_lshl_add_u64 v[202:203], s[42:43], 0, v[136:137]
	s_mov_b32 m0, s58
	s_nop 0
	global_load_lds_dwordx4 v[202:203], off
	v_lshl_add_u64 v[202:203], s[42:43], 0, v[132:133]
	s_add_i32 m0, s58, 0x2000
	s_nop 0
	global_load_lds_dwordx4 v[202:203], off
	v_lshl_add_u64 v[202:203], v[226:227], 0, s[12:13]
	s_mov_b32 m0, s30
	s_nop 0
	global_load_lds_dwordx4 v[202:203], off
	v_lshl_add_u64 v[202:203], v[228:229], 0, s[12:13]
	s_mov_b32 m0, s31
	s_nop 0
	global_load_lds_dwordx4 v[202:203], off
	ds_read_b128 v[182:185], v145 offset:49152
	ds_read_b128 v[186:189], v145 offset:50176
	ds_read_b128 v[190:193], v145 offset:51200
	ds_read_b128 v[194:197], v145 offset:52224
	ds_read_b128 v[198:201], v145 offset:53248
	ds_read_b128 v[212:215], v145 offset:54272
	ds_read_b128 v[216:219], v145 offset:55296
	ds_read_b128 v[220:223], v145 offset:56320
	s_waitcnt vmcnt(8)
	s_waitcnt lgkmcnt(0)
	s_barrier
	s_setprio 1
	s_waitcnt lgkmcnt(0)
	v_mfma_f32_16x16x32_bf16 v[62:65], v[150:153], v[182:185], v[62:65]
	v_mfma_f32_16x16x32_bf16 v[58:61], v[158:161], v[182:185], v[58:61]
	v_mfma_f32_16x16x32_bf16 v[46:49], v[150:153], v[190:193], v[46:49]
	v_mfma_f32_16x16x32_bf16 v[42:45], v[158:161], v[190:193], v[42:45]
	v_mfma_f32_16x16x32_bf16 v[30:33], v[150:153], v[198:201], v[30:33]
	v_mfma_f32_16x16x32_bf16 v[26:29], v[158:161], v[198:201], v[26:29]
	v_mfma_f32_16x16x32_bf16 v[14:17], v[150:153], v[216:219], v[14:17]
	v_mfma_f32_16x16x32_bf16 v[10:13], v[158:161], v[216:219], v[10:13]
	v_mfma_f32_16x16x32_bf16 v[62:65], v[154:157], v[186:189], v[62:65]
	v_mfma_f32_16x16x32_bf16 v[58:61], v[162:165], v[186:189], v[58:61]
	v_mfma_f32_16x16x32_bf16 v[46:49], v[154:157], v[194:197], v[46:49]
	v_mfma_f32_16x16x32_bf16 v[42:45], v[162:165], v[194:197], v[42:45]
	v_mfma_f32_16x16x32_bf16 v[30:33], v[154:157], v[212:215], v[30:33]
	v_mfma_f32_16x16x32_bf16 v[26:29], v[162:165], v[212:215], v[26:29]
	v_mfma_f32_16x16x32_bf16 v[14:17], v[154:157], v[220:223], v[14:17]
	v_mfma_f32_16x16x32_bf16 v[10:13], v[162:165], v[220:223], v[10:13]
	s_setprio 0
	s_setprio 1
	v_mfma_f32_16x16x32_bf16 v[54:57], v[166:169], v[182:185], v[54:57]
	v_mfma_f32_16x16x32_bf16 v[50:53], v[174:177], v[182:185], v[50:53]
	v_mfma_f32_16x16x32_bf16 v[38:41], v[166:169], v[190:193], v[38:41]
	v_mfma_f32_16x16x32_bf16 v[34:37], v[174:177], v[190:193], v[34:37]
	v_mfma_f32_16x16x32_bf16 v[22:25], v[166:169], v[198:201], v[22:25]
	v_mfma_f32_16x16x32_bf16 v[18:21], v[174:177], v[198:201], v[18:21]
	v_mfma_f32_16x16x32_bf16 v[6:9], v[166:169], v[216:219], v[6:9]
	v_mfma_f32_16x16x32_bf16 v[2:5], v[174:177], v[216:219], v[2:5]
	v_mfma_f32_16x16x32_bf16 v[54:57], v[170:173], v[186:189], v[54:57]
	v_mfma_f32_16x16x32_bf16 v[50:53], v[178:181], v[186:189], v[50:53]
	v_mfma_f32_16x16x32_bf16 v[38:41], v[170:173], v[194:197], v[38:41]
	v_mfma_f32_16x16x32_bf16 v[34:37], v[178:181], v[194:197], v[34:37]
	v_mfma_f32_16x16x32_bf16 v[22:25], v[170:173], v[212:215], v[22:25]
	v_mfma_f32_16x16x32_bf16 v[18:21], v[178:181], v[212:215], v[18:21]
	v_mfma_f32_16x16x32_bf16 v[6:9], v[170:173], v[220:223], v[6:9]
	v_mfma_f32_16x16x32_bf16 v[2:5], v[178:181], v[220:223], v[2:5]
	s_setprio 0
	s_barrier
	s_add_u32 s40, s40, 0x100
	s_addc_u32 s41, s41, 0
	s_add_u32 s49, s49, 0x100
	s_addc_u32 s62, s62, 0
	s_cmp_ge_u32 s63, s39
	s_mov_b32 s58, s63
	s_cbranch_scc0 .LBB0_1153
	s_and_b64 vcc, exec, s[4:5]
	s_cbranch_vccz .LBB0_1156
	s_barrier

; #define PG8_STAGE(bufoff, gbase, voff) do { _Pragma("unroll") for (int _i = 0; _i < 2; ++_i) \
;         __builtin_amdgcn_global_load_lds((const unsigned*)((const char*)(gbase) + (voff)[_i]), (LAS unsigned*)(lds + (bufoff) + ldsw + _i * 8192), 16, 0, 0); } while (0)
; #define PG8_LDA(dst, b, h) do { _Pragma("unroll") for (int m = 0; m < 4; ++m) _Pragma("unroll") for (int k = 0; k < 2; ++k) dst[m][k] = *(const LAS bf16x8*)(lds + PG8_SA(b, h) + aoff + m * 2048 + k * 1024); } while (0)
; #define PG8_LDB(dst, b, h) do { _Pragma("unroll") for (int n = 0; n < 2; ++n) _Pragma("unroll") for (int k = 0; k < 2; ++k) dst[n][k] = *(const LAS bf16x8*)(lds + PG8_SB(b, h) + boff + n * 2048 + k * 1024); } while (0)
; #define PG8_MMA(ai, bj, At, Bt) do { __builtin_amdgcn_s_setprio(1); _Pragma("unroll") for (int m = 0; m < 4; ++m) _Pragma("unroll") for (int n = 0; n < 2; ++n) _Pragma("unroll") for (int k = 0; k < 2; ++k) \
;         acc[ai][bj][m][n] = mma16<I8>(Bt[n][k], At[m][k], acc[ai][bj][m][n]); __builtin_amdgcn_s_setprio(0); } while (0)
; #define PG8_WAIT_V(n) asm volatile("s_waitcnt vmcnt(" #n ")" ::: "memory")
; #define PG8_WAIT_L(n) asm volatile("s_waitcnt lgkmcnt(" #n ")" ::: "memory")
; #define PG8_BAR __builtin_amdgcn_s_barrier()
; #define PG8_SCHED __builtin_amdgcn_sched_barrier(0)
; template <class Epi, class Sched, bool I8 = false>
; __device__ __forceinline__ void gemm_phase(LAS unsigned char* lds, const Gemm g, const Sched& S, const Epi& E) {
;     ...
;         for (int t = 0; t < nt; t += 2) {
;             const bool last = (t == nt - 2);
;             const char* a1 = cA + (size_t)(t + 1) * kstep;
;             const char* a2 = last ? nA : cA + (size_t)(t + 2) * kstep; const char* b2 = last ? nB : cB + (size_t)(t + 2) * kstep;
;             const char* a3 = a2 + kstep; const char* b3 = b2 + kstep;
;             if (PG8_SP2) {
;             PG8_LDB(B0, 0, 0); PG8_LDB(B1, 0, 1); PG8_SCHED; PG8_LDA(At, 0, 0); PG8_STAGE(PG8_SA(1, 1), a1 + hstepA, voffA);
;             PG8_WAIT_V(8); PG8_WAIT_L(0); PG8_BAR; PG8_MMA(0, 0, At, B0); PG8_MMA(0, 1, At, B1); PG8_BAR; PG8_SCHED;
;             PG8_LDA(At, 0, 1); PG8_STAGE(PG8_SB(0, 0), b2, voffB); PG8_STAGE(PG8_SB(0, 1), b2 + hstepB, voffB); PG8_STAGE(PG8_SA(0, 0), a2, voffA);
;             PG8_WAIT_V(8); PG8_WAIT_L(0); PG8_BAR; PG8_MMA(1, 0, At, B0); PG8_MMA(1, 1, At, B1); PG8_BAR; PG8_SCHED;
.LBB0_1336:
	s_add_u32 s40, s0, 0xfffc0080
	s_addc_u32 s41, s1, -1
	s_add_i32 s91, 0, 0x10000
	s_cmp_eq_u32 s90, 12
	s_cselect_b32 s43, s44, s41
	s_cselect_b32 s42, s45, s40
	s_cselect_b32 s41, s55, s83
	s_cselect_b32 s40, s57, s82
	s_add_i32 s96, 0, 0x14000
	v_lshl_add_u64 v[160:161], s[0:1], 0, v[156:157]
	s_add_i32 m0, s24, 0xc000
	s_nop 0
	global_load_lds_dwordx4 v[160:161], off
	v_lshl_add_u64 v[160:161], s[0:1], 0, v[158:159]
	s_add_i32 m0, s24, 0xe000
	s_nop 0
	global_load_lds_dwordx4 v[160:161], off
	v_add_u32_e32 v130, s91, v164
	ds_read_b128 v[114:117], v130
	ds_read_b128 v[118:121], v130 offset:1024
	ds_read_b128 v[126:129], v130 offset:2048
	ds_read_b128 v[136:139], v130 offset:3072
	v_add_u32_e32 v130, s96, v164
	ds_read_b128 v[166:169], v130
	ds_read_b128 v[170:173], v130 offset:1024
	ds_read_b128 v[174:177], v130 offset:2048
	ds_read_b128 v[178:181], v130 offset:3072
	ds_read_b128 v[182:185], v165
	ds_read_b128 v[186:189], v165 offset:1024
	ds_read_b128 v[190:193], v165 offset:2048
	ds_read_b128 v[194:197], v165 offset:3072
	ds_read_b128 v[198:201], v165 offset:4096
	ds_read_b128 v[212:215], v165 offset:5120
	ds_read_b128 v[216:219], v165 offset:6144
	ds_read_b128 v[220:223], v165 offset:7168
	s_waitcnt vmcnt(8)
	s_waitcnt lgkmcnt(0)
	s_barrier
	s_setprio 1
	s_waitcnt lgkmcnt(0)
	v_mfma_i32_16x16x64_i8 v[144:147], v[114:117], v[182:185], v[144:147]
	v_mfma_i32_16x16x64_i8 v[140:143], v[126:129], v[182:185], v[140:143]
	v_mfma_i32_16x16x64_i8 v[110:113], v[114:117], v[190:193], v[110:113]
	v_mfma_i32_16x16x64_i8 v[106:109], v[126:129], v[190:193], v[106:109]
	v_mfma_i32_16x16x64_i8 v[94:97], v[114:117], v[198:201], v[94:97]
	v_mfma_i32_16x16x64_i8 v[90:93], v[126:129], v[198:201], v[90:93]
	v_mfma_i32_16x16x64_i8 v[78:81], v[114:117], v[216:219], v[78:81]
	v_mfma_i32_16x16x64_i8 v[74:77], v[126:129], v[216:219], v[74:77]
	v_mfma_i32_16x16x64_i8 v[144:147], v[118:121], v[186:189], v[144:147]
	v_mfma_i32_16x16x64_i8 v[140:143], v[136:139], v[186:189], v[140:143]
	v_mfma_i32_16x16x64_i8 v[110:113], v[118:121], v[194:197], v[110:113]
	v_mfma_i32_16x16x64_i8 v[106:109], v[136:139], v[194:197], v[106:109]
	v_mfma_i32_16x16x64_i8 v[94:97], v[118:121], v[212:215], v[94:97]
	v_mfma_i32_16x16x64_i8 v[90:93], v[136:139], v[212:215], v[90:93]
	v_mfma_i32_16x16x64_i8 v[78:81], v[118:121], v[220:223], v[78:81]
	v_mfma_i32_16x16x64_i8 v[74:77], v[136:139], v[220:223], v[74:77]
	s_setprio 0
	s_setprio 1
	v_mfma_i32_16x16x64_i8 v[132:135], v[166:169], v[182:185], v[132:135]
	v_mfma_i32_16x16x64_i8 v[122:125], v[174:177], v[182:185], v[122:125]
	v_mfma_i32_16x16x64_i8 v[102:105], v[166:169], v[190:193], v[102:105]
	v_mfma_i32_16x16x64_i8 v[98:101], v[174:177], v[190:193], v[98:101]
	v_mfma_i32_16x16x64_i8 v[86:89], v[166:169], v[198:201], v[86:89]
	v_mfma_i32_16x16x64_i8 v[82:85], v[174:177], v[198:201], v[82:85]
	v_mfma_i32_16x16x64_i8 v[70:73], v[166:169], v[216:219], v[70:73]
	v_mfma_i32_16x16x64_i8 v[66:69], v[174:177], v[216:219], v[66:69]
	v_mfma_i32_16x16x64_i8 v[132:135], v[170:173], v[186:189], v[132:135]
	v_mfma_i32_16x16x64_i8 v[122:125], v[178:181], v[186:189], v[122:125]
	v_mfma_i32_16x16x64_i8 v[102:105], v[170:173], v[194:197], v[102:105]
	v_mfma_i32_16x16x64_i8 v[98:101], v[178:181], v[194:197], v[98:101]
	v_mfma_i32_16x16x64_i8 v[86:89], v[170:173], v[212:215], v[86:89]
	v_mfma_i32_16x16x64_i8 v[82:85], v[178:181], v[212:215], v[82:85]
	v_mfma_i32_16x16x64_i8 v[70:73], v[170:173], v[220:223], v[70:73]
	v_mfma_i32_16x16x64_i8 v[66:69], v[178:181], v[220:223], v[66:69]
	s_setprio 0
	s_barrier
	s_add_i32 s91, s91, s21
	v_lshl_add_u64 v[160:161], s[40:41], 0, v[152:153]
	s_mov_b32 m0, s91
	s_nop 0
	global_load_lds_dwordx4 v[160:161], off
	s_add_i32 m0, s91, 0x2000
	s_add_u32 s94, s40, 0x10000
	v_lshl_add_u64 v[202:203], s[40:41], 0, v[148:149]
	s_addc_u32 s95, s41, 0
	s_add_i32 s91, s96, s21
	global_load_lds_dwordx4 v[202:203], off
	v_lshl_add_u64 v[224:225], s[94:95], 0, v[152:153]
	s_mov_b32 m0, s91
	v_lshl_add_u64 v[226:227], s[42:43], 0, v[150:151]
	global_load_lds_dwordx4 v[224:225], off
	v_lshl_add_u64 v[224:225], s[94:95], 0, v[148:149]
	s_add_i32 m0, s91, 0x2000
	s_nop 0
	global_load_lds_dwordx4 v[224:225], off
	v_lshl_add_u64 v[224:225], s[42:43], 0, v[154:155]
	s_mov_b32 m0, s24
	s_nop 0
	global_load_lds_dwordx4 v[224:225], off
	s_mov_b32 m0, s25
	s_nop 0
	global_load_lds_dwordx4 v[226:227], off
	ds_read_b128 v[182:185], v165 offset:16384
	ds_read_b128 v[186:189], v165 offset:17408
	ds_read_b128 v[190:193], v165 offset:18432
	ds_read_b128 v[194:197], v165 offset:19456
	ds_read_b128 v[198:201], v165 offset:20480
	ds_read_b128 v[212:215], v165 offset:21504
	ds_read_b128 v[216:219], v165 offset:22528
	ds_read_b128 v[220:223], v165 offset:23552
	s_waitcnt vmcnt(8)
	s_waitcnt lgkmcnt(0)
	s_barrier
; #define PG8_STAGE(bufoff, gbase, voff) do { _Pragma("unroll") for (int _i = 0; _i < 2; ++_i) \
;         __builtin_amdgcn_global_load_lds((const unsigned*)((const char*)(gbase) + (voff)[_i]), (LAS unsigned*)(lds + (bufoff) + ldsw + _i * 8192), 16, 0, 0); } while (0)
; #define PG8_LDA(dst, b, h) do { _Pragma("unroll") for (int m = 0; m < 4; ++m) _Pragma("unroll") for (int k = 0; k < 2; ++k) dst[m][k] = *(const LAS bf16x8*)(lds + PG8_SA(b, h) + aoff + m * 2048 + k * 1024); } while (0)
; #define PG8_LDB(dst, b, h) do { _Pragma("unroll") for (int n = 0; n < 2; ++n) _Pragma("unroll") for (int k = 0; k < 2; ++k) dst[n][k] = *(const LAS bf16x8*)(lds + PG8_SB(b, h) + boff + n * 2048 + k * 1024); } while (0)
; #define PG8_MMA(ai, bj, At, Bt) do { __builtin_amdgcn_s_setprio(1); _Pragma("unroll") for (int m = 0; m < 4; ++m) _Pragma("unroll") for (int n = 0; n < 2; ++n) _Pragma("unroll") for (int k = 0; k < 2; ++k) \
;         acc[ai][bj][m][n] = mma16<I8>(Bt[n][k], At[m][k], acc[ai][bj][m][n]); __builtin_amdgcn_s_setprio(0); } while (0)
; #define PG8_WAIT_V(n) asm volatile("s_waitcnt vmcnt(" #n ")" ::: "memory")
; #define PG8_WAIT_L(n) asm volatile("s_waitcnt lgkmcnt(" #n ")" ::: "memory")
; #define PG8_BAR __builtin_amdgcn_s_barrier()
; #define PG8_SCHED __builtin_amdgcn_sched_barrier(0)
; template <class Epi, class Sched, bool I8 = false>
; __device__ __forceinline__ void gemm_phase(LAS unsigned char* lds, const Gemm g, const Sched& S, const Epi& E) {
;     ...
;             PG8_WAIT_V(8); PG8_WAIT_L(0); PG8_BAR; PG8_MMA(1, 0, At, B0); PG8_MMA(1, 1, At, B1); PG8_BAR; PG8_SCHED;
;             PG8_LDB(B0, 1, 0); PG8_LDB(B1, 1, 1); PG8_SCHED; PG8_LDA(At, 1, 0); PG8_STAGE(PG8_SA(0, 1), a2 + hstepA, voffA);
;             PG8_WAIT_V(8); PG8_WAIT_L(0); PG8_BAR; PG8_MMA(0, 0, At, B0); PG8_MMA(0, 1, At, B1); PG8_BAR; PG8_SCHED;
	s_setprio 1
	s_waitcnt lgkmcnt(0)
	v_mfma_i32_16x16x64_i8 v[62:65], v[114:117], v[182:185], v[62:65]
	v_mfma_i32_16x16x64_i8 v[58:61], v[126:129], v[182:185], v[58:61]
	v_mfma_i32_16x16x64_i8 v[46:49], v[114:117], v[190:193], v[46:49]
	v_mfma_i32_16x16x64_i8 v[42:45], v[126:129], v[190:193], v[42:45]
	v_mfma_i32_16x16x64_i8 v[30:33], v[114:117], v[198:201], v[30:33]
	v_mfma_i32_16x16x64_i8 v[26:29], v[126:129], v[198:201], v[26:29]
	v_mfma_i32_16x16x64_i8 v[14:17], v[114:117], v[216:219], v[14:17]
	v_mfma_i32_16x16x64_i8 v[10:13], v[126:129], v[216:219], v[10:13]
	v_mfma_i32_16x16x64_i8 v[62:65], v[118:121], v[186:189], v[62:65]
	v_mfma_i32_16x16x64_i8 v[58:61], v[136:139], v[186:189], v[58:61]
	v_mfma_i32_16x16x64_i8 v[46:49], v[118:121], v[194:197], v[46:49]
	v_mfma_i32_16x16x64_i8 v[42:45], v[136:139], v[194:197], v[42:45]
	v_mfma_i32_16x16x64_i8 v[30:33], v[118:121], v[212:215], v[30:33]
	v_mfma_i32_16x16x64_i8 v[26:29], v[136:139], v[212:215], v[26:29]
	v_mfma_i32_16x16x64_i8 v[14:17], v[118:121], v[220:223], v[14:17]
	v_mfma_i32_16x16x64_i8 v[10:13], v[136:139], v[220:223], v[10:13]
	s_setprio 0
	s_setprio 1
	v_mfma_i32_16x16x64_i8 v[54:57], v[166:169], v[182:185], v[54:57]
	v_mfma_i32_16x16x64_i8 v[50:53], v[174:177], v[182:185], v[50:53]
	v_mfma_i32_16x16x64_i8 v[38:41], v[166:169], v[190:193], v[38:41]
	v_mfma_i32_16x16x64_i8 v[34:37], v[174:177], v[190:193], v[34:37]
	v_mfma_i32_16x16x64_i8 v[22:25], v[166:169], v[198:201], v[22:25]
	v_mfma_i32_16x16x64_i8 v[18:21], v[174:177], v[198:201], v[18:21]
	v_mfma_i32_16x16x64_i8 v[6:9], v[166:169], v[216:219], v[6:9]
	v_mfma_i32_16x16x64_i8 v[2:5], v[174:177], v[216:219], v[2:5]
	v_mfma_i32_16x16x64_i8 v[54:57], v[170:173], v[186:189], v[54:57]
	v_mfma_i32_16x16x64_i8 v[50:53], v[178:181], v[186:189], v[50:53]
	v_mfma_i32_16x16x64_i8 v[38:41], v[170:173], v[194:197], v[38:41]
	v_mfma_i32_16x16x64_i8 v[34:37], v[178:181], v[194:197], v[34:37]
	v_mfma_i32_16x16x64_i8 v[22:25], v[170:173], v[212:215], v[22:25]
	v_mfma_i32_16x16x64_i8 v[18:21], v[178:181], v[212:215], v[18:21]
	v_mfma_i32_16x16x64_i8 v[6:9], v[170:173], v[220:223], v[6:9]
	v_mfma_i32_16x16x64_i8 v[2:5], v[178:181], v[220:223], v[2:5]
	s_setprio 0
	s_barrier
	s_add_i32 s91, 0, 0x18000
	s_add_i32 s94, 0, 0x1c000
	s_add_u32 s42, s42, 0x40000
	s_addc_u32 s43, s43, 0
	s_mov_b32 m0, s29
	v_lshl_add_u64 v[228:229], s[42:43], 0, v[154:155]
	global_load_lds_dwordx4 v[228:229], off
	v_lshl_add_u64 v[228:229], s[42:43], 0, v[150:151]
	s_mov_b32 m0, s30
	s_nop 0
	global_load_lds_dwordx4 v[228:229], off
	v_add_u32_e32 v130, s91, v164
	ds_read_b128 v[114:117], v130
	ds_read_b128 v[118:121], v130 offset:1024
	ds_read_b128 v[126:129], v130 offset:2048
	ds_read_b128 v[136:139], v130 offset:3072
	v_add_u32_e32 v130, s94, v164
	ds_read_b128 v[166:169], v130
	ds_read_b128 v[170:173], v130 offset:1024
	ds_read_b128 v[174:177], v130 offset:2048
	ds_read_b128 v[178:181], v130 offset:3072
	ds_read_b128 v[182:185], v165 offset:32768
	ds_read_b128 v[186:189], v165 offset:33792
	ds_read_b128 v[190:193], v165 offset:34816
	ds_read_b128 v[194:197], v165 offset:35840
	ds_read_b128 v[198:201], v165 offset:36864
	ds_read_b128 v[212:215], v165 offset:37888
	ds_read_b128 v[216:219], v165 offset:38912
	ds_read_b128 v[220:223], v165 offset:39936
	s_waitcnt vmcnt(8)
	s_waitcnt lgkmcnt(0)
	s_barrier
	s_setprio 1
	s_waitcnt lgkmcnt(0)
	v_mfma_i32_16x16x64_i8 v[144:147], v[114:117], v[182:185], v[144:147]
	v_mfma_i32_16x16x64_i8 v[140:143], v[126:129], v[182:185], v[140:143]
	v_mfma_i32_16x16x64_i8 v[110:113], v[114:117], v[190:193], v[110:113]
	v_mfma_i32_16x16x64_i8 v[106:109], v[126:129], v[190:193], v[106:109]
	v_mfma_i32_16x16x64_i8 v[94:97], v[114:117], v[198:201], v[94:97]
	v_mfma_i32_16x16x64_i8 v[90:93], v[126:129], v[198:201], v[90:93]
	v_mfma_i32_16x16x64_i8 v[78:81], v[114:117], v[216:219], v[78:81]
	v_mfma_i32_16x16x64_i8 v[74:77], v[126:129], v[216:219], v[74:77]
	v_mfma_i32_16x16x64_i8 v[144:147], v[118:121], v[186:189], v[144:147]
	v_mfma_i32_16x16x64_i8 v[140:143], v[136:139], v[186:189], v[140:143]
	v_mfma_i32_16x16x64_i8 v[110:113], v[118:121], v[194:197], v[110:113]
	v_mfma_i32_16x16x64_i8 v[106:109], v[136:139], v[194:197], v[106:109]
	v_mfma_i32_16x16x64_i8 v[94:97], v[118:121], v[212:215], v[94:97]
	v_mfma_i32_16x16x64_i8 v[90:93], v[136:139], v[212:215], v[90:93]
	v_mfma_i32_16x16x64_i8 v[78:81], v[118:121], v[220:223], v[78:81]
	v_mfma_i32_16x16x64_i8 v[74:77], v[136:139], v[220:223], v[74:77]
	s_setprio 0
	s_setprio 1
	v_mfma_i32_16x16x64_i8 v[132:135], v[166:169], v[182:185], v[132:135]
	v_mfma_i32_16x16x64_i8 v[122:125], v[174:177], v[182:185], v[122:125]
	v_mfma_i32_16x16x64_i8 v[102:105], v[166:169], v[190:193], v[102:105]
	v_mfma_i32_16x16x64_i8 v[98:101], v[174:177], v[190:193], v[98:101]
	v_mfma_i32_16x16x64_i8 v[86:89], v[166:169], v[198:201], v[86:89]
	v_mfma_i32_16x16x64_i8 v[82:85], v[174:177], v[198:201], v[82:85]
	v_mfma_i32_16x16x64_i8 v[70:73], v[166:169], v[216:219], v[70:73]
	v_mfma_i32_16x16x64_i8 v[66:69], v[174:177], v[216:219], v[66:69]
	v_mfma_i32_16x16x64_i8 v[132:135], v[170:173], v[186:189], v[132:135]
	v_mfma_i32_16x16x64_i8 v[122:125], v[178:181], v[186:189], v[122:125]
	v_mfma_i32_16x16x64_i8 v[102:105], v[170:173], v[194:197], v[102:105]
	v_mfma_i32_16x16x64_i8 v[98:101], v[178:181], v[194:197], v[98:101]
	v_mfma_i32_16x16x64_i8 v[86:89], v[170:173], v[212:215], v[86:89]
	v_mfma_i32_16x16x64_i8 v[82:85], v[178:181], v[212:215], v[82:85]
	v_mfma_i32_16x16x64_i8 v[70:73], v[170:173], v[220:223], v[70:73]
	v_mfma_i32_16x16x64_i8 v[66:69], v[178:181], v[220:223], v[66:69]
	s_setprio 0
	s_barrier
; #define PG8_STAGE(bufoff, gbase, voff) do { _Pragma("unroll") for (int _i = 0; _i < 2; ++_i) \
;         __builtin_amdgcn_global_load_lds((const unsigned*)((const char*)(gbase) + (voff)[_i]), (LAS unsigned*)(lds + (bufoff) + ldsw + _i * 8192), 16, 0, 0); } while (0)
; #define PG8_LDA(dst, b, h) do { _Pragma("unroll") for (int m = 0; m < 4; ++m) _Pragma("unroll") for (int k = 0; k < 2; ++k) dst[m][k] = *(const LAS bf16x8*)(lds + PG8_SA(b, h) + aoff + m * 2048 + k * 1024); } while (0)
; #define PG8_MMA(ai, bj, At, Bt) do { __builtin_amdgcn_s_setprio(1); _Pragma("unroll") for (int m = 0; m < 4; ++m) _Pragma("unroll") for (int n = 0; n < 2; ++n) _Pragma("unroll") for (int k = 0; k < 2; ++k) \
;         acc[ai][bj][m][n] = mma16<I8>(Bt[n][k], At[m][k], acc[ai][bj][m][n]); __builtin_amdgcn_s_setprio(0); } while (0)
; #define PG8_WAIT_V(n) asm volatile("s_waitcnt vmcnt(" #n ")" ::: "memory")
; #define PG8_WAIT_L(n) asm volatile("s_waitcnt lgkmcnt(" #n ")" ::: "memory")
; #define PG8_BAR __builtin_amdgcn_s_barrier()
; #define PG8_SCHED __builtin_amdgcn_sched_barrier(0)
; template <class Epi, class Sched, bool I8 = false>
; __device__ __forceinline__ void gemm_phase(LAS unsigned char* lds, const Gemm g, const Sched& S, const Epi& E) {
;     ...
;             PG8_LDA(At, 1, 1); PG8_STAGE(PG8_SB(1, 0), b3, voffB); PG8_STAGE(PG8_SB(1, 1), b3 + hstepB, voffB); PG8_STAGE(PG8_SA(1, 0), a3, voffA);
;             PG8_WAIT_V(8); PG8_WAIT_L(0); PG8_BAR; PG8_MMA(1, 0, At, B0); PG8_MMA(1, 1, At, B1); PG8_BAR; PG8_SCHED;
;     ...
;         if (PG8_ALIGN) { if (wr == 0) PG8_BAR; }
	s_add_i32 s42, s91, s21
	v_lshl_add_u64 v[160:161], v[160:161], 0, s[12:13]
	s_mov_b32 m0, s42
	s_nop 0
	global_load_lds_dwordx4 v[160:161], off
	s_add_i32 m0, s42, 0x2000
	s_add_u32 s40, s40, 0x10080
	v_lshl_add_u64 v[160:161], v[202:203], 0, s[12:13]
	s_addc_u32 s41, s41, 0
	s_add_i32 s42, s94, s21
	global_load_lds_dwordx4 v[160:161], off
	v_lshl_add_u64 v[160:161], s[40:41], 0, v[152:153]
	s_mov_b32 m0, s42
	s_nop 0
	global_load_lds_dwordx4 v[160:161], off
	v_lshl_add_u64 v[160:161], s[40:41], 0, v[148:149]
	s_add_i32 m0, s42, 0x2000
	s_nop 0
	global_load_lds_dwordx4 v[160:161], off
	v_lshl_add_u64 v[160:161], v[224:225], 0, s[12:13]
	s_mov_b32 m0, s49
	s_nop 0
	global_load_lds_dwordx4 v[160:161], off
	v_lshl_add_u64 v[160:161], v[226:227], 0, s[12:13]
	s_mov_b32 m0, s80
	s_nop 0
	global_load_lds_dwordx4 v[160:161], off
	ds_read_b128 v[182:185], v165 offset:49152
	ds_read_b128 v[186:189], v165 offset:50176
	ds_read_b128 v[190:193], v165 offset:51200
	ds_read_b128 v[194:197], v165 offset:52224
	ds_read_b128 v[198:201], v165 offset:53248
	ds_read_b128 v[212:215], v165 offset:54272
	ds_read_b128 v[216:219], v165 offset:55296
	ds_read_b128 v[220:223], v165 offset:56320
	s_waitcnt vmcnt(8)
	s_waitcnt lgkmcnt(0)
	s_barrier
	s_setprio 1
	s_waitcnt lgkmcnt(0)
	v_mfma_i32_16x16x64_i8 v[62:65], v[114:117], v[182:185], v[62:65]
	v_mfma_i32_16x16x64_i8 v[58:61], v[126:129], v[182:185], v[58:61]
	v_mfma_i32_16x16x64_i8 v[46:49], v[114:117], v[190:193], v[46:49]
	v_mfma_i32_16x16x64_i8 v[42:45], v[126:129], v[190:193], v[42:45]
	v_mfma_i32_16x16x64_i8 v[30:33], v[114:117], v[198:201], v[30:33]
	v_mfma_i32_16x16x64_i8 v[26:29], v[126:129], v[198:201], v[26:29]
	v_mfma_i32_16x16x64_i8 v[14:17], v[114:117], v[216:219], v[14:17]
	v_mfma_i32_16x16x64_i8 v[10:13], v[126:129], v[216:219], v[10:13]
	v_mfma_i32_16x16x64_i8 v[62:65], v[118:121], v[186:189], v[62:65]
	v_mfma_i32_16x16x64_i8 v[58:61], v[136:139], v[186:189], v[58:61]
	v_mfma_i32_16x16x64_i8 v[46:49], v[118:121], v[194:197], v[46:49]
	v_mfma_i32_16x16x64_i8 v[42:45], v[136:139], v[194:197], v[42:45]
	v_mfma_i32_16x16x64_i8 v[30:33], v[118:121], v[212:215], v[30:33]
	v_mfma_i32_16x16x64_i8 v[26:29], v[136:139], v[212:215], v[26:29]
	v_mfma_i32_16x16x64_i8 v[14:17], v[118:121], v[220:223], v[14:17]
	v_mfma_i32_16x16x64_i8 v[10:13], v[136:139], v[220:223], v[10:13]
	s_setprio 0
	s_setprio 1
	v_mfma_i32_16x16x64_i8 v[54:57], v[166:169], v[182:185], v[54:57]
	v_mfma_i32_16x16x64_i8 v[50:53], v[174:177], v[182:185], v[50:53]
	v_mfma_i32_16x16x64_i8 v[38:41], v[166:169], v[190:193], v[38:41]
	v_mfma_i32_16x16x64_i8 v[34:37], v[174:177], v[190:193], v[34:37]
	v_mfma_i32_16x16x64_i8 v[22:25], v[166:169], v[198:201], v[22:25]
	v_mfma_i32_16x16x64_i8 v[18:21], v[174:177], v[198:201], v[18:21]
	v_mfma_i32_16x16x64_i8 v[6:9], v[166:169], v[216:219], v[6:9]
	v_mfma_i32_16x16x64_i8 v[2:5], v[174:177], v[216:219], v[2:5]
	v_mfma_i32_16x16x64_i8 v[54:57], v[170:173], v[186:189], v[54:57]
	v_mfma_i32_16x16x64_i8 v[50:53], v[178:181], v[186:189], v[50:53]
	v_mfma_i32_16x16x64_i8 v[38:41], v[170:173], v[194:197], v[38:41]
	v_mfma_i32_16x16x64_i8 v[34:37], v[178:181], v[194:197], v[34:37]
	v_mfma_i32_16x16x64_i8 v[22:25], v[170:173], v[212:215], v[22:25]
	v_mfma_i32_16x16x64_i8 v[18:21], v[178:181], v[212:215], v[18:21]
	v_mfma_i32_16x16x64_i8 v[6:9], v[170:173], v[220:223], v[6:9]
	v_mfma_i32_16x16x64_i8 v[2:5], v[178:181], v[220:223], v[2:5]
	s_setprio 0
	s_barrier
	s_add_i32 s90, s90, 2
	s_add_u32 s0, s0, 0x100
	s_addc_u32 s1, s1, 0
	s_add_u32 s82, s82, 0x100
	s_addc_u32 s83, s83, 0
	s_cmp_gt_u32 s90, 13
	s_cbranch_scc0 .LBB0_1336
	s_and_b64 vcc, exec, s[6:7]
	s_cbranch_vccz .LBB0_1339
	s_barrier

; #define PG8_STAGE(bufoff, gbase, voff) do { _Pragma("unroll") for (int _i = 0; _i < 2; ++_i) \
;         __builtin_amdgcn_global_load_lds((const unsigned*)((const char*)(gbase) + (voff)[_i]), (LAS unsigned*)(lds + (bufoff) + ldsw + _i * 8192), 16, 0, 0); } while (0)
; #define PG8_LDA(dst, b, h) do { _Pragma("unroll") for (int m = 0; m < 4; ++m) _Pragma("unroll") for (int k = 0; k < 2; ++k) dst[m][k] = *(const LAS bf16x8*)(lds + PG8_SA(b, h) + aoff + m * 2048 + k * 1024); } while (0)
; #define PG8_LDB(dst, b, h) do { _Pragma("unroll") for (int n = 0; n < 2; ++n) _Pragma("unroll") for (int k = 0; k < 2; ++k) dst[n][k] = *(const LAS bf16x8*)(lds + PG8_SB(b, h) + boff + n * 2048 + k * 1024); } while (0)
; #define PG8_MMA(ai, bj, At, Bt) do { __builtin_amdgcn_s_setprio(1); _Pragma("unroll") for (int m = 0; m < 4; ++m) _Pragma("unroll") for (int n = 0; n < 2; ++n) _Pragma("unroll") for (int k = 0; k < 2; ++k) \
;         acc[ai][bj][m][n] = mma16<I8>(Bt[n][k], At[m][k], acc[ai][bj][m][n]); __builtin_amdgcn_s_setprio(0); } while (0)
; #define PG8_WAIT_V(n) asm volatile("s_waitcnt vmcnt(" #n ")" ::: "memory")
; #define PG8_WAIT_L(n) asm volatile("s_waitcnt lgkmcnt(" #n ")" ::: "memory")
; #define PG8_BAR __builtin_amdgcn_s_barrier()
; #define PG8_SCHED __builtin_amdgcn_sched_barrier(0)
; template <class Epi, class Sched, bool I8 = false>
; __device__ __forceinline__ void gemm_phase(LAS unsigned char* lds, const Gemm g, const Sched& S, const Epi& E) {
;     ...
;         for (int t = 0; t < nt; t += 2) {
;             const bool last = (t == nt - 2);
;             const char* a1 = cA + (size_t)(t + 1) * kstep;
;             const char* a2 = last ? nA : cA + (size_t)(t + 2) * kstep; const char* b2 = last ? nB : cB + (size_t)(t + 2) * kstep;
;             const char* a3 = a2 + kstep; const char* b3 = b2 + kstep;
;             if (PG8_SP2) {
;             PG8_LDB(B0, 0, 0); PG8_LDB(B1, 0, 1); PG8_SCHED; PG8_LDA(At, 0, 0); PG8_STAGE(PG8_SA(1, 1), a1 + hstepA, voffA);
;             PG8_WAIT_V(8); PG8_WAIT_L(0); PG8_BAR; PG8_MMA(0, 0, At, B0); PG8_MMA(0, 1, At, B1); PG8_BAR; PG8_SCHED;
;             PG8_LDA(At, 0, 1); PG8_STAGE(PG8_SB(0, 0), b2, voffB); PG8_STAGE(PG8_SB(0, 1), b2 + hstepB, voffB); PG8_STAGE(PG8_SA(0, 0), a2, voffA);
;             PG8_WAIT_V(8); PG8_WAIT_L(0); PG8_BAR; PG8_MMA(1, 0, At, B0); PG8_MMA(1, 1, At, B1); PG8_BAR; PG8_SCHED;
.LBB0_1574:
	s_add_i32 s80, s42, 2
	s_add_u32 s40, s0, 0xfff00080
	s_addc_u32 s41, s1, -1
	s_add_i32 s82, 0, 0x10000
	s_cmp_eq_u32 s56, s42
	s_cselect_b32 s43, s23, s41
	s_cselect_b32 s42, s44, s40
	s_cselect_b32 s41, s45, s63
	s_cselect_b32 s40, s46, s57
	s_add_i32 s91, 0, 0x14000
	v_lshl_add_u64 v[202:203], s[0:1], 0, v[178:179]
	s_add_i32 m0, s34, 0xc000
	s_nop 0
	global_load_lds_dwordx4 v[202:203], off
	v_lshl_add_u64 v[202:203], s[0:1], 0, v[180:181]
	s_add_i32 m0, s34, 0xe000
	s_nop 0
	global_load_lds_dwordx4 v[202:203], off
	v_add_u32_e32 v62, s82, v175
	v_add_u32_e32 v78, s91, v175
	ds_read_b128 v[50:53], v62
	ds_read_b128 v[54:57], v62 offset:1024
	ds_read_b128 v[58:61], v62 offset:2048
	ds_read_b128 v[62:65], v62 offset:3072
	ds_read_b128 v[66:69], v78
	ds_read_b128 v[70:73], v78 offset:1024
	ds_read_b128 v[74:77], v78 offset:2048
	ds_read_b128 v[78:81], v78 offset:3072
	ds_read_b128 v[182:185], v177
	ds_read_b128 v[186:189], v177 offset:1024
	ds_read_b128 v[190:193], v177 offset:2048
	ds_read_b128 v[194:197], v177 offset:3072
	ds_read_b128 v[198:201], v177 offset:4096
	ds_read_b128 v[212:215], v177 offset:5120
	ds_read_b128 v[216:219], v177 offset:6144
	ds_read_b128 v[220:223], v177 offset:7168
	s_waitcnt vmcnt(8)
	s_waitcnt lgkmcnt(0)
	s_barrier
	s_setprio 1
	s_waitcnt lgkmcnt(0)
	v_mfma_i32_16x16x64_i8 v[160:163], v[50:53], v[182:185], v[160:163]
	v_mfma_i32_16x16x64_i8 v[156:159], v[58:61], v[182:185], v[156:159]
	v_mfma_i32_16x16x64_i8 v[144:147], v[50:53], v[190:193], v[144:147]
	v_mfma_i32_16x16x64_i8 v[140:143], v[58:61], v[190:193], v[140:143]
	v_mfma_i32_16x16x64_i8 v[126:129], v[50:53], v[198:201], v[126:129]
	v_mfma_i32_16x16x64_i8 v[122:125], v[58:61], v[198:201], v[122:125]
	v_mfma_i32_16x16x64_i8 v[110:113], v[50:53], v[216:219], v[110:113]
	v_mfma_i32_16x16x64_i8 v[106:109], v[58:61], v[216:219], v[106:109]
	v_mfma_i32_16x16x64_i8 v[160:163], v[54:57], v[186:189], v[160:163]
	v_mfma_i32_16x16x64_i8 v[156:159], v[62:65], v[186:189], v[156:159]
	v_mfma_i32_16x16x64_i8 v[144:147], v[54:57], v[194:197], v[144:147]
	v_mfma_i32_16x16x64_i8 v[140:143], v[62:65], v[194:197], v[140:143]
	v_mfma_i32_16x16x64_i8 v[126:129], v[54:57], v[212:215], v[126:129]
	v_mfma_i32_16x16x64_i8 v[122:125], v[62:65], v[212:215], v[122:125]
	v_mfma_i32_16x16x64_i8 v[110:113], v[54:57], v[220:223], v[110:113]
	v_mfma_i32_16x16x64_i8 v[106:109], v[62:65], v[220:223], v[106:109]
	s_setprio 0
	s_setprio 1
	v_mfma_i32_16x16x64_i8 v[152:155], v[66:69], v[182:185], v[152:155]
	v_mfma_i32_16x16x64_i8 v[148:151], v[74:77], v[182:185], v[148:151]
	v_mfma_i32_16x16x64_i8 v[136:139], v[66:69], v[190:193], v[136:139]
	v_mfma_i32_16x16x64_i8 v[132:135], v[74:77], v[190:193], v[132:135]
	v_mfma_i32_16x16x64_i8 v[118:121], v[66:69], v[198:201], v[118:121]
	v_mfma_i32_16x16x64_i8 v[114:117], v[74:77], v[198:201], v[114:117]
	v_mfma_i32_16x16x64_i8 v[102:105], v[66:69], v[216:219], v[102:105]
	v_mfma_i32_16x16x64_i8 v[98:101], v[74:77], v[216:219], v[98:101]
	v_mfma_i32_16x16x64_i8 v[152:155], v[70:73], v[186:189], v[152:155]
	v_mfma_i32_16x16x64_i8 v[148:151], v[78:81], v[186:189], v[148:151]
	v_mfma_i32_16x16x64_i8 v[136:139], v[70:73], v[194:197], v[136:139]
	v_mfma_i32_16x16x64_i8 v[132:135], v[78:81], v[194:197], v[132:135]
	v_mfma_i32_16x16x64_i8 v[118:121], v[70:73], v[212:215], v[118:121]
	v_mfma_i32_16x16x64_i8 v[114:117], v[78:81], v[212:215], v[114:117]
	v_mfma_i32_16x16x64_i8 v[102:105], v[70:73], v[220:223], v[102:105]
	v_mfma_i32_16x16x64_i8 v[98:101], v[78:81], v[220:223], v[98:101]
	s_setprio 0
	s_barrier
	s_add_i32 s82, s82, s85
	v_lshl_add_u64 v[202:203], s[40:41], 0, v[168:169]
	s_mov_b32 m0, s82
	s_nop 0
	global_load_lds_dwordx4 v[202:203], off
	s_add_i32 m0, s82, 0x2000
	s_add_u32 s82, s40, 0x40000
	v_lshl_add_u64 v[228:229], s[40:41], 0, v[164:165]
	s_addc_u32 s83, s41, 0
	s_add_i32 s91, s91, s85
	global_load_lds_dwordx4 v[228:229], off
	v_lshl_add_u64 v[224:225], s[82:83], 0, v[168:169]
	s_mov_b32 m0, s91
	v_lshl_add_u64 v[230:231], s[42:43], 0, v[170:171]
	global_load_lds_dwordx4 v[224:225], off
	v_lshl_add_u64 v[224:225], s[82:83], 0, v[164:165]
	s_add_i32 m0, s91, 0x2000
	v_lshl_add_u64 v[232:233], s[42:43], 0, v[166:167]
	global_load_lds_dwordx4 v[224:225], off
	s_mov_b32 m0, s34
	s_nop 0
	global_load_lds_dwordx4 v[230:231], off
	s_mov_b32 m0, s35
	s_nop 0
	global_load_lds_dwordx4 v[232:233], off
	ds_read_b128 v[182:185], v177 offset:16384
	ds_read_b128 v[186:189], v177 offset:17408
	ds_read_b128 v[190:193], v177 offset:18432
	ds_read_b128 v[194:197], v177 offset:19456
	ds_read_b128 v[198:201], v177 offset:20480
	ds_read_b128 v[212:215], v177 offset:21504
	ds_read_b128 v[216:219], v177 offset:22528
	ds_read_b128 v[220:223], v177 offset:23552
	s_waitcnt vmcnt(8)
	s_waitcnt lgkmcnt(0)
	s_barrier
; #define PG8_STAGE(bufoff, gbase, voff) do { _Pragma("unroll") for (int _i = 0; _i < 2; ++_i) \
;         __builtin_amdgcn_global_load_lds((const unsigned*)((const char*)(gbase) + (voff)[_i]), (LAS unsigned*)(lds + (bufoff) + ldsw + _i * 8192), 16, 0, 0); } while (0)
; #define PG8_LDA(dst, b, h) do { _Pragma("unroll") for (int m = 0; m < 4; ++m) _Pragma("unroll") for (int k = 0; k < 2; ++k) dst[m][k] = *(const LAS bf16x8*)(lds + PG8_SA(b, h) + aoff + m * 2048 + k * 1024); } while (0)
; #define PG8_LDB(dst, b, h) do { _Pragma("unroll") for (int n = 0; n < 2; ++n) _Pragma("unroll") for (int k = 0; k < 2; ++k) dst[n][k] = *(const LAS bf16x8*)(lds + PG8_SB(b, h) + boff + n * 2048 + k * 1024); } while (0)
; #define PG8_MMA(ai, bj, At, Bt) do { __builtin_amdgcn_s_setprio(1); _Pragma("unroll") for (int m = 0; m < 4; ++m) _Pragma("unroll") for (int n = 0; n < 2; ++n) _Pragma("unroll") for (int k = 0; k < 2; ++k) \
;         acc[ai][bj][m][n] = mma16<I8>(Bt[n][k], At[m][k], acc[ai][bj][m][n]); __builtin_amdgcn_s_setprio(0); } while (0)
; #define PG8_WAIT_V(n) asm volatile("s_waitcnt vmcnt(" #n ")" ::: "memory")
; #define PG8_WAIT_L(n) asm volatile("s_waitcnt lgkmcnt(" #n ")" ::: "memory")
; #define PG8_BAR __builtin_amdgcn_s_barrier()
; #define PG8_SCHED __builtin_amdgcn_sched_barrier(0)
; template <class Epi, class Sched, bool I8 = false>
; __device__ __forceinline__ void gemm_phase(LAS unsigned char* lds, const Gemm g, const Sched& S, const Epi& E) {
;     ...
;             PG8_WAIT_V(8); PG8_WAIT_L(0); PG8_BAR; PG8_MMA(1, 0, At, B0); PG8_MMA(1, 1, At, B1); PG8_BAR; PG8_SCHED;
;             PG8_LDB(B0, 1, 0); PG8_LDB(B1, 1, 1); PG8_SCHED; PG8_LDA(At, 1, 0); PG8_STAGE(PG8_SA(0, 1), a2 + hstepA, voffA);
;             PG8_WAIT_V(8); PG8_WAIT_L(0); PG8_BAR; PG8_MMA(0, 0, At, B0); PG8_MMA(0, 1, At, B1); PG8_BAR; PG8_SCHED;
	s_setprio 1
	s_waitcnt lgkmcnt(0)
	v_mfma_i32_16x16x64_i8 v[94:97], v[50:53], v[182:185], v[94:97]
	v_mfma_i32_16x16x64_i8 v[90:93], v[58:61], v[182:185], v[90:93]
	v_mfma_i32_16x16x64_i8 v[46:49], v[50:53], v[190:193], v[46:49]
	v_mfma_i32_16x16x64_i8 v[42:45], v[58:61], v[190:193], v[42:45]
	v_mfma_i32_16x16x64_i8 v[30:33], v[50:53], v[198:201], v[30:33]
	v_mfma_i32_16x16x64_i8 v[26:29], v[58:61], v[198:201], v[26:29]
	v_mfma_i32_16x16x64_i8 v[14:17], v[50:53], v[216:219], v[14:17]
	v_mfma_i32_16x16x64_i8 v[10:13], v[58:61], v[216:219], v[10:13]
	v_mfma_i32_16x16x64_i8 v[94:97], v[54:57], v[186:189], v[94:97]
	v_mfma_i32_16x16x64_i8 v[90:93], v[62:65], v[186:189], v[90:93]
	v_mfma_i32_16x16x64_i8 v[46:49], v[54:57], v[194:197], v[46:49]
	v_mfma_i32_16x16x64_i8 v[42:45], v[62:65], v[194:197], v[42:45]
	v_mfma_i32_16x16x64_i8 v[30:33], v[54:57], v[212:215], v[30:33]
	v_mfma_i32_16x16x64_i8 v[26:29], v[62:65], v[212:215], v[26:29]
	v_mfma_i32_16x16x64_i8 v[14:17], v[54:57], v[220:223], v[14:17]
	v_mfma_i32_16x16x64_i8 v[10:13], v[62:65], v[220:223], v[10:13]
	s_setprio 0
	s_setprio 1
	v_mfma_i32_16x16x64_i8 v[38:41], v[66:69], v[190:193], v[38:41]
	v_mfma_i32_16x16x64_i8 v[34:37], v[74:77], v[190:193], v[34:37]
	v_mfma_i32_16x16x64_i8 v[22:25], v[66:69], v[198:201], v[22:25]
	v_mfma_i32_16x16x64_i8 v[18:21], v[74:77], v[198:201], v[18:21]
	v_mfma_i32_16x16x64_i8 v[6:9], v[66:69], v[216:219], v[6:9]
	v_mfma_i32_16x16x64_i8 v[2:5], v[74:77], v[216:219], v[2:5]
	v_mfma_i32_16x16x64_i8 v[50:53], v[66:69], v[182:185], v[86:89]
	v_mfma_i32_16x16x64_i8 v[54:57], v[74:77], v[182:185], v[82:85]
	v_mfma_i32_16x16x64_i8 v[38:41], v[70:73], v[194:197], v[38:41]
	v_mfma_i32_16x16x64_i8 v[34:37], v[78:81], v[194:197], v[34:37]
	v_mfma_i32_16x16x64_i8 v[22:25], v[70:73], v[212:215], v[22:25]
	v_mfma_i32_16x16x64_i8 v[18:21], v[78:81], v[212:215], v[18:21]
	v_mfma_i32_16x16x64_i8 v[6:9], v[70:73], v[220:223], v[6:9]
	v_mfma_i32_16x16x64_i8 v[2:5], v[78:81], v[220:223], v[2:5]
	v_mfma_i32_16x16x64_i8 v[50:53], v[70:73], v[186:189], v[50:53]
	v_mfma_i32_16x16x64_i8 v[54:57], v[78:81], v[186:189], v[54:57]
	s_setprio 0
	s_barrier
	s_add_i32 s82, 0, 0x18000
	s_add_i32 s83, 0, 0x1c000
	s_add_u32 s42, s42, 0x100000
	s_addc_u32 s43, s43, 0
	s_mov_b32 m0, s30
	v_lshl_add_u64 v[224:225], s[42:43], 0, v[170:171]
	global_load_lds_dwordx4 v[224:225], off
	v_lshl_add_u64 v[224:225], s[42:43], 0, v[166:167]
	s_mov_b32 m0, s31
	s_nop 0
	global_load_lds_dwordx4 v[224:225], off
	v_add_u32_e32 v70, s82, v175
	v_add_u32_e32 v82, s83, v175
	ds_read_b128 v[58:61], v70
	ds_read_b128 v[62:65], v70 offset:1024
	ds_read_b128 v[66:69], v70 offset:2048
	ds_read_b128 v[70:73], v70 offset:3072
	ds_read_b128 v[74:77], v82
	ds_read_b128 v[78:81], v82 offset:1024
	ds_read_b128 v[182:185], v82 offset:2048
	ds_read_b128 v[186:189], v82 offset:3072
	ds_read_b128 v[82:85], v177 offset:32768
	ds_read_b128 v[86:89], v177 offset:33792
	ds_read_b128 v[190:193], v177 offset:34816
	ds_read_b128 v[194:197], v177 offset:35840
	ds_read_b128 v[198:201], v177 offset:36864
	ds_read_b128 v[212:215], v177 offset:37888
	ds_read_b128 v[216:219], v177 offset:38912
	ds_read_b128 v[220:223], v177 offset:39936
	s_waitcnt vmcnt(8)
	s_waitcnt lgkmcnt(0)
	s_barrier
	s_setprio 1
	s_waitcnt lgkmcnt(0)
	v_mfma_i32_16x16x64_i8 v[160:163], v[58:61], v[82:85], v[160:163]
	v_mfma_i32_16x16x64_i8 v[156:159], v[66:69], v[82:85], v[156:159]
	v_mfma_i32_16x16x64_i8 v[144:147], v[58:61], v[190:193], v[144:147]
	v_mfma_i32_16x16x64_i8 v[140:143], v[66:69], v[190:193], v[140:143]
	v_mfma_i32_16x16x64_i8 v[126:129], v[58:61], v[198:201], v[126:129]
	v_mfma_i32_16x16x64_i8 v[122:125], v[66:69], v[198:201], v[122:125]
	v_mfma_i32_16x16x64_i8 v[110:113], v[58:61], v[216:219], v[110:113]
	v_mfma_i32_16x16x64_i8 v[106:109], v[66:69], v[216:219], v[106:109]
	v_mfma_i32_16x16x64_i8 v[160:163], v[62:65], v[86:89], v[160:163]
	v_mfma_i32_16x16x64_i8 v[156:159], v[70:73], v[86:89], v[156:159]
	v_mfma_i32_16x16x64_i8 v[144:147], v[62:65], v[194:197], v[144:147]
	v_mfma_i32_16x16x64_i8 v[140:143], v[70:73], v[194:197], v[140:143]
	v_mfma_i32_16x16x64_i8 v[126:129], v[62:65], v[212:215], v[126:129]
	v_mfma_i32_16x16x64_i8 v[122:125], v[70:73], v[212:215], v[122:125]
	v_mfma_i32_16x16x64_i8 v[110:113], v[62:65], v[220:223], v[110:113]
	v_mfma_i32_16x16x64_i8 v[106:109], v[70:73], v[220:223], v[106:109]
	s_setprio 0
	s_setprio 1
	v_mfma_i32_16x16x64_i8 v[152:155], v[74:77], v[82:85], v[152:155]
	v_mfma_i32_16x16x64_i8 v[82:85], v[182:185], v[82:85], v[148:151]
	v_mfma_i32_16x16x64_i8 v[148:151], v[186:189], v[86:89], v[82:85]
	v_mfma_i32_16x16x64_i8 v[82:85], v[74:77], v[190:193], v[136:139]
	v_mfma_i32_16x16x64_i8 v[136:139], v[78:81], v[194:197], v[82:85]
	v_mfma_i32_16x16x64_i8 v[82:85], v[182:185], v[190:193], v[132:135]
	v_mfma_i32_16x16x64_i8 v[132:135], v[186:189], v[194:197], v[82:85]
	v_mfma_i32_16x16x64_i8 v[82:85], v[74:77], v[198:201], v[118:121]
	v_mfma_i32_16x16x64_i8 v[118:121], v[78:81], v[212:215], v[82:85]
	v_mfma_i32_16x16x64_i8 v[82:85], v[182:185], v[198:201], v[114:117]
	v_mfma_i32_16x16x64_i8 v[114:117], v[186:189], v[212:215], v[82:85]
	v_mfma_i32_16x16x64_i8 v[82:85], v[74:77], v[216:219], v[102:105]
	v_mfma_i32_16x16x64_i8 v[102:105], v[78:81], v[220:223], v[82:85]
	v_mfma_i32_16x16x64_i8 v[82:85], v[182:185], v[216:219], v[98:101]
	v_mfma_i32_16x16x64_i8 v[152:155], v[78:81], v[86:89], v[152:155]
	v_mfma_i32_16x16x64_i8 v[98:101], v[186:189], v[220:223], v[82:85]
	s_setprio 0
	s_barrier
; #define PG8_STAGE(bufoff, gbase, voff) do { _Pragma("unroll") for (int _i = 0; _i < 2; ++_i) \
;         __builtin_amdgcn_global_load_lds((const unsigned*)((const char*)(gbase) + (voff)[_i]), (LAS unsigned*)(lds + (bufoff) + ldsw + _i * 8192), 16, 0, 0); } while (0)
; #define PG8_LDA(dst, b, h) do { _Pragma("unroll") for (int m = 0; m < 4; ++m) _Pragma("unroll") for (int k = 0; k < 2; ++k) dst[m][k] = *(const LAS bf16x8*)(lds + PG8_SA(b, h) + aoff + m * 2048 + k * 1024); } while (0)
; #define PG8_MMA(ai, bj, At, Bt) do { __builtin_amdgcn_s_setprio(1); _Pragma("unroll") for (int m = 0; m < 4; ++m) _Pragma("unroll") for (int n = 0; n < 2; ++n) _Pragma("unroll") for (int k = 0; k < 2; ++k) \
;         acc[ai][bj][m][n] = mma16<I8>(Bt[n][k], At[m][k], acc[ai][bj][m][n]); __builtin_amdgcn_s_setprio(0); } while (0)
; #define PG8_WAIT_V(n) asm volatile("s_waitcnt vmcnt(" #n ")" ::: "memory")
; #define PG8_WAIT_L(n) asm volatile("s_waitcnt lgkmcnt(" #n ")" ::: "memory")
; #define PG8_BAR __builtin_amdgcn_s_barrier()
; #define PG8_SCHED __builtin_amdgcn_sched_barrier(0)
; template <class Epi, class Sched, bool I8 = false>
; __device__ __forceinline__ void gemm_phase(LAS unsigned char* lds, const Gemm g, const Sched& S, const Epi& E) {
;     ...
;         for (int t = 0; t < nt; t += 2) {
;     ...
;             PG8_LDA(At, 1, 1); PG8_STAGE(PG8_SB(1, 0), b3, voffB); PG8_STAGE(PG8_SB(1, 1), b3 + hstepB, voffB); PG8_STAGE(PG8_SA(1, 0), a3, voffA);
;             PG8_WAIT_V(8); PG8_WAIT_L(0); PG8_BAR; PG8_MMA(1, 0, At, B0); PG8_MMA(1, 1, At, B1); PG8_BAR; PG8_SCHED;
	s_add_i32 s42, s82, s85
	v_lshl_add_u64 v[86:87], v[202:203], 0, s[12:13]
	s_mov_b32 m0, s42
	s_nop 0
	global_load_lds_dwordx4 v[86:87], off
	s_add_i32 m0, s42, 0x2000
	s_add_u32 s40, s40, 0x40080
	v_lshl_add_u64 v[86:87], v[228:229], 0, s[12:13]
	s_addc_u32 s41, s41, 0
	s_add_i32 s42, s83, s85
	global_load_lds_dwordx4 v[86:87], off
	v_lshl_add_u64 v[86:87], s[40:41], 0, v[168:169]
	s_mov_b32 m0, s42
	s_nop 0
	global_load_lds_dwordx4 v[86:87], off
	v_lshl_add_u64 v[86:87], s[40:41], 0, v[164:165]
	s_add_i32 m0, s42, 0x2000
	s_nop 0
	global_load_lds_dwordx4 v[86:87], off
	v_lshl_add_u64 v[86:87], v[230:231], 0, s[12:13]
	s_mov_b32 m0, s3
	s_nop 0
	global_load_lds_dwordx4 v[86:87], off
	v_lshl_add_u64 v[86:87], v[232:233], 0, s[12:13]
	s_mov_b32 m0, s2
	s_nop 0
	global_load_lds_dwordx4 v[86:87], off
	ds_read_b128 v[82:85], v177 offset:49152
	ds_read_b128 v[190:193], v177 offset:50176
	ds_read_b128 v[194:197], v177 offset:51200
	ds_read_b128 v[198:201], v177 offset:52224
	ds_read_b128 v[212:215], v177 offset:53248
	ds_read_b128 v[216:219], v177 offset:54272
	ds_read_b128 v[220:223], v177 offset:55296
	ds_read_b128 v[224:227], v177 offset:56320
	s_waitcnt vmcnt(8)
	s_waitcnt lgkmcnt(0)
	s_barrier
	s_setprio 1
	s_waitcnt lgkmcnt(0)
	v_mfma_i32_16x16x64_i8 v[86:89], v[58:61], v[82:85], v[94:97]
	v_mfma_i32_16x16x64_i8 v[94:97], v[62:65], v[190:193], v[86:89]
	v_mfma_i32_16x16x64_i8 v[86:89], v[66:69], v[82:85], v[90:93]
	v_mfma_i32_16x16x64_i8 v[46:49], v[58:61], v[194:197], v[46:49]
	v_mfma_i32_16x16x64_i8 v[42:45], v[66:69], v[194:197], v[42:45]
	v_mfma_i32_16x16x64_i8 v[30:33], v[58:61], v[212:215], v[30:33]
	v_mfma_i32_16x16x64_i8 v[26:29], v[66:69], v[212:215], v[26:29]
	v_mfma_i32_16x16x64_i8 v[14:17], v[58:61], v[220:223], v[14:17]
	v_mfma_i32_16x16x64_i8 v[10:13], v[66:69], v[220:223], v[10:13]
	v_mfma_i32_16x16x64_i8 v[90:93], v[70:73], v[190:193], v[86:89]
	v_mfma_i32_16x16x64_i8 v[46:49], v[62:65], v[198:201], v[46:49]
	v_mfma_i32_16x16x64_i8 v[42:45], v[70:73], v[198:201], v[42:45]
	v_mfma_i32_16x16x64_i8 v[30:33], v[62:65], v[216:219], v[30:33]
	v_mfma_i32_16x16x64_i8 v[26:29], v[70:73], v[216:219], v[26:29]
	v_mfma_i32_16x16x64_i8 v[14:17], v[62:65], v[224:227], v[14:17]
	v_mfma_i32_16x16x64_i8 v[10:13], v[70:73], v[224:227], v[10:13]
	s_setprio 0
	s_setprio 1
	v_mfma_i32_16x16x64_i8 v[50:53], v[74:77], v[82:85], v[50:53]
	v_mfma_i32_16x16x64_i8 v[86:89], v[78:81], v[190:193], v[50:53]
	v_mfma_i32_16x16x64_i8 v[50:53], v[182:185], v[82:85], v[54:57]
	v_mfma_i32_16x16x64_i8 v[38:41], v[74:77], v[194:197], v[38:41]
	v_mfma_i32_16x16x64_i8 v[34:37], v[182:185], v[194:197], v[34:37]
	v_mfma_i32_16x16x64_i8 v[22:25], v[74:77], v[212:215], v[22:25]
	v_mfma_i32_16x16x64_i8 v[18:21], v[182:185], v[212:215], v[18:21]
	v_mfma_i32_16x16x64_i8 v[6:9], v[74:77], v[220:223], v[6:9]
	v_mfma_i32_16x16x64_i8 v[2:5], v[182:185], v[220:223], v[2:5]
	v_mfma_i32_16x16x64_i8 v[82:85], v[186:189], v[190:193], v[50:53]
	v_mfma_i32_16x16x64_i8 v[38:41], v[78:81], v[198:201], v[38:41]
	v_mfma_i32_16x16x64_i8 v[34:37], v[186:189], v[198:201], v[34:37]
	v_mfma_i32_16x16x64_i8 v[22:25], v[78:81], v[216:219], v[22:25]
	v_mfma_i32_16x16x64_i8 v[18:21], v[186:189], v[216:219], v[18:21]
	v_mfma_i32_16x16x64_i8 v[6:9], v[78:81], v[224:227], v[6:9]
	v_mfma_i32_16x16x64_i8 v[2:5], v[186:189], v[224:227], v[2:5]
	s_setprio 0
	s_barrier
	s_add_u32 s0, s0, 0x100
	s_addc_u32 s1, s1, 0
	s_add_u32 s57, s57, 0x100
	s_addc_u32 s63, s63, 0
	s_cmp_ge_u32 s80, s22
	s_mov_b32 s42, s80
	s_cbranch_scc0 .LBB0_1574
	s_and_b64 vcc, exec, s[36:37]
	s_cbranch_vccz .LBB0_1577
	s_barrier
